# P0/P5 hand-written streaming, HGRN norm weights via LDS, P3 merge epilogue gate loads issued in bursts
# speedup vs baseline: 1.0011x; 1.0011x over previous
.LBB0_20:
	s_or_b64 exec, exec, s[10:11]
	s_lshl_b32 s17, s97, 14
	s_lshl_b32 s3, s2, 3
	s_add_i32 s3, s97, s3
	s_lshl_b32 s16, s82, 3
	v_readlane_b32 s40, v239, 7
	v_readlane_b32 s41, v239, 8
	v_lshrrev_b32_e32 v120, 5, v182
	v_and_b32_e32 v121, 31, v182
	v_lshlrev_b32_e32 v122, 2, v121
	v_mul_u32_u24_e32 v123, 0x18000, v120
	v_add_u32_e32 v0, v123, v122
	v_add_u32_e32 v1, 0x30000, v0
	v_add_u32_e32 v2, 0x60000, v0
	v_add_u32_e32 v3, 0x90000, v0
	v_add_u32_e32 v4, 0xc0000, v0
	v_add_u32_e32 v5, 0xf0000, v0
	v_add_u32_e32 v6, 0x120000, v0
	v_add_u32_e32 v7, 0x150000, v0
	v_mul_u32_u24_e32 v123, 0x84, v120
	v_add3_u32 v8, v123, v122, s17
	v_and_b32_e32 v124, 7, v182
	v_lshrrev_b32_e32 v125, 3, v182
	v_mul_u32_u24_e32 v123, 0x420, v124
	v_lshlrev_b32_e32 v126, 2, v125
	v_add3_u32 v9, v123, v126, s17
	v_lshlrev_b32_e32 v123, 13, v125
	v_lshl_add_u32 v10, v124, 4, v123
	v_add_u32_e32 v11, 0x10000, v10
	v_add_u32_e32 v12, 0x20000, v10
	v_add_u32_e32 v13, 0x30000, v10
	v_lshlrev_b32_e32 v123, 12, v125
	v_lshl_add_u32 v14, v124, 3, v123
	v_add_u32_e32 v15, 0x8000, v14
	v_add_u32_e32 v16, 0x10000, v14
	v_add_u32_e32 v17, 0x18000, v14
	s_add_u32 s44, s40, 0x10000
	s_addc_u32 s45, s41, 0
	s_mov_b32 s20, s3
	s_cmp_ge_i32 s20, 0x8000
	s_cbranch_scc1 .Lp0a_done
	s_lshr_b32 s37, s20, 9
	s_and_b32 s38, s20, 511
	s_mul_i32 s37, s37, 0x600000
	s_lshl_b32 s38, s38, 7
	s_add_u32 s37, s37, s38
	s_add_u32 s10, s40, s37
	s_addc_u32 s11, s41, 0
	s_add_u32 s12, s10, 0x180000
	s_addc_u32 s13, s11, 0
	s_add_u32 s14, s12, 0x180000
	s_addc_u32 s15, s13, 0
	s_add_u32 s18, s14, 0x180000
	s_addc_u32 s19, s15, 0
	global_load_dword v20, v0, s[10:11] nt
	global_load_dword v21, v1, s[10:11] nt
	global_load_dword v22, v2, s[10:11] nt
	global_load_dword v23, v3, s[10:11] nt
	global_load_dword v24, v4, s[10:11] nt
	global_load_dword v25, v5, s[10:11] nt
	global_load_dword v26, v6, s[10:11] nt
	global_load_dword v27, v7, s[10:11] nt
	global_load_dword v28, v0, s[12:13] nt
	global_load_dword v29, v1, s[12:13] nt
	global_load_dword v30, v2, s[12:13] nt
	global_load_dword v31, v3, s[12:13] nt
	global_load_dword v32, v4, s[12:13] nt
	global_load_dword v33, v5, s[12:13] nt
	global_load_dword v34, v6, s[12:13] nt
	global_load_dword v35, v7, s[12:13] nt
	global_load_dword v36, v0, s[14:15] nt
	global_load_dword v37, v1, s[14:15] nt
	global_load_dword v38, v2, s[14:15] nt
	global_load_dword v39, v3, s[14:15] nt
	global_load_dword v40, v4, s[14:15] nt
	global_load_dword v41, v5, s[14:15] nt
	global_load_dword v42, v6, s[14:15] nt
	global_load_dword v43, v7, s[14:15] nt
	global_load_dword v44, v0, s[18:19] nt
	global_load_dword v45, v1, s[18:19] nt
	global_load_dword v46, v2, s[18:19] nt
	global_load_dword v47, v3, s[18:19] nt
	global_load_dword v48, v4, s[18:19] nt
	global_load_dword v49, v5, s[18:19] nt
	global_load_dword v50, v6, s[18:19] nt
	global_load_dword v51, v7, s[18:19] nt
	s_mov_b32 s36, s20
	s_add_i32 s20, s20, s16
.Lp0a_loop:
	s_cmp_ge_i32 s20, 0x8000
	s_cbranch_scc1 .Lp0a_lastA
	s_lshr_b32 s37, s20, 9
	s_and_b32 s38, s20, 511
	s_mul_i32 s37, s37, 0x600000
	s_lshl_b32 s38, s38, 7
	s_add_u32 s37, s37, s38
	s_add_u32 s10, s40, s37
	s_addc_u32 s11, s41, 0
	s_add_u32 s12, s10, 0x180000
	s_addc_u32 s13, s11, 0
	s_add_u32 s14, s12, 0x180000
	s_addc_u32 s15, s13, 0
	s_add_u32 s18, s14, 0x180000
	s_addc_u32 s19, s15, 0
	global_load_dword v52, v0, s[10:11] nt
	global_load_dword v53, v1, s[10:11] nt
	global_load_dword v54, v2, s[10:11] nt
	global_load_dword v55, v3, s[10:11] nt
	global_load_dword v56, v4, s[10:11] nt
	global_load_dword v57, v5, s[10:11] nt
	global_load_dword v58, v6, s[10:11] nt
	global_load_dword v59, v7, s[10:11] nt
	global_load_dword v60, v0, s[12:13] nt
	global_load_dword v61, v1, s[12:13] nt
	global_load_dword v62, v2, s[12:13] nt
	global_load_dword v63, v3, s[12:13] nt
	global_load_dword v64, v4, s[12:13] nt
	global_load_dword v65, v5, s[12:13] nt
	global_load_dword v66, v6, s[12:13] nt
	global_load_dword v67, v7, s[12:13] nt
	global_load_dword v68, v0, s[14:15] nt
	global_load_dword v69, v1, s[14:15] nt
	global_load_dword v70, v2, s[14:15] nt
	global_load_dword v71, v3, s[14:15] nt
	global_load_dword v72, v4, s[14:15] nt
	global_load_dword v73, v5, s[14:15] nt
	global_load_dword v74, v6, s[14:15] nt
	global_load_dword v75, v7, s[14:15] nt
	global_load_dword v76, v0, s[18:19] nt
	global_load_dword v77, v1, s[18:19] nt
	global_load_dword v78, v2, s[18:19] nt
	global_load_dword v79, v3, s[18:19] nt
	global_load_dword v80, v4, s[18:19] nt
	global_load_dword v81, v5, s[18:19] nt
	global_load_dword v82, v6, s[18:19] nt
	global_load_dword v83, v7, s[18:19] nt
	s_waitcnt vmcnt(32)
	ds_write_b32 v8, v20 offset:0
	ds_write_b32 v8, v21 offset:264
	ds_write_b32 v8, v22 offset:528
	ds_write_b32 v8, v23 offset:792
	ds_write_b32 v8, v24 offset:1056
	ds_write_b32 v8, v25 offset:1320
	ds_write_b32 v8, v26 offset:1584
	ds_write_b32 v8, v27 offset:1848
	ds_write_b32 v8, v28 offset:2112
	ds_write_b32 v8, v29 offset:2376
	ds_write_b32 v8, v30 offset:2640
	ds_write_b32 v8, v31 offset:2904
	ds_write_b32 v8, v32 offset:3168
	ds_write_b32 v8, v33 offset:3432
	ds_write_b32 v8, v34 offset:3696
	ds_write_b32 v8, v35 offset:3960
	ds_write_b32 v8, v36 offset:4224
	ds_write_b32 v8, v37 offset:4488
	ds_write_b32 v8, v38 offset:4752
	ds_write_b32 v8, v39 offset:5016
	ds_write_b32 v8, v40 offset:5280
	ds_write_b32 v8, v41 offset:5544
	ds_write_b32 v8, v42 offset:5808
	ds_write_b32 v8, v43 offset:6072
	ds_write_b32 v8, v44 offset:6336
	ds_write_b32 v8, v45 offset:6600
	ds_write_b32 v8, v46 offset:6864
	ds_write_b32 v8, v47 offset:7128
	ds_write_b32 v8, v48 offset:7392
	ds_write_b32 v8, v49 offset:7656
	ds_write_b32 v8, v50 offset:7920
	ds_write_b32 v8, v51 offset:8184
	s_lshr_b32 s37, s36, 9
	s_and_b32 s38, s36, 511
	s_lshl_b32 s37, s37, 7
	s_lshl_b32 s38, s38, 18
	s_add_u32 s37, s37, s38
	s_add_u32 s46, s8, s37
	s_addc_u32 s47, s9, 0
	s_waitcnt lgkmcnt(0)
	ds_read2_b32 v[84:85], v9 offset0:0 offset1:8
	ds_read2_b32 v[86:87], v9 offset0:33 offset1:41
	ds_read2_b32 v[88:89], v9 offset0:66 offset1:74
	ds_read2_b32 v[90:91], v9 offset0:99 offset1:107
	ds_read2_b32 v[92:93], v9 offset0:132 offset1:140
	ds_read2_b32 v[94:95], v9 offset0:165 offset1:173
	ds_read2_b32 v[96:97], v9 offset0:198 offset1:206
	ds_read2_b32 v[98:99], v9 offset0:231 offset1:239
	ds_read2_b32 v[100:101], v9 offset0:16 offset1:24
	ds_read2_b32 v[102:103], v9 offset0:49 offset1:57
	ds_read2_b32 v[104:105], v9 offset0:82 offset1:90
	ds_read2_b32 v[106:107], v9 offset0:115 offset1:123
	ds_read2_b32 v[108:109], v9 offset0:148 offset1:156
	ds_read2_b32 v[110:111], v9 offset0:181 offset1:189
	ds_read2_b32 v[112:113], v9 offset0:214 offset1:222
	ds_read2_b32 v[114:115], v9 offset0:247 offset1:255
	s_waitcnt lgkmcnt(8)
	v_cvt_pk_bf16_f32 v116, v84, v86
	v_cvt_pk_bf16_f32 v117, v88, v90
	v_cvt_pk_bf16_f32 v118, v92, v94
	v_cvt_pk_bf16_f32 v119, v96, v98
	global_store_dwordx4 v10, v[116:119], s[46:47]
	v_cvt_pk_bf16_f32 v120, v85, v87
	v_cvt_pk_bf16_f32 v121, v89, v91
	v_cvt_pk_bf16_f32 v122, v93, v95
	v_cvt_pk_bf16_f32 v123, v97, v99
	global_store_dwordx4 v11, v[120:123], s[46:47]
	s_waitcnt lgkmcnt(0)
	v_cvt_pk_bf16_f32 v124, v100, v102
	v_cvt_pk_bf16_f32 v125, v104, v106
	v_cvt_pk_bf16_f32 v126, v108, v110
	v_cvt_pk_bf16_f32 v127, v112, v114
	global_store_dwordx4 v12, v[124:127], s[46:47]
	v_cvt_pk_bf16_f32 v128, v101, v103
	v_cvt_pk_bf16_f32 v129, v105, v107
	v_cvt_pk_bf16_f32 v130, v109, v111
	v_cvt_pk_bf16_f32 v131, v113, v115
	global_store_dwordx4 v13, v[128:131], s[46:47]
	s_mov_b32 s36, s20
	s_add_i32 s20, s20, s16
	s_cmp_ge_i32 s20, 0x8000
	s_cbranch_scc1 .Lp0a_lastB
	s_lshr_b32 s37, s20, 9
	s_and_b32 s38, s20, 511
	s_mul_i32 s37, s37, 0x600000
	s_lshl_b32 s38, s38, 7
	s_add_u32 s37, s37, s38
	s_add_u32 s10, s40, s37
	s_addc_u32 s11, s41, 0
	s_add_u32 s12, s10, 0x180000
	s_addc_u32 s13, s11, 0
	s_add_u32 s14, s12, 0x180000
	s_addc_u32 s15, s13, 0
	s_add_u32 s18, s14, 0x180000
	s_addc_u32 s19, s15, 0
	global_load_dword v20, v0, s[10:11] nt
	global_load_dword v21, v1, s[10:11] nt
	global_load_dword v22, v2, s[10:11] nt
	global_load_dword v23, v3, s[10:11] nt
	global_load_dword v24, v4, s[10:11] nt
	global_load_dword v25, v5, s[10:11] nt
	global_load_dword v26, v6, s[10:11] nt
	global_load_dword v27, v7, s[10:11] nt
	global_load_dword v28, v0, s[12:13] nt
	global_load_dword v29, v1, s[12:13] nt
	global_load_dword v30, v2, s[12:13] nt
	global_load_dword v31, v3, s[12:13] nt
	global_load_dword v32, v4, s[12:13] nt
	global_load_dword v33, v5, s[12:13] nt
	global_load_dword v34, v6, s[12:13] nt
	global_load_dword v35, v7, s[12:13] nt
	global_load_dword v36, v0, s[14:15] nt
	global_load_dword v37, v1, s[14:15] nt
	global_load_dword v38, v2, s[14:15] nt
	global_load_dword v39, v3, s[14:15] nt
	global_load_dword v40, v4, s[14:15] nt
	global_load_dword v41, v5, s[14:15] nt
	global_load_dword v42, v6, s[14:15] nt
	global_load_dword v43, v7, s[14:15] nt
	global_load_dword v44, v0, s[18:19] nt
	global_load_dword v45, v1, s[18:19] nt
	global_load_dword v46, v2, s[18:19] nt
	global_load_dword v47, v3, s[18:19] nt
	global_load_dword v48, v4, s[18:19] nt
	global_load_dword v49, v5, s[18:19] nt
	global_load_dword v50, v6, s[18:19] nt
	global_load_dword v51, v7, s[18:19] nt
	s_waitcnt vmcnt(32)
	ds_write_b32 v8, v52 offset:0
	ds_write_b32 v8, v53 offset:264
	ds_write_b32 v8, v54 offset:528
	ds_write_b32 v8, v55 offset:792
	ds_write_b32 v8, v56 offset:1056
	ds_write_b32 v8, v57 offset:1320
	ds_write_b32 v8, v58 offset:1584
	ds_write_b32 v8, v59 offset:1848
	ds_write_b32 v8, v60 offset:2112
	ds_write_b32 v8, v61 offset:2376
	ds_write_b32 v8, v62 offset:2640
	ds_write_b32 v8, v63 offset:2904
	ds_write_b32 v8, v64 offset:3168
	ds_write_b32 v8, v65 offset:3432
	ds_write_b32 v8, v66 offset:3696
	ds_write_b32 v8, v67 offset:3960
	ds_write_b32 v8, v68 offset:4224
	ds_write_b32 v8, v69 offset:4488
	ds_write_b32 v8, v70 offset:4752
	ds_write_b32 v8, v71 offset:5016
	ds_write_b32 v8, v72 offset:5280
	ds_write_b32 v8, v73 offset:5544
	ds_write_b32 v8, v74 offset:5808
	ds_write_b32 v8, v75 offset:6072
	ds_write_b32 v8, v76 offset:6336
	ds_write_b32 v8, v77 offset:6600
	ds_write_b32 v8, v78 offset:6864
	ds_write_b32 v8, v79 offset:7128
	ds_write_b32 v8, v80 offset:7392
	ds_write_b32 v8, v81 offset:7656
	ds_write_b32 v8, v82 offset:7920
	ds_write_b32 v8, v83 offset:8184
	s_lshr_b32 s37, s36, 9
	s_and_b32 s38, s36, 511
	s_lshl_b32 s37, s37, 7
	s_lshl_b32 s38, s38, 18
	s_add_u32 s37, s37, s38
	s_add_u32 s46, s8, s37
	s_addc_u32 s47, s9, 0
	s_waitcnt lgkmcnt(0)
	ds_read2_b32 v[84:85], v9 offset0:0 offset1:8
	ds_read2_b32 v[86:87], v9 offset0:33 offset1:41
	ds_read2_b32 v[88:89], v9 offset0:66 offset1:74
	ds_read2_b32 v[90:91], v9 offset0:99 offset1:107
	ds_read2_b32 v[92:93], v9 offset0:132 offset1:140
	ds_read2_b32 v[94:95], v9 offset0:165 offset1:173
	ds_read2_b32 v[96:97], v9 offset0:198 offset1:206
	ds_read2_b32 v[98:99], v9 offset0:231 offset1:239
	ds_read2_b32 v[100:101], v9 offset0:16 offset1:24
	ds_read2_b32 v[102:103], v9 offset0:49 offset1:57
	ds_read2_b32 v[104:105], v9 offset0:82 offset1:90
	ds_read2_b32 v[106:107], v9 offset0:115 offset1:123
	ds_read2_b32 v[108:109], v9 offset0:148 offset1:156
	ds_read2_b32 v[110:111], v9 offset0:181 offset1:189
	ds_read2_b32 v[112:113], v9 offset0:214 offset1:222
	ds_read2_b32 v[114:115], v9 offset0:247 offset1:255
	s_waitcnt lgkmcnt(8)
	v_cvt_pk_bf16_f32 v116, v84, v86
	v_cvt_pk_bf16_f32 v117, v88, v90
	v_cvt_pk_bf16_f32 v118, v92, v94
	v_cvt_pk_bf16_f32 v119, v96, v98
	global_store_dwordx4 v10, v[116:119], s[46:47]
	v_cvt_pk_bf16_f32 v120, v85, v87
	v_cvt_pk_bf16_f32 v121, v89, v91
	v_cvt_pk_bf16_f32 v122, v93, v95
	v_cvt_pk_bf16_f32 v123, v97, v99
	global_store_dwordx4 v11, v[120:123], s[46:47]
	s_waitcnt lgkmcnt(0)
	v_cvt_pk_bf16_f32 v124, v100, v102
	v_cvt_pk_bf16_f32 v125, v104, v106
	v_cvt_pk_bf16_f32 v126, v108, v110
	v_cvt_pk_bf16_f32 v127, v112, v114
	global_store_dwordx4 v12, v[124:127], s[46:47]
	v_cvt_pk_bf16_f32 v128, v101, v103
	v_cvt_pk_bf16_f32 v129, v105, v107
	v_cvt_pk_bf16_f32 v130, v109, v111
	v_cvt_pk_bf16_f32 v131, v113, v115
	global_store_dwordx4 v13, v[128:131], s[46:47]
	s_mov_b32 s36, s20
	s_add_i32 s20, s20, s16
	s_branch .Lp0a_loop
.Lp0a_lastA:
	s_waitcnt vmcnt(0)
	ds_write_b32 v8, v20 offset:0
	ds_write_b32 v8, v21 offset:264
	ds_write_b32 v8, v22 offset:528
	ds_write_b32 v8, v23 offset:792
	ds_write_b32 v8, v24 offset:1056
	ds_write_b32 v8, v25 offset:1320
	ds_write_b32 v8, v26 offset:1584
	ds_write_b32 v8, v27 offset:1848
	ds_write_b32 v8, v28 offset:2112
	ds_write_b32 v8, v29 offset:2376
	ds_write_b32 v8, v30 offset:2640
	ds_write_b32 v8, v31 offset:2904
	ds_write_b32 v8, v32 offset:3168
	ds_write_b32 v8, v33 offset:3432
	ds_write_b32 v8, v34 offset:3696
	ds_write_b32 v8, v35 offset:3960
	ds_write_b32 v8, v36 offset:4224
	ds_write_b32 v8, v37 offset:4488
	ds_write_b32 v8, v38 offset:4752
	ds_write_b32 v8, v39 offset:5016
	ds_write_b32 v8, v40 offset:5280
	ds_write_b32 v8, v41 offset:5544
	ds_write_b32 v8, v42 offset:5808
	ds_write_b32 v8, v43 offset:6072
	ds_write_b32 v8, v44 offset:6336
	ds_write_b32 v8, v45 offset:6600
	ds_write_b32 v8, v46 offset:6864
	ds_write_b32 v8, v47 offset:7128
	ds_write_b32 v8, v48 offset:7392
	ds_write_b32 v8, v49 offset:7656
	ds_write_b32 v8, v50 offset:7920
	ds_write_b32 v8, v51 offset:8184
	s_lshr_b32 s37, s36, 9
	s_and_b32 s38, s36, 511
	s_lshl_b32 s37, s37, 7
	s_lshl_b32 s38, s38, 18
	s_add_u32 s37, s37, s38
	s_add_u32 s46, s8, s37
	s_addc_u32 s47, s9, 0
	s_waitcnt lgkmcnt(0)
	ds_read2_b32 v[84:85], v9 offset0:0 offset1:8
	ds_read2_b32 v[86:87], v9 offset0:33 offset1:41
	ds_read2_b32 v[88:89], v9 offset0:66 offset1:74
	ds_read2_b32 v[90:91], v9 offset0:99 offset1:107
	ds_read2_b32 v[92:93], v9 offset0:132 offset1:140
	ds_read2_b32 v[94:95], v9 offset0:165 offset1:173
	ds_read2_b32 v[96:97], v9 offset0:198 offset1:206
	ds_read2_b32 v[98:99], v9 offset0:231 offset1:239
	ds_read2_b32 v[100:101], v9 offset0:16 offset1:24
	ds_read2_b32 v[102:103], v9 offset0:49 offset1:57
	ds_read2_b32 v[104:105], v9 offset0:82 offset1:90
	ds_read2_b32 v[106:107], v9 offset0:115 offset1:123
	ds_read2_b32 v[108:109], v9 offset0:148 offset1:156
	ds_read2_b32 v[110:111], v9 offset0:181 offset1:189
	ds_read2_b32 v[112:113], v9 offset0:214 offset1:222
	ds_read2_b32 v[114:115], v9 offset0:247 offset1:255
	s_waitcnt lgkmcnt(8)
	v_cvt_pk_bf16_f32 v116, v84, v86
	v_cvt_pk_bf16_f32 v117, v88, v90
	v_cvt_pk_bf16_f32 v118, v92, v94
	v_cvt_pk_bf16_f32 v119, v96, v98
	global_store_dwordx4 v10, v[116:119], s[46:47]
	v_cvt_pk_bf16_f32 v120, v85, v87
	v_cvt_pk_bf16_f32 v121, v89, v91
	v_cvt_pk_bf16_f32 v122, v93, v95
	v_cvt_pk_bf16_f32 v123, v97, v99
	global_store_dwordx4 v11, v[120:123], s[46:47]
	s_waitcnt lgkmcnt(0)
	v_cvt_pk_bf16_f32 v124, v100, v102
	v_cvt_pk_bf16_f32 v125, v104, v106
	v_cvt_pk_bf16_f32 v126, v108, v110
	v_cvt_pk_bf16_f32 v127, v112, v114
	global_store_dwordx4 v12, v[124:127], s[46:47]
	v_cvt_pk_bf16_f32 v128, v101, v103
	v_cvt_pk_bf16_f32 v129, v105, v107
	v_cvt_pk_bf16_f32 v130, v109, v111
	v_cvt_pk_bf16_f32 v131, v113, v115
	global_store_dwordx4 v13, v[128:131], s[46:47]
	s_branch .Lp0a_done
.Lp0a_lastB:
	s_waitcnt vmcnt(0)
	ds_write_b32 v8, v52 offset:0
	ds_write_b32 v8, v53 offset:264
	ds_write_b32 v8, v54 offset:528
	ds_write_b32 v8, v55 offset:792
	ds_write_b32 v8, v56 offset:1056
	ds_write_b32 v8, v57 offset:1320
	ds_write_b32 v8, v58 offset:1584
	ds_write_b32 v8, v59 offset:1848
	ds_write_b32 v8, v60 offset:2112
	ds_write_b32 v8, v61 offset:2376
	ds_write_b32 v8, v62 offset:2640
	ds_write_b32 v8, v63 offset:2904
	ds_write_b32 v8, v64 offset:3168
	ds_write_b32 v8, v65 offset:3432
	ds_write_b32 v8, v66 offset:3696
	ds_write_b32 v8, v67 offset:3960
	ds_write_b32 v8, v68 offset:4224
	ds_write_b32 v8, v69 offset:4488
	ds_write_b32 v8, v70 offset:4752
	ds_write_b32 v8, v71 offset:5016
	ds_write_b32 v8, v72 offset:5280
	ds_write_b32 v8, v73 offset:5544
	ds_write_b32 v8, v74 offset:5808
	ds_write_b32 v8, v75 offset:6072
	ds_write_b32 v8, v76 offset:6336
	ds_write_b32 v8, v77 offset:6600
	ds_write_b32 v8, v78 offset:6864
	ds_write_b32 v8, v79 offset:7128
	ds_write_b32 v8, v80 offset:7392
	ds_write_b32 v8, v81 offset:7656
	ds_write_b32 v8, v82 offset:7920
	ds_write_b32 v8, v83 offset:8184
	s_lshr_b32 s37, s36, 9
	s_and_b32 s38, s36, 511
	s_lshl_b32 s37, s37, 7
	s_lshl_b32 s38, s38, 18
	s_add_u32 s37, s37, s38
	s_add_u32 s46, s8, s37
	s_addc_u32 s47, s9, 0
	s_waitcnt lgkmcnt(0)
	ds_read2_b32 v[84:85], v9 offset0:0 offset1:8
	ds_read2_b32 v[86:87], v9 offset0:33 offset1:41
	ds_read2_b32 v[88:89], v9 offset0:66 offset1:74
	ds_read2_b32 v[90:91], v9 offset0:99 offset1:107
	ds_read2_b32 v[92:93], v9 offset0:132 offset1:140
	ds_read2_b32 v[94:95], v9 offset0:165 offset1:173
	ds_read2_b32 v[96:97], v9 offset0:198 offset1:206
	ds_read2_b32 v[98:99], v9 offset0:231 offset1:239
	ds_read2_b32 v[100:101], v9 offset0:16 offset1:24
	ds_read2_b32 v[102:103], v9 offset0:49 offset1:57
	ds_read2_b32 v[104:105], v9 offset0:82 offset1:90
	ds_read2_b32 v[106:107], v9 offset0:115 offset1:123
	ds_read2_b32 v[108:109], v9 offset0:148 offset1:156
	ds_read2_b32 v[110:111], v9 offset0:181 offset1:189
	ds_read2_b32 v[112:113], v9 offset0:214 offset1:222
	ds_read2_b32 v[114:115], v9 offset0:247 offset1:255
	s_waitcnt lgkmcnt(8)
	v_cvt_pk_bf16_f32 v116, v84, v86
	v_cvt_pk_bf16_f32 v117, v88, v90
	v_cvt_pk_bf16_f32 v118, v92, v94
	v_cvt_pk_bf16_f32 v119, v96, v98
	global_store_dwordx4 v10, v[116:119], s[46:47]
	v_cvt_pk_bf16_f32 v120, v85, v87
	v_cvt_pk_bf16_f32 v121, v89, v91
	v_cvt_pk_bf16_f32 v122, v93, v95
	v_cvt_pk_bf16_f32 v123, v97, v99
	global_store_dwordx4 v11, v[120:123], s[46:47]
	s_waitcnt lgkmcnt(0)
	v_cvt_pk_bf16_f32 v124, v100, v102
	v_cvt_pk_bf16_f32 v125, v104, v106
	v_cvt_pk_bf16_f32 v126, v108, v110
	v_cvt_pk_bf16_f32 v127, v112, v114
	global_store_dwordx4 v12, v[124:127], s[46:47]
	v_cvt_pk_bf16_f32 v128, v101, v103
	v_cvt_pk_bf16_f32 v129, v105, v107
	v_cvt_pk_bf16_f32 v130, v109, v111
	v_cvt_pk_bf16_f32 v131, v113, v115
	global_store_dwordx4 v13, v[128:131], s[46:47]
.Lp0a_done:
	s_mov_b32 s20, s3
	s_cmp_ge_i32 s20, 0x4000
	s_cbranch_scc1 .Lp0b_done
	s_lshr_b32 s37, s20, 8
	s_and_b32 s38, s20, 255
	s_mul_i32 s37, s37, 0x600000
	s_lshl_b32 s38, s38, 7
	s_add_u32 s37, s37, s38
	s_add_u32 s10, s44, s37
	s_addc_u32 s11, s45, 0
	s_add_u32 s12, s10, 0x180000
	s_addc_u32 s13, s11, 0
	s_add_u32 s14, s12, 0x180000
	s_addc_u32 s15, s13, 0
	s_add_u32 s18, s14, 0x180000
	s_addc_u32 s19, s15, 0
	global_load_dword v20, v0, s[10:11] nt
	global_load_dword v21, v1, s[10:11] nt
	global_load_dword v22, v2, s[10:11] nt
	global_load_dword v23, v3, s[10:11] nt
	global_load_dword v24, v4, s[10:11] nt
	global_load_dword v25, v5, s[10:11] nt
	global_load_dword v26, v6, s[10:11] nt
	global_load_dword v27, v7, s[10:11] nt
	global_load_dword v28, v0, s[12:13] nt
	global_load_dword v29, v1, s[12:13] nt
	global_load_dword v30, v2, s[12:13] nt
	global_load_dword v31, v3, s[12:13] nt
	global_load_dword v32, v4, s[12:13] nt
	global_load_dword v33, v5, s[12:13] nt
	global_load_dword v34, v6, s[12:13] nt
	global_load_dword v35, v7, s[12:13] nt
	global_load_dword v36, v0, s[14:15] nt
	global_load_dword v37, v1, s[14:15] nt
	global_load_dword v38, v2, s[14:15] nt
	global_load_dword v39, v3, s[14:15] nt
	global_load_dword v40, v4, s[14:15] nt
	global_load_dword v41, v5, s[14:15] nt
	global_load_dword v42, v6, s[14:15] nt
	global_load_dword v43, v7, s[14:15] nt
	global_load_dword v44, v0, s[18:19] nt
	global_load_dword v45, v1, s[18:19] nt
	global_load_dword v46, v2, s[18:19] nt
	global_load_dword v47, v3, s[18:19] nt
	global_load_dword v48, v4, s[18:19] nt
	global_load_dword v49, v5, s[18:19] nt
	global_load_dword v50, v6, s[18:19] nt
	global_load_dword v51, v7, s[18:19] nt
	s_mov_b32 s36, s20
	s_add_i32 s20, s20, s16
.Lp0b_loop:
	s_cmp_ge_i32 s20, 0x4000
	s_cbranch_scc1 .Lp0b_lastA
	s_lshr_b32 s37, s20, 8
	s_and_b32 s38, s20, 255
	s_mul_i32 s37, s37, 0x600000
	s_lshl_b32 s38, s38, 7
	s_add_u32 s37, s37, s38
	s_add_u32 s10, s44, s37
	s_addc_u32 s11, s45, 0
	s_add_u32 s12, s10, 0x180000
	s_addc_u32 s13, s11, 0
	s_add_u32 s14, s12, 0x180000
	s_addc_u32 s15, s13, 0
	s_add_u32 s18, s14, 0x180000
	s_addc_u32 s19, s15, 0
	global_load_dword v52, v0, s[10:11] nt
	global_load_dword v53, v1, s[10:11] nt
	global_load_dword v54, v2, s[10:11] nt
	global_load_dword v55, v3, s[10:11] nt
	global_load_dword v56, v4, s[10:11] nt
	global_load_dword v57, v5, s[10:11] nt
	global_load_dword v58, v6, s[10:11] nt
	global_load_dword v59, v7, s[10:11] nt
	global_load_dword v60, v0, s[12:13] nt
	global_load_dword v61, v1, s[12:13] nt
	global_load_dword v62, v2, s[12:13] nt
	global_load_dword v63, v3, s[12:13] nt
	global_load_dword v64, v4, s[12:13] nt
	global_load_dword v65, v5, s[12:13] nt
	global_load_dword v66, v6, s[12:13] nt
	global_load_dword v67, v7, s[12:13] nt
	global_load_dword v68, v0, s[14:15] nt
	global_load_dword v69, v1, s[14:15] nt
	global_load_dword v70, v2, s[14:15] nt
	global_load_dword v71, v3, s[14:15] nt
	global_load_dword v72, v4, s[14:15] nt
	global_load_dword v73, v5, s[14:15] nt
	global_load_dword v74, v6, s[14:15] nt
	global_load_dword v75, v7, s[14:15] nt
	global_load_dword v76, v0, s[18:19] nt
	global_load_dword v77, v1, s[18:19] nt
	global_load_dword v78, v2, s[18:19] nt
	global_load_dword v79, v3, s[18:19] nt
	global_load_dword v80, v4, s[18:19] nt
	global_load_dword v81, v5, s[18:19] nt
	global_load_dword v82, v6, s[18:19] nt
	global_load_dword v83, v7, s[18:19] nt
	s_waitcnt vmcnt(32)
	ds_write_b32 v8, v20 offset:0
	ds_write_b32 v8, v21 offset:264
	ds_write_b32 v8, v22 offset:528
	ds_write_b32 v8, v23 offset:792
	ds_write_b32 v8, v24 offset:1056
	ds_write_b32 v8, v25 offset:1320
	ds_write_b32 v8, v26 offset:1584
	ds_write_b32 v8, v27 offset:1848
	ds_write_b32 v8, v28 offset:2112
	ds_write_b32 v8, v29 offset:2376
	ds_write_b32 v8, v30 offset:2640
	ds_write_b32 v8, v31 offset:2904
	ds_write_b32 v8, v32 offset:3168
	ds_write_b32 v8, v33 offset:3432
	ds_write_b32 v8, v34 offset:3696
	ds_write_b32 v8, v35 offset:3960
	ds_write_b32 v8, v36 offset:4224
	ds_write_b32 v8, v37 offset:4488
	ds_write_b32 v8, v38 offset:4752
	ds_write_b32 v8, v39 offset:5016
	ds_write_b32 v8, v40 offset:5280
	ds_write_b32 v8, v41 offset:5544
	ds_write_b32 v8, v42 offset:5808
	ds_write_b32 v8, v43 offset:6072
	ds_write_b32 v8, v44 offset:6336
	ds_write_b32 v8, v45 offset:6600
	ds_write_b32 v8, v46 offset:6864
	ds_write_b32 v8, v47 offset:7128
	ds_write_b32 v8, v48 offset:7392
	ds_write_b32 v8, v49 offset:7656
	ds_write_b32 v8, v50 offset:7920
	ds_write_b32 v8, v51 offset:8184
	s_lshr_b32 s37, s36, 8
	s_and_b32 s38, s36, 255
	s_lshl_b32 s37, s37, 6
	s_lshl_b32 s38, s38, 17
	s_add_u32 s37, s37, s38
	s_add_u32 s46, s0, s37
	s_addc_u32 s47, s1, 0
	s_waitcnt lgkmcnt(0)
	ds_read2_b32 v[84:85], v9 offset0:0 offset1:8
	ds_read2_b32 v[86:87], v9 offset0:33 offset1:41
	ds_read2_b32 v[88:89], v9 offset0:66 offset1:74
	ds_read2_b32 v[90:91], v9 offset0:99 offset1:107
	ds_read2_b32 v[92:93], v9 offset0:132 offset1:140
	ds_read2_b32 v[94:95], v9 offset0:165 offset1:173
	ds_read2_b32 v[96:97], v9 offset0:198 offset1:206
	ds_read2_b32 v[98:99], v9 offset0:231 offset1:239
	ds_read2_b32 v[100:101], v9 offset0:16 offset1:24
	ds_read2_b32 v[102:103], v9 offset0:49 offset1:57
	ds_read2_b32 v[104:105], v9 offset0:82 offset1:90
	ds_read2_b32 v[106:107], v9 offset0:115 offset1:123
	ds_read2_b32 v[108:109], v9 offset0:148 offset1:156
	ds_read2_b32 v[110:111], v9 offset0:181 offset1:189
	ds_read2_b32 v[112:113], v9 offset0:214 offset1:222
	ds_read2_b32 v[114:115], v9 offset0:247 offset1:255
	s_waitcnt lgkmcnt(0)
	v_mul_f32_e32 v84, 0x42800000, v84
	v_mul_f32_e32 v85, 0x42800000, v85
	v_mul_f32_e32 v86, 0x42800000, v86
	v_mul_f32_e32 v87, 0x42800000, v87
	v_mul_f32_e32 v88, 0x42800000, v88
	v_mul_f32_e32 v89, 0x42800000, v89
	v_mul_f32_e32 v90, 0x42800000, v90
	v_mul_f32_e32 v91, 0x42800000, v91
	v_mul_f32_e32 v92, 0x42800000, v92
	v_mul_f32_e32 v93, 0x42800000, v93
	v_mul_f32_e32 v94, 0x42800000, v94
	v_mul_f32_e32 v95, 0x42800000, v95
	v_mul_f32_e32 v96, 0x42800000, v96
	v_mul_f32_e32 v97, 0x42800000, v97
	v_mul_f32_e32 v98, 0x42800000, v98
	v_mul_f32_e32 v99, 0x42800000, v99
	v_mul_f32_e32 v100, 0x42800000, v100
	v_mul_f32_e32 v101, 0x42800000, v101
	v_mul_f32_e32 v102, 0x42800000, v102
	v_mul_f32_e32 v103, 0x42800000, v103
	v_mul_f32_e32 v104, 0x42800000, v104
	v_mul_f32_e32 v105, 0x42800000, v105
	v_mul_f32_e32 v106, 0x42800000, v106
	v_mul_f32_e32 v107, 0x42800000, v107
	v_mul_f32_e32 v108, 0x42800000, v108
	v_mul_f32_e32 v109, 0x42800000, v109
	v_mul_f32_e32 v110, 0x42800000, v110
	v_mul_f32_e32 v111, 0x42800000, v111
	v_mul_f32_e32 v112, 0x42800000, v112
	v_mul_f32_e32 v113, 0x42800000, v113
	v_mul_f32_e32 v114, 0x42800000, v114
	v_mul_f32_e32 v115, 0x42800000, v115
	v_cvt_pk_fp8_f32 v116, v84, v86
	v_cvt_pk_fp8_f32 v117, v92, v94
	v_cvt_pk_fp8_f32 v116, v88, v90 op_sel:[0,0,1]
	v_cvt_pk_fp8_f32 v117, v96, v98 op_sel:[0,0,1]
	v_cvt_pk_fp8_f32 v118, v85, v87
	v_cvt_pk_fp8_f32 v119, v93, v95
	v_cvt_pk_fp8_f32 v118, v89, v91 op_sel:[0,0,1]
	v_cvt_pk_fp8_f32 v119, v97, v99 op_sel:[0,0,1]
	v_cvt_pk_fp8_f32 v120, v100, v102
	v_cvt_pk_fp8_f32 v121, v108, v110
	v_cvt_pk_fp8_f32 v120, v104, v106 op_sel:[0,0,1]
	v_cvt_pk_fp8_f32 v121, v112, v114 op_sel:[0,0,1]
	v_cvt_pk_fp8_f32 v122, v101, v103
	v_cvt_pk_fp8_f32 v123, v109, v111
	v_cvt_pk_fp8_f32 v122, v105, v107 op_sel:[0,0,1]
	v_cvt_pk_fp8_f32 v123, v113, v115 op_sel:[0,0,1]
	global_store_dwordx2 v14, v[116:117], s[46:47]
	global_store_dwordx2 v15, v[118:119], s[46:47]
	global_store_dwordx2 v16, v[120:121], s[46:47]
	global_store_dwordx2 v17, v[122:123], s[46:47]
	s_mov_b32 s36, s20
	s_add_i32 s20, s20, s16
	s_cmp_ge_i32 s20, 0x4000
	s_cbranch_scc1 .Lp0b_lastB
	s_lshr_b32 s37, s20, 8
	s_and_b32 s38, s20, 255
	s_mul_i32 s37, s37, 0x600000
	s_lshl_b32 s38, s38, 7
	s_add_u32 s37, s37, s38
	s_add_u32 s10, s44, s37
	s_addc_u32 s11, s45, 0
	s_add_u32 s12, s10, 0x180000
	s_addc_u32 s13, s11, 0
	s_add_u32 s14, s12, 0x180000
	s_addc_u32 s15, s13, 0
	s_add_u32 s18, s14, 0x180000
	s_addc_u32 s19, s15, 0
	global_load_dword v20, v0, s[10:11] nt
	global_load_dword v21, v1, s[10:11] nt
	global_load_dword v22, v2, s[10:11] nt
	global_load_dword v23, v3, s[10:11] nt
	global_load_dword v24, v4, s[10:11] nt
	global_load_dword v25, v5, s[10:11] nt
	global_load_dword v26, v6, s[10:11] nt
	global_load_dword v27, v7, s[10:11] nt
	global_load_dword v28, v0, s[12:13] nt
	global_load_dword v29, v1, s[12:13] nt
	global_load_dword v30, v2, s[12:13] nt
	global_load_dword v31, v3, s[12:13] nt
	global_load_dword v32, v4, s[12:13] nt
	global_load_dword v33, v5, s[12:13] nt
	global_load_dword v34, v6, s[12:13] nt
	global_load_dword v35, v7, s[12:13] nt
	global_load_dword v36, v0, s[14:15] nt
	global_load_dword v37, v1, s[14:15] nt
	global_load_dword v38, v2, s[14:15] nt
	global_load_dword v39, v3, s[14:15] nt
	global_load_dword v40, v4, s[14:15] nt
	global_load_dword v41, v5, s[14:15] nt
	global_load_dword v42, v6, s[14:15] nt
	global_load_dword v43, v7, s[14:15] nt
	global_load_dword v44, v0, s[18:19] nt
	global_load_dword v45, v1, s[18:19] nt
	global_load_dword v46, v2, s[18:19] nt
	global_load_dword v47, v3, s[18:19] nt
	global_load_dword v48, v4, s[18:19] nt
	global_load_dword v49, v5, s[18:19] nt
	global_load_dword v50, v6, s[18:19] nt
	global_load_dword v51, v7, s[18:19] nt
	s_waitcnt vmcnt(32)
	ds_write_b32 v8, v52 offset:0
	ds_write_b32 v8, v53 offset:264
	ds_write_b32 v8, v54 offset:528
	ds_write_b32 v8, v55 offset:792
	ds_write_b32 v8, v56 offset:1056
	ds_write_b32 v8, v57 offset:1320
	ds_write_b32 v8, v58 offset:1584
	ds_write_b32 v8, v59 offset:1848
	ds_write_b32 v8, v60 offset:2112
	ds_write_b32 v8, v61 offset:2376
	ds_write_b32 v8, v62 offset:2640
	ds_write_b32 v8, v63 offset:2904
	ds_write_b32 v8, v64 offset:3168
	ds_write_b32 v8, v65 offset:3432
	ds_write_b32 v8, v66 offset:3696
	ds_write_b32 v8, v67 offset:3960
	ds_write_b32 v8, v68 offset:4224
	ds_write_b32 v8, v69 offset:4488
	ds_write_b32 v8, v70 offset:4752
	ds_write_b32 v8, v71 offset:5016
	ds_write_b32 v8, v72 offset:5280
	ds_write_b32 v8, v73 offset:5544
	ds_write_b32 v8, v74 offset:5808
	ds_write_b32 v8, v75 offset:6072
	ds_write_b32 v8, v76 offset:6336
	ds_write_b32 v8, v77 offset:6600
	ds_write_b32 v8, v78 offset:6864
	ds_write_b32 v8, v79 offset:7128
	ds_write_b32 v8, v80 offset:7392
	ds_write_b32 v8, v81 offset:7656
	ds_write_b32 v8, v82 offset:7920
	ds_write_b32 v8, v83 offset:8184
	s_lshr_b32 s37, s36, 8
	s_and_b32 s38, s36, 255
	s_lshl_b32 s37, s37, 6
	s_lshl_b32 s38, s38, 17
	s_add_u32 s37, s37, s38
	s_add_u32 s46, s0, s37
	s_addc_u32 s47, s1, 0
	s_waitcnt lgkmcnt(0)
	ds_read2_b32 v[84:85], v9 offset0:0 offset1:8
	ds_read2_b32 v[86:87], v9 offset0:33 offset1:41
	ds_read2_b32 v[88:89], v9 offset0:66 offset1:74
	ds_read2_b32 v[90:91], v9 offset0:99 offset1:107
	ds_read2_b32 v[92:93], v9 offset0:132 offset1:140
	ds_read2_b32 v[94:95], v9 offset0:165 offset1:173
	ds_read2_b32 v[96:97], v9 offset0:198 offset1:206
	ds_read2_b32 v[98:99], v9 offset0:231 offset1:239
	ds_read2_b32 v[100:101], v9 offset0:16 offset1:24
	ds_read2_b32 v[102:103], v9 offset0:49 offset1:57
	ds_read2_b32 v[104:105], v9 offset0:82 offset1:90
	ds_read2_b32 v[106:107], v9 offset0:115 offset1:123
	ds_read2_b32 v[108:109], v9 offset0:148 offset1:156
	ds_read2_b32 v[110:111], v9 offset0:181 offset1:189
	ds_read2_b32 v[112:113], v9 offset0:214 offset1:222
	ds_read2_b32 v[114:115], v9 offset0:247 offset1:255
	s_waitcnt lgkmcnt(0)
	v_mul_f32_e32 v84, 0x42800000, v84
	v_mul_f32_e32 v85, 0x42800000, v85
	v_mul_f32_e32 v86, 0x42800000, v86
	v_mul_f32_e32 v87, 0x42800000, v87
	v_mul_f32_e32 v88, 0x42800000, v88
	v_mul_f32_e32 v89, 0x42800000, v89
	v_mul_f32_e32 v90, 0x42800000, v90
	v_mul_f32_e32 v91, 0x42800000, v91
	v_mul_f32_e32 v92, 0x42800000, v92
	v_mul_f32_e32 v93, 0x42800000, v93
	v_mul_f32_e32 v94, 0x42800000, v94
	v_mul_f32_e32 v95, 0x42800000, v95
	v_mul_f32_e32 v96, 0x42800000, v96
	v_mul_f32_e32 v97, 0x42800000, v97
	v_mul_f32_e32 v98, 0x42800000, v98
	v_mul_f32_e32 v99, 0x42800000, v99
	v_mul_f32_e32 v100, 0x42800000, v100
	v_mul_f32_e32 v101, 0x42800000, v101
	v_mul_f32_e32 v102, 0x42800000, v102
	v_mul_f32_e32 v103, 0x42800000, v103
	v_mul_f32_e32 v104, 0x42800000, v104
	v_mul_f32_e32 v105, 0x42800000, v105
	v_mul_f32_e32 v106, 0x42800000, v106
	v_mul_f32_e32 v107, 0x42800000, v107
	v_mul_f32_e32 v108, 0x42800000, v108
	v_mul_f32_e32 v109, 0x42800000, v109
	v_mul_f32_e32 v110, 0x42800000, v110
	v_mul_f32_e32 v111, 0x42800000, v111
	v_mul_f32_e32 v112, 0x42800000, v112
	v_mul_f32_e32 v113, 0x42800000, v113
	v_mul_f32_e32 v114, 0x42800000, v114
	v_mul_f32_e32 v115, 0x42800000, v115
	v_cvt_pk_fp8_f32 v116, v84, v86
	v_cvt_pk_fp8_f32 v117, v92, v94
	v_cvt_pk_fp8_f32 v116, v88, v90 op_sel:[0,0,1]
	v_cvt_pk_fp8_f32 v117, v96, v98 op_sel:[0,0,1]
	v_cvt_pk_fp8_f32 v118, v85, v87
	v_cvt_pk_fp8_f32 v119, v93, v95
	v_cvt_pk_fp8_f32 v118, v89, v91 op_sel:[0,0,1]
	v_cvt_pk_fp8_f32 v119, v97, v99 op_sel:[0,0,1]
	v_cvt_pk_fp8_f32 v120, v100, v102
	v_cvt_pk_fp8_f32 v121, v108, v110
	v_cvt_pk_fp8_f32 v120, v104, v106 op_sel:[0,0,1]
	v_cvt_pk_fp8_f32 v121, v112, v114 op_sel:[0,0,1]
	v_cvt_pk_fp8_f32 v122, v101, v103
	v_cvt_pk_fp8_f32 v123, v109, v111
	v_cvt_pk_fp8_f32 v122, v105, v107 op_sel:[0,0,1]
	v_cvt_pk_fp8_f32 v123, v113, v115 op_sel:[0,0,1]
	global_store_dwordx2 v14, v[116:117], s[46:47]
	global_store_dwordx2 v15, v[118:119], s[46:47]
	global_store_dwordx2 v16, v[120:121], s[46:47]
	global_store_dwordx2 v17, v[122:123], s[46:47]
	s_mov_b32 s36, s20
	s_add_i32 s20, s20, s16
	s_branch .Lp0b_loop
.Lp0b_lastA:
	s_waitcnt vmcnt(0)
	ds_write_b32 v8, v20 offset:0
	ds_write_b32 v8, v21 offset:264
	ds_write_b32 v8, v22 offset:528
	ds_write_b32 v8, v23 offset:792
	ds_write_b32 v8, v24 offset:1056
	ds_write_b32 v8, v25 offset:1320
	ds_write_b32 v8, v26 offset:1584
	ds_write_b32 v8, v27 offset:1848
	ds_write_b32 v8, v28 offset:2112
	ds_write_b32 v8, v29 offset:2376
	ds_write_b32 v8, v30 offset:2640
	ds_write_b32 v8, v31 offset:2904
	ds_write_b32 v8, v32 offset:3168
	ds_write_b32 v8, v33 offset:3432
	ds_write_b32 v8, v34 offset:3696
	ds_write_b32 v8, v35 offset:3960
	ds_write_b32 v8, v36 offset:4224
	ds_write_b32 v8, v37 offset:4488
	ds_write_b32 v8, v38 offset:4752
	ds_write_b32 v8, v39 offset:5016
	ds_write_b32 v8, v40 offset:5280
	ds_write_b32 v8, v41 offset:5544
	ds_write_b32 v8, v42 offset:5808
	ds_write_b32 v8, v43 offset:6072
	ds_write_b32 v8, v44 offset:6336
	ds_write_b32 v8, v45 offset:6600
	ds_write_b32 v8, v46 offset:6864
	ds_write_b32 v8, v47 offset:7128
	ds_write_b32 v8, v48 offset:7392
	ds_write_b32 v8, v49 offset:7656
	ds_write_b32 v8, v50 offset:7920
	ds_write_b32 v8, v51 offset:8184
	s_lshr_b32 s37, s36, 8
	s_and_b32 s38, s36, 255
	s_lshl_b32 s37, s37, 6
	s_lshl_b32 s38, s38, 17
	s_add_u32 s37, s37, s38
	s_add_u32 s46, s0, s37
	s_addc_u32 s47, s1, 0
	s_waitcnt lgkmcnt(0)
	ds_read2_b32 v[84:85], v9 offset0:0 offset1:8
	ds_read2_b32 v[86:87], v9 offset0:33 offset1:41
	ds_read2_b32 v[88:89], v9 offset0:66 offset1:74
	ds_read2_b32 v[90:91], v9 offset0:99 offset1:107
	ds_read2_b32 v[92:93], v9 offset0:132 offset1:140
	ds_read2_b32 v[94:95], v9 offset0:165 offset1:173
	ds_read2_b32 v[96:97], v9 offset0:198 offset1:206
	ds_read2_b32 v[98:99], v9 offset0:231 offset1:239
	ds_read2_b32 v[100:101], v9 offset0:16 offset1:24
	ds_read2_b32 v[102:103], v9 offset0:49 offset1:57
	ds_read2_b32 v[104:105], v9 offset0:82 offset1:90
	ds_read2_b32 v[106:107], v9 offset0:115 offset1:123
	ds_read2_b32 v[108:109], v9 offset0:148 offset1:156
	ds_read2_b32 v[110:111], v9 offset0:181 offset1:189
	ds_read2_b32 v[112:113], v9 offset0:214 offset1:222
	ds_read2_b32 v[114:115], v9 offset0:247 offset1:255
	s_waitcnt lgkmcnt(0)
	v_mul_f32_e32 v84, 0x42800000, v84
	v_mul_f32_e32 v85, 0x42800000, v85
	v_mul_f32_e32 v86, 0x42800000, v86
	v_mul_f32_e32 v87, 0x42800000, v87
	v_mul_f32_e32 v88, 0x42800000, v88
	v_mul_f32_e32 v89, 0x42800000, v89
	v_mul_f32_e32 v90, 0x42800000, v90
	v_mul_f32_e32 v91, 0x42800000, v91
	v_mul_f32_e32 v92, 0x42800000, v92
	v_mul_f32_e32 v93, 0x42800000, v93
	v_mul_f32_e32 v94, 0x42800000, v94
	v_mul_f32_e32 v95, 0x42800000, v95
	v_mul_f32_e32 v96, 0x42800000, v96
	v_mul_f32_e32 v97, 0x42800000, v97
	v_mul_f32_e32 v98, 0x42800000, v98
	v_mul_f32_e32 v99, 0x42800000, v99
	v_mul_f32_e32 v100, 0x42800000, v100
	v_mul_f32_e32 v101, 0x42800000, v101
	v_mul_f32_e32 v102, 0x42800000, v102
	v_mul_f32_e32 v103, 0x42800000, v103
	v_mul_f32_e32 v104, 0x42800000, v104
	v_mul_f32_e32 v105, 0x42800000, v105
	v_mul_f32_e32 v106, 0x42800000, v106
	v_mul_f32_e32 v107, 0x42800000, v107
	v_mul_f32_e32 v108, 0x42800000, v108
	v_mul_f32_e32 v109, 0x42800000, v109
	v_mul_f32_e32 v110, 0x42800000, v110
	v_mul_f32_e32 v111, 0x42800000, v111
	v_mul_f32_e32 v112, 0x42800000, v112
	v_mul_f32_e32 v113, 0x42800000, v113
	v_mul_f32_e32 v114, 0x42800000, v114
	v_mul_f32_e32 v115, 0x42800000, v115
	v_cvt_pk_fp8_f32 v116, v84, v86
	v_cvt_pk_fp8_f32 v117, v92, v94
	v_cvt_pk_fp8_f32 v116, v88, v90 op_sel:[0,0,1]
	v_cvt_pk_fp8_f32 v117, v96, v98 op_sel:[0,0,1]
	v_cvt_pk_fp8_f32 v118, v85, v87
	v_cvt_pk_fp8_f32 v119, v93, v95
	v_cvt_pk_fp8_f32 v118, v89, v91 op_sel:[0,0,1]
	v_cvt_pk_fp8_f32 v119, v97, v99 op_sel:[0,0,1]
	v_cvt_pk_fp8_f32 v120, v100, v102
	v_cvt_pk_fp8_f32 v121, v108, v110
	v_cvt_pk_fp8_f32 v120, v104, v106 op_sel:[0,0,1]
	v_cvt_pk_fp8_f32 v121, v112, v114 op_sel:[0,0,1]
	v_cvt_pk_fp8_f32 v122, v101, v103
	v_cvt_pk_fp8_f32 v123, v109, v111
	v_cvt_pk_fp8_f32 v122, v105, v107 op_sel:[0,0,1]
	v_cvt_pk_fp8_f32 v123, v113, v115 op_sel:[0,0,1]
	global_store_dwordx2 v14, v[116:117], s[46:47]
	global_store_dwordx2 v15, v[118:119], s[46:47]
	global_store_dwordx2 v16, v[120:121], s[46:47]
	global_store_dwordx2 v17, v[122:123], s[46:47]
	s_branch .Lp0b_done
.Lp0b_lastB:
	s_waitcnt vmcnt(0)
	ds_write_b32 v8, v52 offset:0
	ds_write_b32 v8, v53 offset:264
	ds_write_b32 v8, v54 offset:528
	ds_write_b32 v8, v55 offset:792
	ds_write_b32 v8, v56 offset:1056
	ds_write_b32 v8, v57 offset:1320
	ds_write_b32 v8, v58 offset:1584
	ds_write_b32 v8, v59 offset:1848
	ds_write_b32 v8, v60 offset:2112
	ds_write_b32 v8, v61 offset:2376
	ds_write_b32 v8, v62 offset:2640
	ds_write_b32 v8, v63 offset:2904
	ds_write_b32 v8, v64 offset:3168
	ds_write_b32 v8, v65 offset:3432
	ds_write_b32 v8, v66 offset:3696
	ds_write_b32 v8, v67 offset:3960
	ds_write_b32 v8, v68 offset:4224
	ds_write_b32 v8, v69 offset:4488
	ds_write_b32 v8, v70 offset:4752
	ds_write_b32 v8, v71 offset:5016
	ds_write_b32 v8, v72 offset:5280
	ds_write_b32 v8, v73 offset:5544
	ds_write_b32 v8, v74 offset:5808
	ds_write_b32 v8, v75 offset:6072
	ds_write_b32 v8, v76 offset:6336
	ds_write_b32 v8, v77 offset:6600
	ds_write_b32 v8, v78 offset:6864
	ds_write_b32 v8, v79 offset:7128
	ds_write_b32 v8, v80 offset:7392
	ds_write_b32 v8, v81 offset:7656
	ds_write_b32 v8, v82 offset:7920
	ds_write_b32 v8, v83 offset:8184
	s_lshr_b32 s37, s36, 8
	s_and_b32 s38, s36, 255
	s_lshl_b32 s37, s37, 6
	s_lshl_b32 s38, s38, 17
	s_add_u32 s37, s37, s38
	s_add_u32 s46, s0, s37
	s_addc_u32 s47, s1, 0
	s_waitcnt lgkmcnt(0)
	ds_read2_b32 v[84:85], v9 offset0:0 offset1:8
	ds_read2_b32 v[86:87], v9 offset0:33 offset1:41
	ds_read2_b32 v[88:89], v9 offset0:66 offset1:74
	ds_read2_b32 v[90:91], v9 offset0:99 offset1:107
	ds_read2_b32 v[92:93], v9 offset0:132 offset1:140
	ds_read2_b32 v[94:95], v9 offset0:165 offset1:173
	ds_read2_b32 v[96:97], v9 offset0:198 offset1:206
	ds_read2_b32 v[98:99], v9 offset0:231 offset1:239
	ds_read2_b32 v[100:101], v9 offset0:16 offset1:24
	ds_read2_b32 v[102:103], v9 offset0:49 offset1:57
	ds_read2_b32 v[104:105], v9 offset0:82 offset1:90
	ds_read2_b32 v[106:107], v9 offset0:115 offset1:123
	ds_read2_b32 v[108:109], v9 offset0:148 offset1:156
	ds_read2_b32 v[110:111], v9 offset0:181 offset1:189
	ds_read2_b32 v[112:113], v9 offset0:214 offset1:222
	ds_read2_b32 v[114:115], v9 offset0:247 offset1:255
	s_waitcnt lgkmcnt(0)
	v_mul_f32_e32 v84, 0x42800000, v84
	v_mul_f32_e32 v85, 0x42800000, v85
	v_mul_f32_e32 v86, 0x42800000, v86
	v_mul_f32_e32 v87, 0x42800000, v87
	v_mul_f32_e32 v88, 0x42800000, v88
	v_mul_f32_e32 v89, 0x42800000, v89
	v_mul_f32_e32 v90, 0x42800000, v90
	v_mul_f32_e32 v91, 0x42800000, v91
	v_mul_f32_e32 v92, 0x42800000, v92
	v_mul_f32_e32 v93, 0x42800000, v93
	v_mul_f32_e32 v94, 0x42800000, v94
	v_mul_f32_e32 v95, 0x42800000, v95
	v_mul_f32_e32 v96, 0x42800000, v96
	v_mul_f32_e32 v97, 0x42800000, v97
	v_mul_f32_e32 v98, 0x42800000, v98
	v_mul_f32_e32 v99, 0x42800000, v99
	v_mul_f32_e32 v100, 0x42800000, v100
	v_mul_f32_e32 v101, 0x42800000, v101
	v_mul_f32_e32 v102, 0x42800000, v102
	v_mul_f32_e32 v103, 0x42800000, v103
	v_mul_f32_e32 v104, 0x42800000, v104
	v_mul_f32_e32 v105, 0x42800000, v105
	v_mul_f32_e32 v106, 0x42800000, v106
	v_mul_f32_e32 v107, 0x42800000, v107
	v_mul_f32_e32 v108, 0x42800000, v108
	v_mul_f32_e32 v109, 0x42800000, v109
	v_mul_f32_e32 v110, 0x42800000, v110
	v_mul_f32_e32 v111, 0x42800000, v111
	v_mul_f32_e32 v112, 0x42800000, v112
	v_mul_f32_e32 v113, 0x42800000, v113
	v_mul_f32_e32 v114, 0x42800000, v114
	v_mul_f32_e32 v115, 0x42800000, v115
	v_cvt_pk_fp8_f32 v116, v84, v86
	v_cvt_pk_fp8_f32 v117, v92, v94
	v_cvt_pk_fp8_f32 v116, v88, v90 op_sel:[0,0,1]
	v_cvt_pk_fp8_f32 v117, v96, v98 op_sel:[0,0,1]
	v_cvt_pk_fp8_f32 v118, v85, v87
	v_cvt_pk_fp8_f32 v119, v93, v95
	v_cvt_pk_fp8_f32 v118, v89, v91 op_sel:[0,0,1]
	v_cvt_pk_fp8_f32 v119, v97, v99 op_sel:[0,0,1]
	v_cvt_pk_fp8_f32 v120, v100, v102
	v_cvt_pk_fp8_f32 v121, v108, v110
	v_cvt_pk_fp8_f32 v120, v104, v106 op_sel:[0,0,1]
	v_cvt_pk_fp8_f32 v121, v112, v114 op_sel:[0,0,1]
	v_cvt_pk_fp8_f32 v122, v101, v103
	v_cvt_pk_fp8_f32 v123, v109, v111
	v_cvt_pk_fp8_f32 v122, v105, v107 op_sel:[0,0,1]
	v_cvt_pk_fp8_f32 v123, v113, v115 op_sel:[0,0,1]
	global_store_dwordx2 v14, v[116:117], s[46:47]
	global_store_dwordx2 v15, v[118:119], s[46:47]
	global_store_dwordx2 v16, v[120:121], s[46:47]
	global_store_dwordx2 v17, v[122:123], s[46:47]
.Lp0b_done:
	s_cmp_ge_i32 s3, 0x2000
	s_cbranch_scc1 .Lp0c_done
	v_readlane_b32 s36, v239, 3
	v_readlane_b32 s37, v239, 4
	v_readlane_b32 s38, v239, 5
	v_readlane_b32 s39, v239, 6
	v_lshlrev_b32_e32 v0, 4, v182
	v_add_u32_e32 v1, 0x1000, v0
	v_add_u32_e32 v2, 0x2000, v0
	v_add_u32_e32 v3, 0x3000, v0
	v_lshlrev_b32_e32 v4, 3, v182
	v_add_u32_e32 v5, 0x1000, v4
	v_lshlrev_b32_e32 v6, 2, v182
	v_xor_b32_e32 v7, 1, v182
	v_lshlrev_b32_e32 v8, 2, v7
	v_xor_b32_e32 v7, 2, v182
	v_lshlrev_b32_e32 v9, 2, v7
	v_xor_b32_e32 v7, 4, v182
	v_lshlrev_b32_e32 v10, 2, v7
	v_xor_b32_e32 v7, 8, v182
	v_lshlrev_b32_e32 v11, 2, v7
	v_xor_b32_e32 v7, 16, v182
	v_lshlrev_b32_e32 v12, 2, v7
	v_xor_b32_e32 v7, 32, v182
	v_lshlrev_b32_e32 v13, 2, v7
	v_mov_b32_e32 v14, 0x358637bd
	global_load_dwordx4 v[16:19], v0, s[38:39] offset:0
	global_load_dwordx4 v[20:23], v0, s[38:39] offset:1024
	global_load_dwordx4 v[24:27], v0, s[38:39] offset:2048
	global_load_dwordx4 v[28:31], v0, s[38:39] offset:3072
	global_load_dwordx4 v[32:35], v1, s[38:39] offset:0
	global_load_dwordx4 v[36:39], v1, s[38:39] offset:1024
	global_load_dwordx4 v[40:43], v1, s[38:39] offset:2048
	global_load_dwordx4 v[44:47], v1, s[38:39] offset:3072
	global_load_dwordx4 v[48:51], v2, s[38:39] offset:0
	global_load_dwordx4 v[52:55], v2, s[38:39] offset:1024
	global_load_dwordx4 v[56:59], v2, s[38:39] offset:2048
	global_load_dwordx4 v[60:63], v2, s[38:39] offset:3072
	global_load_dwordx4 v[64:67], v3, s[38:39] offset:0
	global_load_dwordx4 v[68:71], v3, s[38:39] offset:1024
	global_load_dwordx4 v[72:75], v3, s[38:39] offset:2048
	global_load_dwordx4 v[76:79], v3, s[38:39] offset:3072
.Lp0c_row:
	s_lshl_b32 s10, s3, 14
	s_add_u32 s12, s36, s10
	s_addc_u32 s13, s37, 0
	global_load_dwordx4 v[80:83], v0, s[12:13] offset:0 nt
	global_load_dwordx4 v[84:87], v0, s[12:13] offset:1024 nt
	global_load_dwordx4 v[88:91], v0, s[12:13] offset:2048 nt
	global_load_dwordx4 v[92:95], v0, s[12:13] offset:3072 nt
	global_load_dwordx4 v[96:99], v1, s[12:13] offset:0 nt
	global_load_dwordx4 v[100:103], v1, s[12:13] offset:1024 nt
	global_load_dwordx4 v[104:107], v1, s[12:13] offset:2048 nt
	global_load_dwordx4 v[108:111], v1, s[12:13] offset:3072 nt
	global_load_dwordx4 v[112:115], v2, s[12:13] offset:0 nt
	global_load_dwordx4 v[116:119], v2, s[12:13] offset:1024 nt
	global_load_dwordx4 v[120:123], v2, s[12:13] offset:2048 nt
	global_load_dwordx4 v[124:127], v2, s[12:13] offset:3072 nt
	global_load_dwordx4 v[128:131], v3, s[12:13] offset:0 nt
	global_load_dwordx4 v[132:135], v3, s[12:13] offset:1024 nt
	global_load_dwordx4 v[136:139], v3, s[12:13] offset:2048 nt
	global_load_dwordx4 v[140:143], v3, s[12:13] offset:3072 nt
	s_lshl_b32 s10, s3, 13
	s_add_u32 s14, s92, s10
	s_addc_u32 s15, s93, 0
	s_lshl_b32 s10, s3, 12
	s_add_u32 s18, s4, s10
	s_addc_u32 s19, s5, 0
	s_add_i32 s3, s3, s16
	s_waitcnt vmcnt(15)
	v_mul_f32_e32 v144, v80, v80
	v_mul_f32_e32 v145, v81, v81
	v_mul_f32_e32 v146, v82, v82
	v_mul_f32_e32 v147, v83, v83
	s_waitcnt vmcnt(14)
	v_fmac_f32_e32 v144, v84, v84
	v_fmac_f32_e32 v145, v85, v85
	v_fmac_f32_e32 v146, v86, v86
	v_fmac_f32_e32 v147, v87, v87
	s_waitcnt vmcnt(13)
	v_fmac_f32_e32 v144, v88, v88
	v_fmac_f32_e32 v145, v89, v89
	v_fmac_f32_e32 v146, v90, v90
	v_fmac_f32_e32 v147, v91, v91
	s_waitcnt vmcnt(12)
	v_fmac_f32_e32 v144, v92, v92
	v_fmac_f32_e32 v145, v93, v93
	v_fmac_f32_e32 v146, v94, v94
	v_fmac_f32_e32 v147, v95, v95
	s_waitcnt vmcnt(11)
	v_fmac_f32_e32 v144, v96, v96
	v_fmac_f32_e32 v145, v97, v97
	v_fmac_f32_e32 v146, v98, v98
	v_fmac_f32_e32 v147, v99, v99
	s_waitcnt vmcnt(10)
	v_fmac_f32_e32 v144, v100, v100
	v_fmac_f32_e32 v145, v101, v101
	v_fmac_f32_e32 v146, v102, v102
	v_fmac_f32_e32 v147, v103, v103
	s_waitcnt vmcnt(9)
	v_fmac_f32_e32 v144, v104, v104
	v_fmac_f32_e32 v145, v105, v105
	v_fmac_f32_e32 v146, v106, v106
	v_fmac_f32_e32 v147, v107, v107
	s_waitcnt vmcnt(8)
	v_fmac_f32_e32 v144, v108, v108
	v_fmac_f32_e32 v145, v109, v109
	v_fmac_f32_e32 v146, v110, v110
	v_fmac_f32_e32 v147, v111, v111
	s_waitcnt vmcnt(7)
	v_fmac_f32_e32 v144, v112, v112
	v_fmac_f32_e32 v145, v113, v113
	v_fmac_f32_e32 v146, v114, v114
	v_fmac_f32_e32 v147, v115, v115
	s_waitcnt vmcnt(6)
	v_fmac_f32_e32 v144, v116, v116
	v_fmac_f32_e32 v145, v117, v117
	v_fmac_f32_e32 v146, v118, v118
	v_fmac_f32_e32 v147, v119, v119
	s_waitcnt vmcnt(5)
	v_fmac_f32_e32 v144, v120, v120
	v_fmac_f32_e32 v145, v121, v121
	v_fmac_f32_e32 v146, v122, v122
	v_fmac_f32_e32 v147, v123, v123
	s_waitcnt vmcnt(4)
	v_fmac_f32_e32 v144, v124, v124
	v_fmac_f32_e32 v145, v125, v125
	v_fmac_f32_e32 v146, v126, v126
	v_fmac_f32_e32 v147, v127, v127
	s_waitcnt vmcnt(3)
	v_fmac_f32_e32 v144, v128, v128
	v_fmac_f32_e32 v145, v129, v129
	v_fmac_f32_e32 v146, v130, v130
	v_fmac_f32_e32 v147, v131, v131
	s_waitcnt vmcnt(2)
	v_fmac_f32_e32 v144, v132, v132
	v_fmac_f32_e32 v145, v133, v133
	v_fmac_f32_e32 v146, v134, v134
	v_fmac_f32_e32 v147, v135, v135
	s_waitcnt vmcnt(1)
	v_fmac_f32_e32 v144, v136, v136
	v_fmac_f32_e32 v145, v137, v137
	v_fmac_f32_e32 v146, v138, v138
	v_fmac_f32_e32 v147, v139, v139
	s_waitcnt vmcnt(0)
	v_fmac_f32_e32 v144, v140, v140
	v_fmac_f32_e32 v145, v141, v141
	v_fmac_f32_e32 v146, v142, v142
	v_fmac_f32_e32 v147, v143, v143
	v_add_f32_e32 v144, v144, v145
	v_add_f32_e32 v146, v146, v147
	v_add_f32_e32 v144, v144, v146
	ds_bpermute_b32 v145, v8, v144
	s_waitcnt lgkmcnt(0)
	v_add_f32_e32 v144, v144, v145
	ds_bpermute_b32 v145, v9, v144
	s_waitcnt lgkmcnt(0)
	v_add_f32_e32 v144, v144, v145
	ds_bpermute_b32 v145, v10, v144
	s_waitcnt lgkmcnt(0)
	v_add_f32_e32 v144, v144, v145
	ds_bpermute_b32 v145, v11, v144
	s_waitcnt lgkmcnt(0)
	v_add_f32_e32 v144, v144, v145
	ds_bpermute_b32 v145, v12, v144
	s_waitcnt lgkmcnt(0)
	v_add_f32_e32 v144, v144, v145
	ds_bpermute_b32 v145, v13, v144
	s_waitcnt lgkmcnt(0)
	v_add_f32_e32 v144, v144, v145
	v_fmamk_f32 v144, v144, 0x39800000, v14
	v_rsq_f32_e32 v144, v144
	s_nop 0
	v_pk_mul_f32 v[80:81], v[80:81], v[144:145] op_sel_hi:[1,0]
	v_pk_mul_f32 v[82:83], v[82:83], v[144:145] op_sel_hi:[1,0]
	v_pk_mul_f32 v[80:81], v[80:81], v[16:17]
	v_pk_mul_f32 v[82:83], v[82:83], v[18:19]
	v_cvt_pk_fp8_f32 v148, v80, v81
	v_cvt_pk_bf16_f32 v80, v80, v81
	v_cvt_pk_fp8_f32 v148, v82, v83 op_sel:[0,0,1]
	v_cvt_pk_bf16_f32 v81, v82, v83
	global_store_dwordx2 v4, v[80:81], s[14:15] offset:0
	global_store_dword v6, v148, s[18:19] offset:0
	v_pk_mul_f32 v[84:85], v[84:85], v[144:145] op_sel_hi:[1,0]
	v_pk_mul_f32 v[86:87], v[86:87], v[144:145] op_sel_hi:[1,0]
	v_pk_mul_f32 v[84:85], v[84:85], v[20:21]
	v_pk_mul_f32 v[86:87], v[86:87], v[22:23]
	v_cvt_pk_fp8_f32 v149, v84, v85
	v_cvt_pk_bf16_f32 v84, v84, v85
	v_cvt_pk_fp8_f32 v149, v86, v87 op_sel:[0,0,1]
	v_cvt_pk_bf16_f32 v85, v86, v87
	global_store_dwordx2 v4, v[84:85], s[14:15] offset:512
	global_store_dword v6, v149, s[18:19] offset:256
	v_pk_mul_f32 v[88:89], v[88:89], v[144:145] op_sel_hi:[1,0]
	v_pk_mul_f32 v[90:91], v[90:91], v[144:145] op_sel_hi:[1,0]
	v_pk_mul_f32 v[88:89], v[88:89], v[24:25]
	v_pk_mul_f32 v[90:91], v[90:91], v[26:27]
	v_cvt_pk_fp8_f32 v150, v88, v89
	v_cvt_pk_bf16_f32 v88, v88, v89
	v_cvt_pk_fp8_f32 v150, v90, v91 op_sel:[0,0,1]
	v_cvt_pk_bf16_f32 v89, v90, v91
	global_store_dwordx2 v4, v[88:89], s[14:15] offset:1024
	global_store_dword v6, v150, s[18:19] offset:512
	v_pk_mul_f32 v[92:93], v[92:93], v[144:145] op_sel_hi:[1,0]
	v_pk_mul_f32 v[94:95], v[94:95], v[144:145] op_sel_hi:[1,0]
	v_pk_mul_f32 v[92:93], v[92:93], v[28:29]
	v_pk_mul_f32 v[94:95], v[94:95], v[30:31]
	v_cvt_pk_fp8_f32 v151, v92, v93
	v_cvt_pk_bf16_f32 v92, v92, v93
	v_cvt_pk_fp8_f32 v151, v94, v95 op_sel:[0,0,1]
	v_cvt_pk_bf16_f32 v93, v94, v95
	global_store_dwordx2 v4, v[92:93], s[14:15] offset:1536
	global_store_dword v6, v151, s[18:19] offset:768
	v_pk_mul_f32 v[96:97], v[96:97], v[144:145] op_sel_hi:[1,0]
	v_pk_mul_f32 v[98:99], v[98:99], v[144:145] op_sel_hi:[1,0]
	v_pk_mul_f32 v[96:97], v[96:97], v[32:33]
	v_pk_mul_f32 v[98:99], v[98:99], v[34:35]
	v_cvt_pk_fp8_f32 v152, v96, v97
	v_cvt_pk_bf16_f32 v96, v96, v97
	v_cvt_pk_fp8_f32 v152, v98, v99 op_sel:[0,0,1]
	v_cvt_pk_bf16_f32 v97, v98, v99
	global_store_dwordx2 v4, v[96:97], s[14:15] offset:2048
	global_store_dword v6, v152, s[18:19] offset:1024
	v_pk_mul_f32 v[100:101], v[100:101], v[144:145] op_sel_hi:[1,0]
	v_pk_mul_f32 v[102:103], v[102:103], v[144:145] op_sel_hi:[1,0]
	v_pk_mul_f32 v[100:101], v[100:101], v[36:37]
	v_pk_mul_f32 v[102:103], v[102:103], v[38:39]
	v_cvt_pk_fp8_f32 v153, v100, v101
	v_cvt_pk_bf16_f32 v100, v100, v101
	v_cvt_pk_fp8_f32 v153, v102, v103 op_sel:[0,0,1]
	v_cvt_pk_bf16_f32 v101, v102, v103
	global_store_dwordx2 v4, v[100:101], s[14:15] offset:2560
	global_store_dword v6, v153, s[18:19] offset:1280
	v_pk_mul_f32 v[104:105], v[104:105], v[144:145] op_sel_hi:[1,0]
	v_pk_mul_f32 v[106:107], v[106:107], v[144:145] op_sel_hi:[1,0]
	v_pk_mul_f32 v[104:105], v[104:105], v[40:41]
	v_pk_mul_f32 v[106:107], v[106:107], v[42:43]
	v_cvt_pk_fp8_f32 v154, v104, v105
	v_cvt_pk_bf16_f32 v104, v104, v105
	v_cvt_pk_fp8_f32 v154, v106, v107 op_sel:[0,0,1]
	v_cvt_pk_bf16_f32 v105, v106, v107
	global_store_dwordx2 v4, v[104:105], s[14:15] offset:3072
	global_store_dword v6, v154, s[18:19] offset:1536
	v_pk_mul_f32 v[108:109], v[108:109], v[144:145] op_sel_hi:[1,0]
	v_pk_mul_f32 v[110:111], v[110:111], v[144:145] op_sel_hi:[1,0]
	v_pk_mul_f32 v[108:109], v[108:109], v[44:45]
	v_pk_mul_f32 v[110:111], v[110:111], v[46:47]
	v_cvt_pk_fp8_f32 v155, v108, v109
	v_cvt_pk_bf16_f32 v108, v108, v109
	v_cvt_pk_fp8_f32 v155, v110, v111 op_sel:[0,0,1]
	v_cvt_pk_bf16_f32 v109, v110, v111
	global_store_dwordx2 v4, v[108:109], s[14:15] offset:3584
	global_store_dword v6, v155, s[18:19] offset:1792
	v_pk_mul_f32 v[112:113], v[112:113], v[144:145] op_sel_hi:[1,0]
	v_pk_mul_f32 v[114:115], v[114:115], v[144:145] op_sel_hi:[1,0]
	v_pk_mul_f32 v[112:113], v[112:113], v[48:49]
	v_pk_mul_f32 v[114:115], v[114:115], v[50:51]
	v_cvt_pk_fp8_f32 v156, v112, v113
	v_cvt_pk_bf16_f32 v112, v112, v113
	v_cvt_pk_fp8_f32 v156, v114, v115 op_sel:[0,0,1]
	v_cvt_pk_bf16_f32 v113, v114, v115
	global_store_dwordx2 v5, v[112:113], s[14:15] offset:0
	global_store_dword v6, v156, s[18:19] offset:2048
	v_pk_mul_f32 v[116:117], v[116:117], v[144:145] op_sel_hi:[1,0]
	v_pk_mul_f32 v[118:119], v[118:119], v[144:145] op_sel_hi:[1,0]
	v_pk_mul_f32 v[116:117], v[116:117], v[52:53]
	v_pk_mul_f32 v[118:119], v[118:119], v[54:55]
	v_cvt_pk_fp8_f32 v157, v116, v117
	v_cvt_pk_bf16_f32 v116, v116, v117
	v_cvt_pk_fp8_f32 v157, v118, v119 op_sel:[0,0,1]
	v_cvt_pk_bf16_f32 v117, v118, v119
	global_store_dwordx2 v5, v[116:117], s[14:15] offset:512
	global_store_dword v6, v157, s[18:19] offset:2304
	v_pk_mul_f32 v[120:121], v[120:121], v[144:145] op_sel_hi:[1,0]
	v_pk_mul_f32 v[122:123], v[122:123], v[144:145] op_sel_hi:[1,0]
	v_pk_mul_f32 v[120:121], v[120:121], v[56:57]
	v_pk_mul_f32 v[122:123], v[122:123], v[58:59]
	v_cvt_pk_fp8_f32 v158, v120, v121
	v_cvt_pk_bf16_f32 v120, v120, v121
	v_cvt_pk_fp8_f32 v158, v122, v123 op_sel:[0,0,1]
	v_cvt_pk_bf16_f32 v121, v122, v123
	global_store_dwordx2 v5, v[120:121], s[14:15] offset:1024
	global_store_dword v6, v158, s[18:19] offset:2560
	v_pk_mul_f32 v[124:125], v[124:125], v[144:145] op_sel_hi:[1,0]
	v_pk_mul_f32 v[126:127], v[126:127], v[144:145] op_sel_hi:[1,0]
	v_pk_mul_f32 v[124:125], v[124:125], v[60:61]
	v_pk_mul_f32 v[126:127], v[126:127], v[62:63]
	v_cvt_pk_fp8_f32 v159, v124, v125
	v_cvt_pk_bf16_f32 v124, v124, v125
	v_cvt_pk_fp8_f32 v159, v126, v127 op_sel:[0,0,1]
	v_cvt_pk_bf16_f32 v125, v126, v127
	global_store_dwordx2 v5, v[124:125], s[14:15] offset:1536
	global_store_dword v6, v159, s[18:19] offset:2816
	v_pk_mul_f32 v[128:129], v[128:129], v[144:145] op_sel_hi:[1,0]
	v_pk_mul_f32 v[130:131], v[130:131], v[144:145] op_sel_hi:[1,0]
	v_pk_mul_f32 v[128:129], v[128:129], v[64:65]
	v_pk_mul_f32 v[130:131], v[130:131], v[66:67]
	v_cvt_pk_fp8_f32 v160, v128, v129
	v_cvt_pk_bf16_f32 v128, v128, v129
	v_cvt_pk_fp8_f32 v160, v130, v131 op_sel:[0,0,1]
	v_cvt_pk_bf16_f32 v129, v130, v131
	global_store_dwordx2 v5, v[128:129], s[14:15] offset:2048
	global_store_dword v6, v160, s[18:19] offset:3072
	v_pk_mul_f32 v[132:133], v[132:133], v[144:145] op_sel_hi:[1,0]
	v_pk_mul_f32 v[134:135], v[134:135], v[144:145] op_sel_hi:[1,0]
	v_pk_mul_f32 v[132:133], v[132:133], v[68:69]
	v_pk_mul_f32 v[134:135], v[134:135], v[70:71]
	v_cvt_pk_fp8_f32 v161, v132, v133
	v_cvt_pk_bf16_f32 v132, v132, v133
	v_cvt_pk_fp8_f32 v161, v134, v135 op_sel:[0,0,1]
	v_cvt_pk_bf16_f32 v133, v134, v135
	global_store_dwordx2 v5, v[132:133], s[14:15] offset:2560
	global_store_dword v6, v161, s[18:19] offset:3328
	v_pk_mul_f32 v[136:137], v[136:137], v[144:145] op_sel_hi:[1,0]
	v_pk_mul_f32 v[138:139], v[138:139], v[144:145] op_sel_hi:[1,0]
	v_pk_mul_f32 v[136:137], v[136:137], v[72:73]
	v_pk_mul_f32 v[138:139], v[138:139], v[74:75]
	v_cvt_pk_fp8_f32 v162, v136, v137
	v_cvt_pk_bf16_f32 v136, v136, v137
	v_cvt_pk_fp8_f32 v162, v138, v139 op_sel:[0,0,1]
	v_cvt_pk_bf16_f32 v137, v138, v139
	global_store_dwordx2 v5, v[136:137], s[14:15] offset:3072
	global_store_dword v6, v162, s[18:19] offset:3584
	v_pk_mul_f32 v[140:141], v[140:141], v[144:145] op_sel_hi:[1,0]
	v_pk_mul_f32 v[142:143], v[142:143], v[144:145] op_sel_hi:[1,0]
	v_pk_mul_f32 v[140:141], v[140:141], v[76:77]
	v_pk_mul_f32 v[142:143], v[142:143], v[78:79]
	v_cvt_pk_fp8_f32 v163, v140, v141
	v_cvt_pk_bf16_f32 v140, v140, v141
	v_cvt_pk_fp8_f32 v163, v142, v143 op_sel:[0,0,1]
	v_cvt_pk_bf16_f32 v141, v142, v143
	global_store_dwordx2 v5, v[140:141], s[14:15] offset:3584
	global_store_dword v6, v163, s[18:19] offset:3840
	s_cmp_lt_i32 s3, 0x2000
	s_cbranch_scc1 .Lp0c_row
.Lp0c_done:
.LBB0_33:
	s_cmp_gt_i32 s81, 1
	s_cselect_b64 s[10:11], -1, 0
	s_and_b64 s[6:7], s[6:7], s[10:11]
	s_andn2_b64 vcc, exec, s[6:7]
	s_cbranch_vccnz .LBB0_87
	s_waitcnt vmcnt(0)
	s_barrier
	s_and_saveexec_b64 s[6:7], s[52:53]
	s_cbranch_execz .LBB0_86
	s_add_i32 s3, 0, 0x22020
	v_mov_b32_e32 v0, s3
	s_waitcnt vmcnt(0) expcnt(0) lgkmcnt(0)
	ds_read_b32 v2, v0
	s_add_i32 s3, 0, 0x22024
	v_mov_b32_e32 v0, s3
	ds_read_b32 v0, v0
	s_waitcnt lgkmcnt(1)
	v_cmp_ne_u32_e32 vcc, 0, v2
	s_cbranch_vccnz .LBB0_50
	s_add_u32 s12, s70, 0x1200
	s_addc_u32 s13, s71, 0
	s_add_u32 s14, s70, 0x1400
	s_addc_u32 s15, s71, 0
	s_add_u32 s16, s70, 0x1500
	s_addc_u32 s17, s71, 0
	s_add_u32 s18, s70, 0x1600
	s_addc_u32 s19, s71, 0
	s_add_u32 s20, s70, 0x1700
	s_addc_u32 s21, s71, 0
	s_add_u32 s22, s70, 0x1800
	s_addc_u32 s23, s71, 0
	s_add_u32 s24, s70, 0x1900
	s_addc_u32 s25, s71, 0
	s_add_u32 s26, s70, 0x1a00
	s_addc_u32 s27, s71, 0
	s_add_u32 s28, s70, 0x1b00
	s_addc_u32 s29, s71, 0
	s_add_u32 s30, s70, 0x1c00
	s_addc_u32 s31, s71, 0
	s_add_u32 s34, s70, 0x1d00
	s_addc_u32 s35, s71, 0
	s_add_u32 s36, s70, 0x1e00
	s_addc_u32 s37, s71, 0
	s_add_u32 s38, s70, 0x1f00
	s_addc_u32 s39, s71, 0
	s_add_u32 s40, s70, 0x2000
	s_addc_u32 s41, s71, 0
	s_add_u32 s42, s70, 0x2100
	s_addc_u32 s43, s71, 0
	s_add_u32 s44, s70, 0x2200
	v_readlane_b32 s3, v239, 0
	s_addc_u32 s45, s71, 0
	s_mul_i32 s3, s83, s3
	s_add_u32 s46, s70, 0x2300
	s_mul_i32 s3, s3, s82
	s_addc_u32 s47, s71, 0
	s_mov_b32 s33, 1
	v_mov_b32_e32 v16, 0
	s_branch .LBB0_38

.LBB0_192:
	s_cmp_lt_i32 s80, 3
	s_cselect_b64 s[4:5], -1, 0
	s_add_u32 s94, s70, 0xc100000
	s_addc_u32 s95, s71, 0
	s_add_u32 s6, s70, 0xd100000
	v_writelane_b32 v239, s84, 19
	s_addc_u32 s7, s71, 0
	v_writelane_b32 v239, s6, 20
	s_nop 1
	v_writelane_b32 v239, s7, 21
	s_add_u32 s6, s70, 0xe100000
	s_addc_u32 s7, s71, 0
	v_writelane_b32 v239, s6, 22
	s_add_u32 s98, s70, 0x2e100000
	s_addc_u32 s99, s71, 0
	v_writelane_b32 v239, s7, 23
	s_and_b64 s[0:1], s[4:5], s[0:1]
	v_writelane_b32 v239, s0, 24
	s_andn2_b64 vcc, exec, s[0:1]
	s_nop 0
	v_writelane_b32 v239, s1, 25
	s_cbranch_vccnz .LBB0_262
	v_writelane_b32 v239, s80, 26
	v_lshlrev_b32_e32 v0, 2, v182
	v_mbcnt_lo_u32_b32 v1, -1, 0
	v_writelane_b32 v239, s81, 27
	v_writelane_b32 v239, s82, 28
	v_writelane_b32 v239, s83, 29
	v_mov_b32_e32 v75, 0
	v_readlane_b32 s4, v239, 3
	v_readlane_b32 s8, v239, 7
	v_readlane_b32 s9, v239, 8
	v_readlane_b32 s10, v239, 9
	v_readlane_b32 s11, v239, 10
	v_readlane_b32 s12, v239, 11
	v_readlane_b32 s13, v239, 12
	v_readlane_b32 s14, v239, 13
	v_readlane_b32 s15, v239, 14
	v_readlane_b32 s16, v239, 15
	v_readlane_b32 s17, v239, 16
	v_readlane_b32 s18, v239, 17
	v_readlane_b32 s19, v239, 18
	s_mov_b64 s[8:9], s[12:13]
	v_and_b32_e32 v24, 0x7f, v183
	v_lshlrev_b32_e32 v24, 2, v24
	global_load_dword v25, v24, s[8:9]
	s_mov_b64 s[10:11], s[14:15]
	s_mov_b64 s[12:13], s[16:17]
	s_mov_b64 s[14:15], s[18:19]
	global_load_dword v4, v0, s[10:11]
	global_load_dword v5, v0, s[10:11] offset:256
	global_load_dword v6, v0, s[12:13] offset:256
	global_load_dword v7, v0, s[56:57]
	global_load_dword v8, v0, s[56:57] offset:256
	global_load_dword v9, v0, s[14:15] offset:256
	global_load_dword v10, v0, s[12:13]
	global_load_dword v11, v0, s[14:15]
	s_add_i32 s4, 0, 0x1bc00
	v_and_b32_e32 v12, 48, v183
	s_add_i32 s10, 0, 0x11000
	v_mbcnt_hi_u32_b32 v14, -1, v1
	v_and_b32_e32 v74, 48, v182
	v_lshrrev_b32_e32 v13, 1, v183
	v_add_u32_e32 v139, 0, v12
	v_add_u32_e32 v140, s10, v12
	v_add_u32_e32 v141, s4, v12
	v_mov_b32_e32 v1, v75
	v_and_b32_e32 v12, 64, v14
	v_add_u32_e32 v137, 0, v0
	v_lshl_add_u64 v[76:77], s[8:9], 0, v[74:75]
	v_and_b32_e32 v74, 24, v13
	v_xor_b32_e32 v13, 1, v14
	v_lshl_add_u64 v[78:79], s[70:71], 0, v[0:1]
	v_add_u32_e32 v0, 64, v12
	v_cmp_lt_i32_e32 vcc, v13, v0
	v_xor_b32_e32 v15, 2, v14
	v_xor_b32_e32 v16, 4, v14
	v_cndmask_b32_e32 v12, v14, v13, vcc
	v_lshlrev_b32_e32 v12, 2, v12
	v_cmp_lt_i32_e32 vcc, v15, v0
	v_xor_b32_e32 v17, 8, v14
	v_xor_b32_e32 v18, 16, v14
	v_xor_b32_e32 v19, 32, v14
	v_lshrrev_b32_e32 v2, 4, v182
	v_and_b32_e32 v169, 15, v183
	v_lshlrev_b32_e32 v3, 3, v182
	s_add_i32 s3, 0, 0x1be00
	v_readlane_b32 s5, v239, 4
	v_readlane_b32 s6, v239, 5
	v_readlane_b32 s7, v239, 6
	v_bfe_u32 v73, v183, 2, 2
	v_add_u32_e32 v136, s3, v3
	v_add_u32_e32 v138, s4, v3
	v_lshlrev_b32_e32 v3, 2, v2
	v_lshlrev_b32_e32 v2, 3, v2
	v_mul_u32_u24_e32 v133, 0x110, v169
	s_mov_b64 s[12:13], 0x2c100020
	v_cmp_gt_u32_e64 s[4:5], v3, v169
	v_cmp_lt_u32_e64 s[6:7], v3, v169
	v_or_b32_e32 v20, 2, v3
	v_or_b32_e32 v21, 3, v3
	v_or_b32_e32 v22, v3, v73
	v_or_b32_e32 v23, v2, v73
	v_add3_u32 v143, s10, v2, v133
	v_lshl_add_u64 v[2:3], s[70:71], 0, v[74:75]
	v_lshlrev_b32_e32 v170, 3, v183
	v_lshl_add_u64 v[80:81], v[2:3], 0, s[12:13]
	s_mov_b64 s[12:13], 0x14103020
	s_movk_i32 s90, 0x110
	v_lshlrev_b32_e32 v134, 4, v183
	s_mov_b64 s[14:15], 0x2c100000
	v_and_b32_e32 v132, 24, v170
	v_mul_u32_u24_e32 v1, 0x110, v23
	v_lshl_add_u64 v[84:85], v[2:3], 0, s[12:13]
	s_mov_b64 s[12:13], 0x14103000
	s_mov_b32 s57, 0
	v_lshlrev_b32_e32 v72, 1, v182
	v_cmp_gt_u32_e64 s[0:1], 16, v182
	v_add_u32_e32 v135, 0xfffffe00, v183
	v_add_u32_e32 v142, s10, v134
	v_writelane_b32 v239, s10, 30
	v_cmp_gt_u32_e64 s[8:9], v20, v169
	v_cmp_gt_u32_e64 s[10:11], v21, v169
	v_mad_u32_u24 v144, v22, s90, 0
	v_add3_u32 v146, 0, v132, v1
	v_lshl_add_u64 v[82:83], v[2:3], 0, s[14:15]
	v_mul_u32_u24_e32 v150, 0x6000, v169
	v_lshl_add_u64 v[86:87], v[2:3], 0, s[12:13]
	s_add_i32 s33, 0, 0x22000
	s_add_i32 s3, 0, 0x1ce00
	s_mov_b32 s91, 0xbfb8aa3b
	s_waitcnt vmcnt(0)
	v_add_u32_e32 v24, 0x1d000, v24
	ds_write_b32 v24, v25
	v_mul_f32_e32 v5, v5, v6
	v_mov_b32_e32 v151, 0x358637bd
	s_mov_b64 s[80:81], 0x40000
	v_mul_f32_e32 v6, v9, v8
	v_fmac_f32_e32 v5, v4, v10
	v_fmac_f32_e32 v6, v11, v7
	ds_bpermute_b32 v4, v12, v5
	ds_bpermute_b32 v7, v12, v6
	v_cndmask_b32_e32 v8, v14, v15, vcc
	v_lshlrev_b32_e32 v8, 2, v8
	v_cmp_lt_i32_e32 vcc, v16, v0
	s_waitcnt lgkmcnt(1)
	v_add_f32_e32 v4, v5, v4
	s_waitcnt lgkmcnt(0)
	v_add_f32_e32 v5, v6, v7
	ds_bpermute_b32 v6, v8, v4
	ds_bpermute_b32 v7, v8, v5
	v_cndmask_b32_e32 v8, v14, v16, vcc
	v_lshlrev_b32_e32 v8, 2, v8
	v_cmp_lt_i32_e32 vcc, v17, v0
	s_waitcnt lgkmcnt(1)
	v_add_f32_e32 v4, v4, v6
	s_waitcnt lgkmcnt(0)
	v_add_f32_e32 v5, v5, v7
	ds_bpermute_b32 v6, v8, v4
	ds_bpermute_b32 v7, v8, v5
	v_cndmask_b32_e32 v8, v14, v17, vcc
	v_lshlrev_b32_e32 v8, 2, v8
	v_cmp_lt_i32_e32 vcc, v18, v0
	s_waitcnt lgkmcnt(1)
	v_add_f32_e32 v4, v4, v6
	s_waitcnt lgkmcnt(0)
	v_add_f32_e32 v5, v5, v7
	ds_bpermute_b32 v6, v8, v4
	ds_bpermute_b32 v7, v8, v5
	v_cndmask_b32_e32 v8, v14, v18, vcc
	v_lshlrev_b32_e32 v8, 2, v8
	v_cmp_lt_i32_e32 vcc, v19, v0
	s_waitcnt lgkmcnt(1)
	v_add_f32_e32 v4, v4, v6
	s_waitcnt lgkmcnt(0)
	v_add_f32_e32 v5, v5, v7
	ds_bpermute_b32 v6, v8, v4
	ds_bpermute_b32 v7, v8, v5
	v_cndmask_b32_e32 v0, v14, v19, vcc
	v_lshlrev_b32_e32 v0, 2, v0
	s_mov_b64 s[82:83], 0x300000
	s_waitcnt lgkmcnt(1)
	v_add_f32_e32 v147, v4, v6
	s_waitcnt lgkmcnt(0)
	v_add_f32_e32 v145, v5, v7
	ds_bpermute_b32 v149, v0, v147
	ds_bpermute_b32 v148, v0, v145
	v_mov_b32_e32 v0, v75
	v_mov_b32_e32 v1, v75
	v_mov_b32_e32 v2, v75
	v_mov_b32_e32 v3, v75
	s_branch .LBB0_196

.LBB0_202:
	v_add_u32_e32 v9, 0x200, v9
	s_movk_i32 s16, 0x67f
	v_cmp_lt_u32_e32 vcc, s16, v9
	ds_write_b128 v8, v[0:3]
	s_or_b64 s[12:13], vcc, s[12:13]
	v_add_u32_e32 v8, 0x2000, v8
	s_andn2_b64 exec, exec, s[12:13]
	s_cbranch_execnz .LBB0_202
	s_or_b64 exec, exec, s[12:13]
	s_waitcnt vmcnt(0)
	v_sub_f32_e32 v4, v6, v4
	v_sub_f32_e32 v5, v7, v5
	v_mul_f32_e32 v4, 0x3fb8aa3b, v4
	v_mul_f32_e32 v5, 0x3fb8aa3b, v5
	v_exp_f32_e32 v4, v4
	v_exp_f32_e32 v5, v5
	s_and_b32 s29, s15, 0xfffff800
	v_readfirstlane_b32 s36, v183
	s_ashr_i32 s30, s29, 31
	v_pk_add_f32 v[4:5], v[4:5], 1.0 op_sel_hi:[1,0]
	s_mul_i32 s34, s29, 0xc000
	v_div_scale_f32 v6, s[12:13], v5, v5, 1.0
	v_rcp_f32_e32 v7, v6
	s_lshr_b32 s35, s36, 6
	s_mul_hi_i32 s31, s29, 0xc000
	s_mul_i32 s37, s35, 0x60000
	v_fma_f32 v8, -v6, v7, 1.0
	v_fmac_f32_e32 v7, v8, v7
	v_div_scale_f32 v8, vcc, 1.0, v5, 1.0
	v_mul_f32_e32 v9, v8, v7
	v_fma_f32 v10, -v6, v9, v8
	v_fmac_f32_e32 v9, v10, v7
	v_fma_f32 v6, -v6, v9, v8
	v_div_scale_f32 v8, s[12:13], v4, v4, 1.0
	v_rcp_f32_e32 v10, v8
	v_div_fmas_f32 v6, v6, v7, v9
	v_div_fixup_f32 v89, v6, v5, 1.0
	s_add_u32 s12, s74, s34
	v_fma_f32 v5, -v8, v10, 1.0
	v_fmac_f32_e32 v10, v5, v10
	v_div_scale_f32 v5, vcc, 1.0, v4, 1.0
	v_mul_f32_e32 v6, v5, v10
	s_addc_u32 s13, s75, s31
	s_lshl_b32 s15, s35, 3
	v_fma_f32 v7, -v8, v6, v5
	s_mul_hi_u32 s15, s15, 0xc000
	s_add_u32 s12, s12, s37
	v_fmac_f32_e32 v6, v7, v10
	s_addc_u32 s13, s13, s15
	s_lshl_b32 s14, s14, 1
	v_fma_f32 v5, -v8, v6, v5
	s_add_u32 s12, s12, s14
	v_div_fmas_f32 v5, v5, v10, v6
	s_addc_u32 s13, s13, 0
	v_lshlrev_b32_e32 v74, 1, v72
	v_div_fixup_f32 v88, v5, v4, 1.0
	v_lshl_add_u64 v[4:5], s[12:13], 0, v[74:75]
	s_movk_i32 s14, 0x2000
	v_add_co_u32_e32 v6, vcc, s14, v4
	s_mov_b32 s14, 0xe000
	s_nop 0
	v_addc_co_u32_e32 v7, vcc, 0, v5, vcc
	v_add_co_u32_e32 v8, vcc, s14, v4
	s_mov_b32 s14, 0xc000
	s_nop 0
	v_addc_co_u32_e32 v9, vcc, 0, v5, vcc
	v_add_co_u32_e32 v10, vcc, s14, v4
	s_mov_b32 s14, 0x1a000
	s_nop 0
	v_addc_co_u32_e32 v11, vcc, 0, v5, vcc
	v_add_co_u32_e32 v12, vcc, s14, v4
	s_mov_b32 s14, 0x18000
	s_nop 0
	v_addc_co_u32_e32 v13, vcc, 0, v5, vcc
	v_add_co_u32_e32 v14, vcc, s14, v4
	s_mov_b32 s14, 0x26000
	s_nop 0
	v_addc_co_u32_e32 v15, vcc, 0, v5, vcc
	v_add_co_u32_e32 v16, vcc, s14, v4
	s_mov_b32 s14, 0x24000
	s_nop 0
	v_addc_co_u32_e32 v17, vcc, 0, v5, vcc
	v_add_co_u32_e32 v18, vcc, s14, v4
	s_mov_b32 s14, 0x32000
	s_nop 0
	v_addc_co_u32_e32 v19, vcc, 0, v5, vcc
	global_load_dword v152, v[6:7], off offset:-4096 nt
	global_load_dword v153, v[6:7], off nt
	global_load_dword v154, v[8:9], off offset:-4096 nt
	global_load_dword v155, v[8:9], off nt
	global_load_dword v156, v[12:13], off offset:-4096 nt
	global_load_dword v161, v[12:13], off nt
	global_load_dword v162, v[16:17], off offset:-4096 nt
	global_load_dword v163, v[16:17], off nt
	v_add_co_u32_e32 v6, vcc, s14, v4
	s_mov_b32 s14, 0x30000
	s_nop 0
	v_addc_co_u32_e32 v7, vcc, 0, v5, vcc
	v_add_co_u32_e32 v8, vcc, s14, v4
	s_mov_b32 s14, 0x3e000
	s_nop 0
	v_addc_co_u32_e32 v9, vcc, 0, v5, vcc
	v_add_co_u32_e32 v12, vcc, s14, v4
	s_mov_b32 s14, 0x3c000
	s_nop 0
	v_addc_co_u32_e32 v13, vcc, 0, v5, vcc
	v_add_co_u32_e32 v16, vcc, s14, v4
	s_mov_b32 s14, 0x4a000
	s_nop 0
	v_addc_co_u32_e32 v17, vcc, 0, v5, vcc
	v_add_co_u32_e32 v20, vcc, s14, v4
	s_mov_b32 s14, 0x48000
	s_nop 0
	v_addc_co_u32_e32 v21, vcc, 0, v5, vcc
	v_add_co_u32_e32 v22, vcc, s14, v4
	s_mov_b32 s14, 0x56000
	s_nop 0
	v_addc_co_u32_e32 v23, vcc, 0, v5, vcc
	v_add_co_u32_e32 v24, vcc, s14, v4
	s_mov_b32 s14, 0x54000
	s_nop 0
	v_addc_co_u32_e32 v25, vcc, 0, v5, vcc
	v_add_co_u32_e32 v4, vcc, s14, v4
	s_bfe_u32 s40, s36, 0x20006
	s_nop 0
	v_addc_co_u32_e32 v5, vcc, 0, v5, vcc
	global_load_dword v157, v74, s[12:13] nt
	global_load_dword v160, v[10:11], off nt
	global_load_dword v164, v[14:15], off nt
	global_load_dword v165, v[18:19], off nt
	global_load_dword v180, v[8:9], off nt
	global_load_dword v184, v[16:17], off nt
	global_load_dword v188, v[22:23], off nt
	global_load_dword v191, v[4:5], off nt
	global_load_dword v179, v[6:7], off offset:-4096 nt
	global_load_dword v181, v[6:7], off nt
	global_load_dword v185, v[12:13], off offset:-4096 nt
	global_load_dword v186, v[12:13], off nt
	global_load_dword v187, v[20:21], off offset:-4096 nt
	global_load_dword v189, v[20:21], off nt
	global_load_dword v190, v[24:25], off offset:-4096 nt
	global_load_dword v192, v[24:25], off nt
	s_and_b32 s39, s35, 0x3fffffc
	s_lshl_b32 s76, s35, 9
	s_cmp_lt_u32 s36, 64
	s_cselect_b64 s[84:85], -1, 0
	s_and_b32 s12, s36, 0xffffff00
	s_add_i32 s12, s3, s12
	s_lshl_b32 s13, s40, 6
	s_add_i32 s12, s12, s13
	s_lshl_b32 s77, s35, 5
	s_and_b32 s41, s36, 0xffffffc0
	s_lshl_b32 s56, s39, 6
	s_cmpk_gt_u32 s36, 0x7f
	v_lshl_add_u32 v158, v169, 2, s12
	s_cselect_b64 s[12:13], -1, 0
	s_cmpk_gt_u32 s36, 0xbf
	s_cselect_b64 s[14:15], -1, 0
	s_cmpk_gt_u32 s36, 0xff
	s_cselect_b64 s[16:17], -1, 0
	s_cmpk_gt_u32 s36, 0x13f
	s_cselect_b64 s[18:19], -1, 0
	s_cmpk_gt_u32 s36, 0x17f
	s_cselect_b64 s[20:21], -1, 0
	s_cmpk_gt_u32 s36, 0x1bf
	s_cselect_b64 s[22:23], -1, 0
	s_cmpk_gt_u32 s36, 0x1ff
	s_cselect_b64 s[24:25], -1, 0
	s_or_b32 s43, s39, 1
	s_or_b32 s44, s39, 2
	s_or_b32 s45, s35, 3
	s_cmp_eq_u32 s40, 0
	s_cselect_b64 s[26:27], -1, 0
	s_cmp_lg_u32 s40, 0
	s_cselect_b64 s[86:87], -1, 0
	s_cmp_eq_u32 s40, 1
	s_cselect_b64 s[54:55], -1, 0
	s_cmp_gt_u32 s40, 1
	s_cselect_b64 s[72:73], -1, 0
	s_cmp_eq_u32 s40, 2
	s_cselect_b64 s[78:79], -1, 0
	s_cmp_eq_u32 s40, 3
	v_lshl_or_b32 v5, s39, 4, v169
	v_and_b32_e32 v92, 48, v182
	v_add_u32_e32 v92, s56, v92
	v_add_u32_e32 v92, 0x1d000, v92
	s_cselect_b64 s[88:89], -1, 0
	v_mul_lo_u32 v13, v5, s90
	v_lshl_or_b32 v5, s43, 4, v169
	s_lshl_b32 s56, s43, 6
	v_mul_lo_u32 v14, v5, s90
	v_lshl_or_b32 v5, s44, 4, v169
	s_lshl_b32 s56, s44, 6
	v_lshl_or_b32 v4, s40, 4, v169
	v_mul_lo_u32 v15, v5, s90
	v_lshl_or_b32 v5, s45, 4, v169
	s_lshl_b32 s56, s45, 6
	s_and_b32 s28, s28, 15
	v_mul_u32_u24_e32 v8, 0x110, v4
	v_lshl_add_u32 v159, v4, 2, s3
	v_mul_lo_u32 v16, v5, s90
	s_lshl_b32 s56, s28, 8
	v_or_b32_e32 v4, s29, v4
	v_mov_b32_e32 v5, s30
	s_lshr_b32 s28, s36, 1
	s_lshl_b32 s38, s45, 5
	v_lshlrev_b64 v[4:5], 12, v[4:5]
	s_and_b32 s28, s28, 0x7fffff80
	s_mov_b32 s29, s57
	v_lshl_add_u64 v[6:7], v[4:5], 0, s[28:29]
	s_mul_hi_u32 s29, s35, 0x60000
	s_add_u32 s36, s37, s34
	s_addc_u32 s37, s29, s31
	v_lshl_or_b32 v9, s39, 5, v132
	s_mov_b32 s39, s57
	s_add_u32 s28, s34, s28
	s_mul_i32 s40, s40, 0x60000
	v_lshl_add_u64 v[4:5], v[4:5], 0, s[38:39]
	s_addc_u32 s29, s31, 0
	v_add_lshl_u32 v74, v150, s40, 1
	v_lshl_add_u64 v[104:105], v[82:83], 0, v[4:5]
	v_lshl_add_u64 v[4:5], s[28:29], 0, v[74:75]
	s_add_u32 s28, s34, s38
	s_addc_u32 s29, s31, 0
	s_mul_i32 s42, s35, 0x880
	v_lshl_or_b32 v10, s43, 5, v132
	v_lshl_or_b32 v11, s44, 5, v132
	v_or_b32_e32 v12, s38, v132
	v_lshl_add_u64 v[106:107], v[84:85], 0, v[4:5]
	v_lshl_add_u64 v[4:5], s[28:29], 0, v[74:75]
	v_mov_b32_e32 v28, 0
	v_pk_add_f32 v[90:91], v[88:89], 1.0 op_sel_hi:[1,0] neg_lo:[1,0] neg_hi:[1,0]
	v_lshl_add_u64 v[100:101], v[80:81], 0, v[6:7]
	v_lshl_add_u64 v[102:103], v[78:79], 0, s[36:37]
	v_lshl_add_u64 v[108:109], v[86:87], 0, v[4:5]
	s_mov_b32 s96, 32
	v_add_u32_e32 v74, s42, v137
	v_add_u32_e32 v166, v139, v8
	v_add_u32_e32 v167, v140, v13
	v_add_u32_e32 v168, v140, v14
	v_add_u32_e32 v171, v140, v15
	v_add_u32_e32 v172, v140, v16
	v_add_u32_e32 v173, s41, v141
	v_add_u32_e32 v174, s77, v143
	v_add_u32_e32 v175, v144, v9
	v_add_u32_e32 v176, v144, v10
	v_add_u32_e32 v177, v144, v11
	v_add_u32_e32 v178, v144, v12
	v_mov_b32_e32 v29, v28
	v_mov_b32_e32 v30, v28
	v_mov_b32_e32 v31, v28
	v_mov_b32_e32 v32, v28
	v_mov_b32_e32 v33, v28
	v_mov_b32_e32 v34, v28
	v_mov_b32_e32 v35, v28
	v_mov_b32_e32 v24, v28
	v_mov_b32_e32 v25, v28
	v_mov_b32_e32 v26, v28
	v_mov_b32_e32 v27, v28
	v_mov_b32_e32 v20, v28
	v_mov_b32_e32 v21, v28
	v_mov_b32_e32 v22, v28
	v_mov_b32_e32 v23, v28
	v_mov_b32_e32 v16, v28
	v_mov_b32_e32 v17, v28
	v_mov_b32_e32 v18, v28
	v_mov_b32_e32 v19, v28
	v_mov_b32_e32 v12, v28
	v_mov_b32_e32 v13, v28
	v_mov_b32_e32 v14, v28
	v_mov_b32_e32 v15, v28
	v_mov_b32_e32 v8, v28
	v_mov_b32_e32 v9, v28
	v_mov_b32_e32 v10, v28
	v_mov_b32_e32 v11, v28
	v_mov_b32_e32 v4, v28
	v_mov_b32_e32 v5, v28
	v_mov_b32_e32 v6, v28
	v_mov_b32_e32 v7, v28
	s_branch .LBB0_205
.LBB0_204:
	s_or_b64 exec, exec, s[28:29]
	v_add_u32_e32 v54, s77, v146
	ds_read_b64_tr_b16 v[56:57], v54 offset:17408
	ds_read_b64_tr_b16 v[58:59], v54 offset:18496
	ds_read_b64_tr_b16 v[52:53], v54 offset:26112
	ds_read_b64_tr_b16 v[54:55], v54 offset:27200
	ds_read_b64_tr_b16 v[62:63], v146 offset:53312
	ds_read_b64_tr_b16 v[60:61], v146 offset:52224
	ds_read_b64_tr_b16 v[64:65], v146 offset:52256
	s_mov_b32 s28, 0x800000
	s_add_i32 s96, s96, -1
	v_lshl_add_u64 v[102:103], v[102:103], 0, s[82:83]
	s_waitcnt lgkmcnt(1)
	v_mfma_f32_16x16x32_bf16 v[28:31], v[56:59], v[60:63], v[28:31]
	ds_read_b64_tr_b16 v[60:61], v146 offset:60928
	ds_read_b64_tr_b16 v[62:63], v146 offset:62016
	ds_read_b64_tr_b16 v[66:67], v146 offset:53344
	v_lshl_add_u64 v[106:107], v[106:107], 0, s[82:83]
	v_lshl_add_u64 v[108:109], v[108:109], 0, s[82:83]
	s_waitcnt lgkmcnt(1)
	v_mfma_f32_16x16x32_bf16 v[28:31], v[52:55], v[60:63], v[28:31]
	ds_read_b64_tr_b16 v[60:61], v146 offset:60960
	ds_read_b64_tr_b16 v[62:63], v146 offset:62048
	s_cmp_eq_u32 s96, 0
	s_waitcnt lgkmcnt(2)
	v_mfma_f32_16x16x32_bf16 v[32:35], v[56:59], v[64:67], v[32:35]
	s_waitcnt lgkmcnt(0)
	v_mfma_f32_16x16x32_bf16 v[32:35], v[52:55], v[60:63], v[32:35]
	ds_read_b64_tr_b16 v[60:61], v146 offset:52288
	ds_read_b64_tr_b16 v[62:63], v146 offset:53376
	s_waitcnt lgkmcnt(0)
	v_mfma_f32_16x16x32_bf16 v[24:27], v[56:59], v[60:63], v[24:27]
	ds_read_b64_tr_b16 v[60:61], v146 offset:60992
	ds_read_b64_tr_b16 v[62:63], v146 offset:62080
	s_waitcnt lgkmcnt(0)
	v_mfma_f32_16x16x32_bf16 v[24:27], v[52:55], v[60:63], v[24:27]
	ds_read_b64_tr_b16 v[60:61], v146 offset:52320
	ds_read_b64_tr_b16 v[62:63], v146 offset:53408
	s_waitcnt lgkmcnt(0)
	v_mfma_f32_16x16x32_bf16 v[20:23], v[56:59], v[60:63], v[20:23]
	ds_read_b64_tr_b16 v[60:61], v146 offset:61024
	ds_read_b64_tr_b16 v[62:63], v146 offset:62112
	s_waitcnt lgkmcnt(0)
	v_mfma_f32_16x16x32_bf16 v[20:23], v[52:55], v[60:63], v[20:23]
	ds_read_b64_tr_b16 v[60:61], v146 offset:52352
	ds_read_b64_tr_b16 v[62:63], v146 offset:53440
	s_waitcnt lgkmcnt(0)
	v_mfma_f32_16x16x32_bf16 v[16:19], v[56:59], v[60:63], v[16:19]
	ds_read_b64_tr_b16 v[60:61], v146 offset:61056
	ds_read_b64_tr_b16 v[62:63], v146 offset:62144
	s_waitcnt lgkmcnt(0)
	v_mfma_f32_16x16x32_bf16 v[16:19], v[52:55], v[60:63], v[16:19]
	ds_read_b64_tr_b16 v[60:61], v146 offset:52384
	ds_read_b64_tr_b16 v[62:63], v146 offset:53472
	s_waitcnt lgkmcnt(0)
	v_mfma_f32_16x16x32_bf16 v[12:15], v[56:59], v[60:63], v[12:15]
	ds_read_b64_tr_b16 v[60:61], v146 offset:61088
	ds_read_b64_tr_b16 v[62:63], v146 offset:62176
	s_waitcnt lgkmcnt(0)
	v_mfma_f32_16x16x32_bf16 v[12:15], v[52:55], v[60:63], v[12:15]
	ds_read_b64_tr_b16 v[60:61], v146 offset:52416
	ds_read_b64_tr_b16 v[62:63], v146 offset:53504
	s_waitcnt lgkmcnt(0)
	v_mfma_f32_16x16x32_bf16 v[8:11], v[56:59], v[60:63], v[8:11]
	ds_read_b64_tr_b16 v[60:61], v146 offset:61120
	ds_read_b64_tr_b16 v[62:63], v146 offset:62208
	s_waitcnt lgkmcnt(0)
	v_mfma_f32_16x16x32_bf16 v[8:11], v[52:55], v[60:63], v[8:11]
	ds_read_b64_tr_b16 v[60:61], v146 offset:52448
	ds_read_b64_tr_b16 v[62:63], v146 offset:53536
	s_waitcnt lgkmcnt(0)
	v_mfma_f32_16x16x32_bf16 v[4:7], v[56:59], v[60:63], v[4:7]
	ds_read_b64_tr_b16 v[56:57], v146 offset:61152
	ds_read_b64_tr_b16 v[58:59], v146 offset:62240
	s_waitcnt lgkmcnt(0)
	v_mfma_f32_16x16x32_bf16 v[4:7], v[52:55], v[56:59], v[4:7]
	ds_read_b128 v[52:55], v173
	s_waitcnt lgkmcnt(0)
	s_barrier
	s_waitcnt vmcnt(0)
	v_lshlrev_b32_e32 v58, 16, v116
	s_waitcnt lgkmcnt(0)
	v_pk_mul_f32 v[28:29], v[52:53], v[28:29]
	v_pk_mul_f32 v[30:31], v[54:55], v[30:31]
	v_pk_mul_f32 v[32:33], v[52:53], v[32:33]
	v_pk_mul_f32 v[24:25], v[52:53], v[24:25]
	v_pk_mul_f32 v[20:21], v[52:53], v[20:21]
	v_pk_mul_f32 v[16:17], v[52:53], v[16:17]
	v_pk_mul_f32 v[12:13], v[52:53], v[12:13]
	v_pk_mul_f32 v[8:9], v[52:53], v[8:9]
	v_pk_mul_f32 v[4:5], v[52:53], v[4:5]
	v_pk_mul_f32 v[34:35], v[54:55], v[34:35]
	v_cvt_pk_bf16_f32 v52, v28, v29
	v_cvt_pk_bf16_f32 v53, v30, v31
	v_pk_mul_f32 v[26:27], v[54:55], v[26:27]
	ds_write_b64 v174, v[52:53]
	v_cvt_pk_bf16_f32 v52, v32, v33
	v_cvt_pk_bf16_f32 v53, v34, v35
	v_pk_mul_f32 v[22:23], v[54:55], v[22:23]
	ds_write_b64 v174, v[52:53] offset:4352
	v_cvt_pk_bf16_f32 v52, v24, v25
	v_cvt_pk_bf16_f32 v53, v26, v27
	v_pk_mul_f32 v[18:19], v[54:55], v[18:19]
	ds_write_b64 v174, v[52:53] offset:8704
	v_cvt_pk_bf16_f32 v52, v20, v21
	v_cvt_pk_bf16_f32 v53, v22, v23
	v_pk_mul_f32 v[14:15], v[54:55], v[14:15]
	ds_write_b64 v174, v[52:53] offset:13056
	v_cvt_pk_bf16_f32 v52, v16, v17
	v_cvt_pk_bf16_f32 v53, v18, v19
	v_pk_mul_f32 v[10:11], v[54:55], v[10:11]
	ds_write_b64 v174, v[52:53] offset:17408
	v_cvt_pk_bf16_f32 v52, v12, v13
	v_cvt_pk_bf16_f32 v53, v14, v15
	v_pk_mul_f32 v[6:7], v[54:55], v[6:7]
	ds_write_b64 v174, v[52:53] offset:21760
	v_cvt_pk_bf16_f32 v52, v8, v9
	v_cvt_pk_bf16_f32 v53, v10, v11
	ds_write_b64 v174, v[52:53] offset:26112
	v_cvt_pk_bf16_f32 v52, v4, v5
	v_cvt_pk_bf16_f32 v53, v6, v7
	ds_write_b64 v174, v[52:53] offset:30464
	ds_read2st64_b32 v[52:53], v159 offset1:1
	v_mul_f32_e32 v57, 0xbfb8aa3b, v58
	v_exp_f32_e32 v57, v57
	v_and_b32_e32 v59, 0xffff0000, v116
	s_waitcnt lgkmcnt(0)
	v_add_f32_e32 v52, v52, v53
	v_fmamk_f32 v52, v52, 0x3c000000, v151
	v_cmp_gt_f32_e32 vcc, s28, v52
	v_mul_f32_e32 v53, 0x4b800000, v52
	v_add_f32_e32 v57, 1.0, v57
	v_cndmask_b32_e32 v52, v52, v53, vcc
	v_rsq_f32_e32 v52, v52
	v_rcp_f32_e32 v60, v57
	v_mul_f32_e32 v53, 0x45800000, v52
	v_cndmask_b32_e32 v56, v52, v53, vcc
	ds_read_b128 v[52:55], v92
	v_pk_mul_f32 v[48:49], v[48:49], v[56:57] op_sel_hi:[1,0]
	s_waitcnt lgkmcnt(0)
	v_pk_mul_f32 v[48:49], v[52:53], v[48:49]
	v_mul_f32_e32 v52, 0xbfb8aa3b, v59
	v_exp_f32_e32 v52, v52
	v_and_b32_e32 v53, 0xffff0000, v117
	v_pk_mul_f32 v[48:49], v[48:49], v[58:59]
	v_add_f32_e32 v52, 1.0, v52
	v_rcp_f32_e32 v61, v52
	v_lshlrev_b32_e32 v52, 16, v117
	v_mul_f32_e32 v57, 0xbfb8aa3b, v52
	v_exp_f32_e32 v57, v57
	v_pk_mul_f32 v[48:49], v[60:61], v[48:49]
	v_add_f32_e32 v57, 1.0, v57
	v_pk_mul_f32 v[50:51], v[50:51], v[56:57] op_sel_hi:[1,0]
	v_rcp_f32_e32 v58, v57
	v_pk_mul_f32 v[50:51], v[54:55], v[50:51]
	v_lshlrev_b32_e32 v54, 16, v114
	v_pk_mul_f32 v[50:51], v[50:51], v[52:53]
	v_mul_f32_e32 v52, 0xbfb8aa3b, v53
	v_exp_f32_e32 v52, v52
	v_mul_f32_e32 v57, 0xbfb8aa3b, v54
	v_exp_f32_e32 v57, v57
	v_and_b32_e32 v55, 0xffff0000, v114
	v_add_f32_e32 v52, 1.0, v52
	v_rcp_f32_e32 v59, v52
	v_cvt_pk_bf16_f32 v52, v48, v49
	v_lshl_add_u64 v[48:49], v[100:101], 0, s[56:57]
	v_add_f32_e32 v57, 1.0, v57
	v_pk_mul_f32 v[50:51], v[58:59], v[50:51]
	v_pk_mul_f32 v[44:45], v[44:45], v[56:57] op_sel_hi:[1,0]
	v_cvt_pk_bf16_f32 v53, v50, v51
	global_store_dwordx2 v[48:49], v[52:53], off offset:-32
	ds_read_b128 v[50:53], v92 offset:64
	v_pk_mul_f32 v[46:47], v[46:47], v[56:57] op_sel_hi:[1,0]
	v_rcp_f32_e32 v58, v57
	v_pk_mul_f32 v[40:41], v[40:41], v[56:57] op_sel_hi:[1,0]
	v_pk_mul_f32 v[42:43], v[42:43], v[56:57] op_sel_hi:[1,0]
	v_pk_mul_f32 v[36:37], v[36:37], v[56:57] op_sel_hi:[1,0]
	v_pk_mul_f32 v[38:39], v[38:39], v[56:57] op_sel_hi:[1,0]
	v_lshl_add_u64 v[100:101], v[100:101], 0, s[80:81]
	s_waitcnt lgkmcnt(0)
	v_pk_mul_f32 v[44:45], v[50:51], v[44:45]
	v_mul_f32_e32 v50, 0xbfb8aa3b, v55
	v_exp_f32_e32 v50, v50
	v_and_b32_e32 v51, 0xffff0000, v115
	v_pk_mul_f32 v[46:47], v[52:53], v[46:47]
	v_pk_mul_f32 v[44:45], v[44:45], v[54:55]
	v_add_f32_e32 v50, 1.0, v50
	v_rcp_f32_e32 v59, v50
	v_lshlrev_b32_e32 v50, 16, v115
	v_mul_f32_e32 v54, 0xbfb8aa3b, v50
	v_pk_mul_f32 v[46:47], v[46:47], v[50:51]
	v_mul_f32_e32 v50, 0xbfb8aa3b, v51
	v_exp_f32_e32 v54, v54
	v_exp_f32_e32 v50, v50
	v_pk_mul_f32 v[44:45], v[58:59], v[44:45]
	v_and_b32_e32 v51, 0xffff0000, v112
	v_add_f32_e32 v54, 1.0, v54
	v_add_f32_e32 v50, 1.0, v50
	v_rcp_f32_e32 v54, v54
	v_rcp_f32_e32 v55, v50
	v_cvt_pk_bf16_f32 v44, v44, v45
	v_lshlrev_b32_e32 v50, 16, v112
	v_mul_f32_e32 v52, 0xbfb8aa3b, v50
	v_pk_mul_f32 v[46:47], v[54:55], v[46:47]
	v_exp_f32_e32 v52, v52
	v_cvt_pk_bf16_f32 v45, v46, v47
	global_store_dwordx2 v[48:49], v[44:45], off
	ds_read_b128 v[44:47], v92 offset:128
	v_add_f32_e32 v52, 1.0, v52
	v_rcp_f32_e32 v52, v52
	s_waitcnt lgkmcnt(0)
	v_pk_mul_f32 v[40:41], v[44:45], v[40:41]
	v_mul_f32_e32 v44, 0xbfb8aa3b, v51
	v_exp_f32_e32 v44, v44
	v_and_b32_e32 v45, 0xffff0000, v113
	v_pk_mul_f32 v[42:43], v[46:47], v[42:43]
	v_pk_mul_f32 v[40:41], v[40:41], v[50:51]
	v_add_f32_e32 v44, 1.0, v44
	v_rcp_f32_e32 v53, v44
	v_lshlrev_b32_e32 v44, 16, v113
	v_mul_f32_e32 v50, 0xbfb8aa3b, v44
	v_pk_mul_f32 v[42:43], v[42:43], v[44:45]
	v_mul_f32_e32 v44, 0xbfb8aa3b, v45
	v_exp_f32_e32 v50, v50
	v_exp_f32_e32 v44, v44
	v_pk_mul_f32 v[40:41], v[52:53], v[40:41]
	v_and_b32_e32 v45, 0xffff0000, v110
	v_add_f32_e32 v50, 1.0, v50
	v_add_f32_e32 v44, 1.0, v44
	v_rcp_f32_e32 v50, v50
	v_rcp_f32_e32 v51, v44
	v_cvt_pk_bf16_f32 v40, v40, v41
	v_lshlrev_b32_e32 v44, 16, v110
	v_mul_f32_e32 v46, 0xbfb8aa3b, v44
	v_pk_mul_f32 v[42:43], v[50:51], v[42:43]
	v_exp_f32_e32 v46, v46
	v_cvt_pk_bf16_f32 v41, v42, v43
	global_store_dwordx2 v[48:49], v[40:41], off offset:32
	ds_read_b128 v[40:43], v92 offset:192
	v_add_f32_e32 v46, 1.0, v46
	v_rcp_f32_e32 v46, v46
	s_waitcnt lgkmcnt(0)
	v_pk_mul_f32 v[36:37], v[40:41], v[36:37]
	v_mul_f32_e32 v40, 0xbfb8aa3b, v45
	v_exp_f32_e32 v40, v40
	v_and_b32_e32 v41, 0xffff0000, v111
	v_pk_mul_f32 v[38:39], v[42:43], v[38:39]
	v_pk_mul_f32 v[36:37], v[36:37], v[44:45]
	v_add_f32_e32 v40, 1.0, v40
	v_rcp_f32_e32 v47, v40
	v_lshlrev_b32_e32 v40, 16, v111
	v_mul_f32_e32 v44, 0xbfb8aa3b, v40
	v_pk_mul_f32 v[38:39], v[38:39], v[40:41]
	v_mul_f32_e32 v40, 0xbfb8aa3b, v41
	v_exp_f32_e32 v44, v44
	v_exp_f32_e32 v40, v40
	v_pk_mul_f32 v[36:37], v[46:47], v[36:37]
	v_add_f32_e32 v44, 1.0, v44
	v_add_f32_e32 v40, 1.0, v40
	v_rcp_f32_e32 v44, v44
	v_rcp_f32_e32 v45, v40
	v_cvt_pk_bf16_f32 v36, v36, v37
	v_pk_mul_f32 v[38:39], v[44:45], v[38:39]
	s_nop 0
	v_cvt_pk_bf16_f32 v37, v38, v39
	v_lshl_add_u64 v[38:39], v[104:105], 0, s[56:57]
	v_lshl_add_u64 v[104:105], v[104:105], 0, s[80:81]
	global_store_dwordx2 v[38:39], v[36:37], off
	s_cbranch_scc1 .LBB0_194

.LBB0_340:
	s_mul_i32 s86, s26, 0xc00000
	s_lshl_b32 s87, s28, 9
	s_add_u32 s86, s86, s87
	s_add_u32 s76, s74, s86
	s_addc_u32 s77, s75, 0
	s_add_u32 s78, s76, 0x8000
	s_addc_u32 s79, s77, 0
	s_add_u32 s76, s76, 0xa000
	s_addc_u32 s77, s77, 0
	s_lshl_b32 s86, s26, 21
	s_add_u32 s86, s86, s87
	s_add_u32 s72, s4, s86
	s_addc_u32 s73, s5, 0
	v_mul_u32_u24_e32 v142, 0xc000, v162
	v_lshl_add_u32 v142, v164, 1, v142
	v_lshlrev_b32_e32 v143, 13, v162
	v_lshl_add_u32 v143, v164, 1, v143
	s_cmp_eq_u32 s33, 0
	s_cselect_b64 s[0:1], -1, 0
	s_cbranch_scc0 .Lp3e_half1
	global_load_dwordx4 v[166:169], v142, s[76:77]
	global_load_dwordx4 v[170:173], v142, s[78:79]
	global_load_dwordx4 v[174:177], v142, s[76:77] offset:256
	global_load_dwordx4 v[178:181], v142, s[78:79] offset:256
	v_add_u32_e32 v145, 0xc0000, v142
	global_load_dwordx4 v[184:187], v145, s[76:77]
	global_load_dwordx4 v[188:191], v145, s[78:79]
	global_load_dwordx4 v[192:195], v145, s[76:77] offset:256
	global_load_dwordx4 v[196:199], v145, s[78:79] offset:256
	v_add_u32_e32 v144, 0x180000, v142
	global_load_dwordx4 v[200:203], v144, s[76:77]
	global_load_dwordx4 v[204:207], v144, s[78:79]
	global_load_dwordx4 v[208:211], v144, s[76:77] offset:256
	global_load_dwordx4 v[212:215], v144, s[78:79] offset:256
	v_add_u32_e32 v145, 0x240000, v142
	global_load_dwordx4 v[216:219], v145, s[76:77]
	global_load_dwordx4 v[220:223], v145, s[78:79]
	global_load_dwordx4 v[224:227], v145, s[76:77] offset:256
	global_load_dwordx4 v[228:231], v145, s[78:79] offset:256
	s_waitcnt vmcnt(14)
	v_lshlrev_b32_e32 v146, 16, v166
	v_and_b32_e32 v147, 0xffff0000, v166
	v_lshlrev_b32_e32 v148, 16, v167
	v_and_b32_e32 v149, 0xffff0000, v167
	v_lshlrev_b32_e32 v150, 16, v168
	v_and_b32_e32 v151, 0xffff0000, v168
	v_lshlrev_b32_e32 v152, 16, v169
	v_and_b32_e32 v153, 0xffff0000, v169
	v_rcp_f32_e32 v146, v146
	v_rcp_f32_e32 v147, v147
	v_rcp_f32_e32 v148, v148
	v_rcp_f32_e32 v149, v149
	v_rcp_f32_e32 v150, v150
	v_rcp_f32_e32 v151, v151
	v_rcp_f32_e32 v152, v152
	v_rcp_f32_e32 v153, v153
	v_lshlrev_b32_e32 v154, 16, v170
	v_and_b32_e32 v155, 0xffff0000, v170
	v_lshlrev_b32_e32 v156, 16, v171
	v_and_b32_e32 v157, 0xffff0000, v171
	v_lshlrev_b32_e32 v158, 16, v172
	v_and_b32_e32 v159, 0xffff0000, v172
	v_lshlrev_b32_e32 v160, 16, v173
	v_and_b32_e32 v161, 0xffff0000, v173
	v_pk_mul_f32 v[146:147], v[146:147], v[154:155]
	v_pk_mul_f32 v[148:149], v[148:149], v[156:157]
	v_pk_mul_f32 v[150:151], v[150:151], v[158:159]
	v_pk_mul_f32 v[152:153], v[152:153], v[160:161]
	v_pk_mul_f32 v[124:125], v[124:125], v[146:147]
	v_pk_mul_f32 v[126:127], v[126:127], v[148:149]
	v_pk_mul_f32 v[120:121], v[120:121], v[150:151]
	v_pk_mul_f32 v[122:123], v[122:123], v[152:153]
	s_waitcnt vmcnt(12)
	v_lshlrev_b32_e32 v146, 16, v174
	v_and_b32_e32 v147, 0xffff0000, v174
	v_lshlrev_b32_e32 v148, 16, v175
	v_and_b32_e32 v149, 0xffff0000, v175
	v_lshlrev_b32_e32 v150, 16, v176
	v_and_b32_e32 v151, 0xffff0000, v176
	v_lshlrev_b32_e32 v152, 16, v177
	v_and_b32_e32 v153, 0xffff0000, v177
	v_rcp_f32_e32 v146, v146
	v_rcp_f32_e32 v147, v147
	v_rcp_f32_e32 v148, v148
	v_rcp_f32_e32 v149, v149
	v_rcp_f32_e32 v150, v150
	v_rcp_f32_e32 v151, v151
	v_rcp_f32_e32 v152, v152
	v_rcp_f32_e32 v153, v153
	v_lshlrev_b32_e32 v154, 16, v178
	v_and_b32_e32 v155, 0xffff0000, v178
	v_lshlrev_b32_e32 v156, 16, v179
	v_and_b32_e32 v157, 0xffff0000, v179
	v_lshlrev_b32_e32 v158, 16, v180
	v_and_b32_e32 v159, 0xffff0000, v180
	v_lshlrev_b32_e32 v160, 16, v181
	v_and_b32_e32 v161, 0xffff0000, v181
	v_pk_mul_f32 v[146:147], v[146:147], v[154:155]
	v_pk_mul_f32 v[148:149], v[148:149], v[156:157]
	v_pk_mul_f32 v[150:151], v[150:151], v[158:159]
	v_pk_mul_f32 v[152:153], v[152:153], v[160:161]
	v_pk_mul_f32 v[92:93], v[92:93], v[146:147]
	v_pk_mul_f32 v[94:95], v[94:95], v[148:149]
	v_pk_mul_f32 v[88:89], v[88:89], v[150:151]
	v_pk_mul_f32 v[90:91], v[90:91], v[152:153]
	s_waitcnt vmcnt(10)
	v_lshlrev_b32_e32 v146, 16, v184
	v_and_b32_e32 v147, 0xffff0000, v184
	v_lshlrev_b32_e32 v148, 16, v185
	v_and_b32_e32 v149, 0xffff0000, v185
	v_lshlrev_b32_e32 v150, 16, v186
	v_and_b32_e32 v151, 0xffff0000, v186
	v_lshlrev_b32_e32 v152, 16, v187
	v_and_b32_e32 v153, 0xffff0000, v187
	v_rcp_f32_e32 v146, v146
	v_rcp_f32_e32 v147, v147
	v_rcp_f32_e32 v148, v148
	v_rcp_f32_e32 v149, v149
	v_rcp_f32_e32 v150, v150
	v_rcp_f32_e32 v151, v151
	v_rcp_f32_e32 v152, v152
	v_rcp_f32_e32 v153, v153
	v_lshlrev_b32_e32 v154, 16, v188
	v_and_b32_e32 v155, 0xffff0000, v188
	v_lshlrev_b32_e32 v156, 16, v189
	v_and_b32_e32 v157, 0xffff0000, v189
	v_lshlrev_b32_e32 v158, 16, v190
	v_and_b32_e32 v159, 0xffff0000, v190
	v_lshlrev_b32_e32 v160, 16, v191
	v_and_b32_e32 v161, 0xffff0000, v191
	v_pk_mul_f32 v[146:147], v[146:147], v[154:155]
	v_pk_mul_f32 v[148:149], v[148:149], v[156:157]
	v_pk_mul_f32 v[150:151], v[150:151], v[158:159]
	v_pk_mul_f32 v[152:153], v[152:153], v[160:161]
	v_pk_mul_f32 v[116:117], v[116:117], v[146:147]
	v_pk_mul_f32 v[118:119], v[118:119], v[148:149]
	v_pk_mul_f32 v[112:113], v[112:113], v[150:151]
	v_pk_mul_f32 v[114:115], v[114:115], v[152:153]
	s_waitcnt vmcnt(8)
	v_lshlrev_b32_e32 v146, 16, v192
	v_and_b32_e32 v147, 0xffff0000, v192
	v_lshlrev_b32_e32 v148, 16, v193
	v_and_b32_e32 v149, 0xffff0000, v193
	v_lshlrev_b32_e32 v150, 16, v194
	v_and_b32_e32 v151, 0xffff0000, v194
	v_lshlrev_b32_e32 v152, 16, v195
	v_and_b32_e32 v153, 0xffff0000, v195
	v_rcp_f32_e32 v146, v146
	v_rcp_f32_e32 v147, v147
	v_rcp_f32_e32 v148, v148
	v_rcp_f32_e32 v149, v149
	v_rcp_f32_e32 v150, v150
	v_rcp_f32_e32 v151, v151
	v_rcp_f32_e32 v152, v152
	v_rcp_f32_e32 v153, v153
	v_lshlrev_b32_e32 v154, 16, v196
	v_and_b32_e32 v155, 0xffff0000, v196
	v_lshlrev_b32_e32 v156, 16, v197
	v_and_b32_e32 v157, 0xffff0000, v197
	v_lshlrev_b32_e32 v158, 16, v198
	v_and_b32_e32 v159, 0xffff0000, v198
	v_lshlrev_b32_e32 v160, 16, v199
	v_and_b32_e32 v161, 0xffff0000, v199
	v_pk_mul_f32 v[146:147], v[146:147], v[154:155]
	v_pk_mul_f32 v[148:149], v[148:149], v[156:157]
	v_pk_mul_f32 v[150:151], v[150:151], v[158:159]
	v_pk_mul_f32 v[152:153], v[152:153], v[160:161]
	v_pk_mul_f32 v[84:85], v[84:85], v[146:147]
	v_pk_mul_f32 v[86:87], v[86:87], v[148:149]
	v_pk_mul_f32 v[80:81], v[80:81], v[150:151]
	v_pk_mul_f32 v[82:83], v[82:83], v[152:153]
	v_add_u32_e32 v144, 0x600000, v142
	global_load_dwordx4 v[166:169], v144, s[76:77]
	global_load_dwordx4 v[170:173], v144, s[78:79]
	global_load_dwordx4 v[174:177], v144, s[76:77] offset:256
	global_load_dwordx4 v[178:181], v144, s[78:79] offset:256
	v_add_u32_e32 v145, 0x6c0000, v142
	global_load_dwordx4 v[184:187], v145, s[76:77]
	global_load_dwordx4 v[188:191], v145, s[78:79]
	global_load_dwordx4 v[192:195], v145, s[76:77] offset:256
	global_load_dwordx4 v[196:199], v145, s[78:79] offset:256
	s_waitcnt vmcnt(14)
	v_lshlrev_b32_e32 v146, 16, v200
	v_and_b32_e32 v147, 0xffff0000, v200
	v_lshlrev_b32_e32 v148, 16, v201
	v_and_b32_e32 v149, 0xffff0000, v201
	v_lshlrev_b32_e32 v150, 16, v202
	v_and_b32_e32 v151, 0xffff0000, v202
	v_lshlrev_b32_e32 v152, 16, v203
	v_and_b32_e32 v153, 0xffff0000, v203
	v_rcp_f32_e32 v146, v146
	v_rcp_f32_e32 v147, v147
	v_rcp_f32_e32 v148, v148
	v_rcp_f32_e32 v149, v149
	v_rcp_f32_e32 v150, v150
	v_rcp_f32_e32 v151, v151
	v_rcp_f32_e32 v152, v152
	v_rcp_f32_e32 v153, v153
	v_lshlrev_b32_e32 v154, 16, v204
	v_and_b32_e32 v155, 0xffff0000, v204
	v_lshlrev_b32_e32 v156, 16, v205
	v_and_b32_e32 v157, 0xffff0000, v205
	v_lshlrev_b32_e32 v158, 16, v206
	v_and_b32_e32 v159, 0xffff0000, v206
	v_lshlrev_b32_e32 v160, 16, v207
	v_and_b32_e32 v161, 0xffff0000, v207
	v_pk_mul_f32 v[146:147], v[146:147], v[154:155]
	v_pk_mul_f32 v[148:149], v[148:149], v[156:157]
	v_pk_mul_f32 v[150:151], v[150:151], v[158:159]
	v_pk_mul_f32 v[152:153], v[152:153], v[160:161]
	v_pk_mul_f32 v[108:109], v[108:109], v[146:147]
	v_pk_mul_f32 v[110:111], v[110:111], v[148:149]
	v_pk_mul_f32 v[104:105], v[104:105], v[150:151]
	v_pk_mul_f32 v[106:107], v[106:107], v[152:153]
	s_waitcnt vmcnt(12)
	v_lshlrev_b32_e32 v146, 16, v208
	v_and_b32_e32 v147, 0xffff0000, v208
	v_lshlrev_b32_e32 v148, 16, v209
	v_and_b32_e32 v149, 0xffff0000, v209
	v_lshlrev_b32_e32 v150, 16, v210
	v_and_b32_e32 v151, 0xffff0000, v210
	v_lshlrev_b32_e32 v152, 16, v211
	v_and_b32_e32 v153, 0xffff0000, v211
	v_rcp_f32_e32 v146, v146
	v_rcp_f32_e32 v147, v147
	v_rcp_f32_e32 v148, v148
	v_rcp_f32_e32 v149, v149
	v_rcp_f32_e32 v150, v150
	v_rcp_f32_e32 v151, v151
	v_rcp_f32_e32 v152, v152
	v_rcp_f32_e32 v153, v153
	v_lshlrev_b32_e32 v154, 16, v212
	v_and_b32_e32 v155, 0xffff0000, v212
	v_lshlrev_b32_e32 v156, 16, v213
	v_and_b32_e32 v157, 0xffff0000, v213
	v_lshlrev_b32_e32 v158, 16, v214
	v_and_b32_e32 v159, 0xffff0000, v214
	v_lshlrev_b32_e32 v160, 16, v215
	v_and_b32_e32 v161, 0xffff0000, v215
	v_pk_mul_f32 v[146:147], v[146:147], v[154:155]
	v_pk_mul_f32 v[148:149], v[148:149], v[156:157]
	v_pk_mul_f32 v[150:151], v[150:151], v[158:159]
	v_pk_mul_f32 v[152:153], v[152:153], v[160:161]
	v_pk_mul_f32 v[76:77], v[76:77], v[146:147]
	v_pk_mul_f32 v[78:79], v[78:79], v[148:149]
	v_pk_mul_f32 v[72:73], v[72:73], v[150:151]
	v_pk_mul_f32 v[74:75], v[74:75], v[152:153]
	s_waitcnt vmcnt(10)
	v_lshlrev_b32_e32 v146, 16, v216
	v_and_b32_e32 v147, 0xffff0000, v216
	v_lshlrev_b32_e32 v148, 16, v217
	v_and_b32_e32 v149, 0xffff0000, v217
	v_lshlrev_b32_e32 v150, 16, v218
	v_and_b32_e32 v151, 0xffff0000, v218
	v_lshlrev_b32_e32 v152, 16, v219
	v_and_b32_e32 v153, 0xffff0000, v219
	v_rcp_f32_e32 v146, v146
	v_rcp_f32_e32 v147, v147
	v_rcp_f32_e32 v148, v148
	v_rcp_f32_e32 v149, v149
	v_rcp_f32_e32 v150, v150
	v_rcp_f32_e32 v151, v151
	v_rcp_f32_e32 v152, v152
	v_rcp_f32_e32 v153, v153
	v_lshlrev_b32_e32 v154, 16, v220
	v_and_b32_e32 v155, 0xffff0000, v220
	v_lshlrev_b32_e32 v156, 16, v221
	v_and_b32_e32 v157, 0xffff0000, v221
	v_lshlrev_b32_e32 v158, 16, v222
	v_and_b32_e32 v159, 0xffff0000, v222
	v_lshlrev_b32_e32 v160, 16, v223
	v_and_b32_e32 v161, 0xffff0000, v223
	v_pk_mul_f32 v[146:147], v[146:147], v[154:155]
	v_pk_mul_f32 v[148:149], v[148:149], v[156:157]
	v_pk_mul_f32 v[150:151], v[150:151], v[158:159]
	v_pk_mul_f32 v[152:153], v[152:153], v[160:161]
	v_pk_mul_f32 v[100:101], v[100:101], v[146:147]
	v_pk_mul_f32 v[102:103], v[102:103], v[148:149]
	v_pk_mul_f32 v[96:97], v[96:97], v[150:151]
	v_pk_mul_f32 v[98:99], v[98:99], v[152:153]
	s_waitcnt vmcnt(8)
	v_lshlrev_b32_e32 v146, 16, v224
	v_and_b32_e32 v147, 0xffff0000, v224
	v_lshlrev_b32_e32 v148, 16, v225
	v_and_b32_e32 v149, 0xffff0000, v225
	v_lshlrev_b32_e32 v150, 16, v226
	v_and_b32_e32 v151, 0xffff0000, v226
	v_lshlrev_b32_e32 v152, 16, v227
	v_and_b32_e32 v153, 0xffff0000, v227
	v_rcp_f32_e32 v146, v146
	v_rcp_f32_e32 v147, v147
	v_rcp_f32_e32 v148, v148
	v_rcp_f32_e32 v149, v149
	v_rcp_f32_e32 v150, v150
	v_rcp_f32_e32 v151, v151
	v_rcp_f32_e32 v152, v152
	v_rcp_f32_e32 v153, v153
	v_lshlrev_b32_e32 v154, 16, v228
	v_and_b32_e32 v155, 0xffff0000, v228
	v_lshlrev_b32_e32 v156, 16, v229
	v_and_b32_e32 v157, 0xffff0000, v229
	v_lshlrev_b32_e32 v158, 16, v230
	v_and_b32_e32 v159, 0xffff0000, v230
	v_lshlrev_b32_e32 v160, 16, v231
	v_and_b32_e32 v161, 0xffff0000, v231
	v_pk_mul_f32 v[146:147], v[146:147], v[154:155]
	v_pk_mul_f32 v[148:149], v[148:149], v[156:157]
	v_pk_mul_f32 v[150:151], v[150:151], v[158:159]
	v_pk_mul_f32 v[152:153], v[152:153], v[160:161]
	v_pk_mul_f32 v[68:69], v[68:69], v[146:147]
	v_pk_mul_f32 v[70:71], v[70:71], v[148:149]
	v_pk_mul_f32 v[64:65], v[64:65], v[150:151]
	v_pk_mul_f32 v[66:67], v[66:67], v[152:153]
	v_add_u32_e32 v144, 0x780000, v142
	global_load_dwordx4 v[200:203], v144, s[76:77]
	global_load_dwordx4 v[204:207], v144, s[78:79]
	global_load_dwordx4 v[208:211], v144, s[76:77] offset:256
	global_load_dwordx4 v[212:215], v144, s[78:79] offset:256
	v_add_u32_e32 v145, 0x840000, v142
	global_load_dwordx4 v[216:219], v145, s[76:77]
	global_load_dwordx4 v[220:223], v145, s[78:79]
	global_load_dwordx4 v[224:227], v145, s[76:77] offset:256
	global_load_dwordx4 v[228:231], v145, s[78:79] offset:256
	s_waitcnt vmcnt(14)
	v_lshlrev_b32_e32 v146, 16, v166
	v_and_b32_e32 v147, 0xffff0000, v166
	v_lshlrev_b32_e32 v148, 16, v167
	v_and_b32_e32 v149, 0xffff0000, v167
	v_lshlrev_b32_e32 v150, 16, v168
	v_and_b32_e32 v151, 0xffff0000, v168
	v_lshlrev_b32_e32 v152, 16, v169
	v_and_b32_e32 v153, 0xffff0000, v169
	v_rcp_f32_e32 v146, v146
	v_rcp_f32_e32 v147, v147
	v_rcp_f32_e32 v148, v148
	v_rcp_f32_e32 v149, v149
	v_rcp_f32_e32 v150, v150
	v_rcp_f32_e32 v151, v151
	v_rcp_f32_e32 v152, v152
	v_rcp_f32_e32 v153, v153
	v_lshlrev_b32_e32 v154, 16, v170
	v_and_b32_e32 v155, 0xffff0000, v170
	v_lshlrev_b32_e32 v156, 16, v171
	v_and_b32_e32 v157, 0xffff0000, v171
	v_lshlrev_b32_e32 v158, 16, v172
	v_and_b32_e32 v159, 0xffff0000, v172
	v_lshlrev_b32_e32 v160, 16, v173
	v_and_b32_e32 v161, 0xffff0000, v173
	v_pk_mul_f32 v[146:147], v[146:147], v[154:155]
	v_pk_mul_f32 v[148:149], v[148:149], v[156:157]
	v_pk_mul_f32 v[150:151], v[150:151], v[158:159]
	v_pk_mul_f32 v[152:153], v[152:153], v[160:161]
	v_pk_mul_f32 v[60:61], v[60:61], v[146:147]
	v_pk_mul_f32 v[62:63], v[62:63], v[148:149]
	v_pk_mul_f32 v[56:57], v[56:57], v[150:151]
	v_pk_mul_f32 v[58:59], v[58:59], v[152:153]
	s_waitcnt vmcnt(12)
	v_lshlrev_b32_e32 v146, 16, v174
	v_and_b32_e32 v147, 0xffff0000, v174
	v_lshlrev_b32_e32 v148, 16, v175
	v_and_b32_e32 v149, 0xffff0000, v175
	v_lshlrev_b32_e32 v150, 16, v176
	v_and_b32_e32 v151, 0xffff0000, v176
	v_lshlrev_b32_e32 v152, 16, v177
	v_and_b32_e32 v153, 0xffff0000, v177
	v_rcp_f32_e32 v146, v146
	v_rcp_f32_e32 v147, v147
	v_rcp_f32_e32 v148, v148
	v_rcp_f32_e32 v149, v149
	v_rcp_f32_e32 v150, v150
	v_rcp_f32_e32 v151, v151
	v_rcp_f32_e32 v152, v152
	v_rcp_f32_e32 v153, v153
	v_lshlrev_b32_e32 v154, 16, v178
	v_and_b32_e32 v155, 0xffff0000, v178
	v_lshlrev_b32_e32 v156, 16, v179
	v_and_b32_e32 v157, 0xffff0000, v179
	v_lshlrev_b32_e32 v158, 16, v180
	v_and_b32_e32 v159, 0xffff0000, v180
	v_lshlrev_b32_e32 v160, 16, v181
	v_and_b32_e32 v161, 0xffff0000, v181
	v_pk_mul_f32 v[146:147], v[146:147], v[154:155]
	v_pk_mul_f32 v[148:149], v[148:149], v[156:157]
	v_pk_mul_f32 v[150:151], v[150:151], v[158:159]
	v_pk_mul_f32 v[152:153], v[152:153], v[160:161]
	v_pk_mul_f32 v[28:29], v[28:29], v[146:147]
	v_pk_mul_f32 v[30:31], v[30:31], v[148:149]
	v_pk_mul_f32 v[24:25], v[24:25], v[150:151]
	v_pk_mul_f32 v[26:27], v[26:27], v[152:153]
	s_waitcnt vmcnt(10)
	v_lshlrev_b32_e32 v146, 16, v184
	v_and_b32_e32 v147, 0xffff0000, v184
	v_lshlrev_b32_e32 v148, 16, v185
	v_and_b32_e32 v149, 0xffff0000, v185
	v_lshlrev_b32_e32 v150, 16, v186
	v_and_b32_e32 v151, 0xffff0000, v186
	v_lshlrev_b32_e32 v152, 16, v187
	v_and_b32_e32 v153, 0xffff0000, v187
	v_rcp_f32_e32 v146, v146
	v_rcp_f32_e32 v147, v147
	v_rcp_f32_e32 v148, v148
	v_rcp_f32_e32 v149, v149
	v_rcp_f32_e32 v150, v150
	v_rcp_f32_e32 v151, v151
	v_rcp_f32_e32 v152, v152
	v_rcp_f32_e32 v153, v153
	v_lshlrev_b32_e32 v154, 16, v188
	v_and_b32_e32 v155, 0xffff0000, v188
	v_lshlrev_b32_e32 v156, 16, v189
	v_and_b32_e32 v157, 0xffff0000, v189
	v_lshlrev_b32_e32 v158, 16, v190
	v_and_b32_e32 v159, 0xffff0000, v190
	v_lshlrev_b32_e32 v160, 16, v191
	v_and_b32_e32 v161, 0xffff0000, v191
	v_pk_mul_f32 v[146:147], v[146:147], v[154:155]
	v_pk_mul_f32 v[148:149], v[148:149], v[156:157]
	v_pk_mul_f32 v[150:151], v[150:151], v[158:159]
	v_pk_mul_f32 v[152:153], v[152:153], v[160:161]
	v_pk_mul_f32 v[52:53], v[52:53], v[146:147]
	v_pk_mul_f32 v[54:55], v[54:55], v[148:149]
	v_pk_mul_f32 v[48:49], v[48:49], v[150:151]
	v_pk_mul_f32 v[50:51], v[50:51], v[152:153]
	s_waitcnt vmcnt(8)
	v_lshlrev_b32_e32 v146, 16, v192
	v_and_b32_e32 v147, 0xffff0000, v192
	v_lshlrev_b32_e32 v148, 16, v193
	v_and_b32_e32 v149, 0xffff0000, v193
	v_lshlrev_b32_e32 v150, 16, v194
	v_and_b32_e32 v151, 0xffff0000, v194
	v_lshlrev_b32_e32 v152, 16, v195
	v_and_b32_e32 v153, 0xffff0000, v195
	v_rcp_f32_e32 v146, v146
	v_rcp_f32_e32 v147, v147
	v_rcp_f32_e32 v148, v148
	v_rcp_f32_e32 v149, v149
	v_rcp_f32_e32 v150, v150
	v_rcp_f32_e32 v151, v151
	v_rcp_f32_e32 v152, v152
	v_rcp_f32_e32 v153, v153
	v_lshlrev_b32_e32 v154, 16, v196
	v_and_b32_e32 v155, 0xffff0000, v196
	v_lshlrev_b32_e32 v156, 16, v197
	v_and_b32_e32 v157, 0xffff0000, v197
	v_lshlrev_b32_e32 v158, 16, v198
	v_and_b32_e32 v159, 0xffff0000, v198
	v_lshlrev_b32_e32 v160, 16, v199
	v_and_b32_e32 v161, 0xffff0000, v199
	v_pk_mul_f32 v[146:147], v[146:147], v[154:155]
	v_pk_mul_f32 v[148:149], v[148:149], v[156:157]
	v_pk_mul_f32 v[150:151], v[150:151], v[158:159]
	v_pk_mul_f32 v[152:153], v[152:153], v[160:161]
	v_pk_mul_f32 v[20:21], v[20:21], v[146:147]
	v_pk_mul_f32 v[22:23], v[22:23], v[148:149]
	v_pk_mul_f32 v[16:17], v[16:17], v[150:151]
	v_pk_mul_f32 v[18:19], v[18:19], v[152:153]
	s_waitcnt vmcnt(6)
	v_lshlrev_b32_e32 v146, 16, v200
	v_and_b32_e32 v147, 0xffff0000, v200
	v_lshlrev_b32_e32 v148, 16, v201
	v_and_b32_e32 v149, 0xffff0000, v201
	v_lshlrev_b32_e32 v150, 16, v202
	v_and_b32_e32 v151, 0xffff0000, v202
	v_lshlrev_b32_e32 v152, 16, v203
	v_and_b32_e32 v153, 0xffff0000, v203
	v_rcp_f32_e32 v146, v146
	v_rcp_f32_e32 v147, v147
	v_rcp_f32_e32 v148, v148
	v_rcp_f32_e32 v149, v149
	v_rcp_f32_e32 v150, v150
	v_rcp_f32_e32 v151, v151
	v_rcp_f32_e32 v152, v152
	v_rcp_f32_e32 v153, v153
	v_lshlrev_b32_e32 v154, 16, v204
	v_and_b32_e32 v155, 0xffff0000, v204
	v_lshlrev_b32_e32 v156, 16, v205
	v_and_b32_e32 v157, 0xffff0000, v205
	v_lshlrev_b32_e32 v158, 16, v206
	v_and_b32_e32 v159, 0xffff0000, v206
	v_lshlrev_b32_e32 v160, 16, v207
	v_and_b32_e32 v161, 0xffff0000, v207
	v_pk_mul_f32 v[146:147], v[146:147], v[154:155]
	v_pk_mul_f32 v[148:149], v[148:149], v[156:157]
	v_pk_mul_f32 v[150:151], v[150:151], v[158:159]
	v_pk_mul_f32 v[152:153], v[152:153], v[160:161]
	v_pk_mul_f32 v[44:45], v[44:45], v[146:147]
	v_pk_mul_f32 v[46:47], v[46:47], v[148:149]
	v_pk_mul_f32 v[40:41], v[40:41], v[150:151]
	v_pk_mul_f32 v[42:43], v[42:43], v[152:153]
	s_waitcnt vmcnt(4)
	v_lshlrev_b32_e32 v146, 16, v208
	v_and_b32_e32 v147, 0xffff0000, v208
	v_lshlrev_b32_e32 v148, 16, v209
	v_and_b32_e32 v149, 0xffff0000, v209
	v_lshlrev_b32_e32 v150, 16, v210
	v_and_b32_e32 v151, 0xffff0000, v210
	v_lshlrev_b32_e32 v152, 16, v211
	v_and_b32_e32 v153, 0xffff0000, v211
	v_rcp_f32_e32 v146, v146
	v_rcp_f32_e32 v147, v147
	v_rcp_f32_e32 v148, v148
	v_rcp_f32_e32 v149, v149
	v_rcp_f32_e32 v150, v150
	v_rcp_f32_e32 v151, v151
	v_rcp_f32_e32 v152, v152
	v_rcp_f32_e32 v153, v153
	v_lshlrev_b32_e32 v154, 16, v212
	v_and_b32_e32 v155, 0xffff0000, v212
	v_lshlrev_b32_e32 v156, 16, v213
	v_and_b32_e32 v157, 0xffff0000, v213
	v_lshlrev_b32_e32 v158, 16, v214
	v_and_b32_e32 v159, 0xffff0000, v214
	v_lshlrev_b32_e32 v160, 16, v215
	v_and_b32_e32 v161, 0xffff0000, v215
	v_pk_mul_f32 v[146:147], v[146:147], v[154:155]
	v_pk_mul_f32 v[148:149], v[148:149], v[156:157]
	v_pk_mul_f32 v[150:151], v[150:151], v[158:159]
	v_pk_mul_f32 v[152:153], v[152:153], v[160:161]
	v_pk_mul_f32 v[12:13], v[12:13], v[146:147]
	v_pk_mul_f32 v[14:15], v[14:15], v[148:149]
	v_pk_mul_f32 v[8:9], v[8:9], v[150:151]
	v_pk_mul_f32 v[10:11], v[10:11], v[152:153]
	s_waitcnt vmcnt(2)
	v_lshlrev_b32_e32 v146, 16, v216
	v_and_b32_e32 v147, 0xffff0000, v216
	v_lshlrev_b32_e32 v148, 16, v217
	v_and_b32_e32 v149, 0xffff0000, v217
	v_lshlrev_b32_e32 v150, 16, v218
	v_and_b32_e32 v151, 0xffff0000, v218
	v_lshlrev_b32_e32 v152, 16, v219
	v_and_b32_e32 v153, 0xffff0000, v219
	v_rcp_f32_e32 v146, v146
	v_rcp_f32_e32 v147, v147
	v_rcp_f32_e32 v148, v148
	v_rcp_f32_e32 v149, v149
	v_rcp_f32_e32 v150, v150
	v_rcp_f32_e32 v151, v151
	v_rcp_f32_e32 v152, v152
	v_rcp_f32_e32 v153, v153
	v_lshlrev_b32_e32 v154, 16, v220
	v_and_b32_e32 v155, 0xffff0000, v220
	v_lshlrev_b32_e32 v156, 16, v221
	v_and_b32_e32 v157, 0xffff0000, v221
	v_lshlrev_b32_e32 v158, 16, v222
	v_and_b32_e32 v159, 0xffff0000, v222
	v_lshlrev_b32_e32 v160, 16, v223
	v_and_b32_e32 v161, 0xffff0000, v223
	v_pk_mul_f32 v[146:147], v[146:147], v[154:155]
	v_pk_mul_f32 v[148:149], v[148:149], v[156:157]
	v_pk_mul_f32 v[150:151], v[150:151], v[158:159]
	v_pk_mul_f32 v[152:153], v[152:153], v[160:161]
	v_pk_mul_f32 v[36:37], v[36:37], v[146:147]
	v_pk_mul_f32 v[38:39], v[38:39], v[148:149]
	v_pk_mul_f32 v[32:33], v[32:33], v[150:151]
	v_pk_mul_f32 v[34:35], v[34:35], v[152:153]
	s_waitcnt vmcnt(0)
	v_lshlrev_b32_e32 v146, 16, v224
	v_and_b32_e32 v147, 0xffff0000, v224
	v_lshlrev_b32_e32 v148, 16, v225
	v_and_b32_e32 v149, 0xffff0000, v225
	v_lshlrev_b32_e32 v150, 16, v226
	v_and_b32_e32 v151, 0xffff0000, v226
	v_lshlrev_b32_e32 v152, 16, v227
	v_and_b32_e32 v153, 0xffff0000, v227
	v_rcp_f32_e32 v146, v146
	v_rcp_f32_e32 v147, v147
	v_rcp_f32_e32 v148, v148
	v_rcp_f32_e32 v149, v149
	v_rcp_f32_e32 v150, v150
	v_rcp_f32_e32 v151, v151
	v_rcp_f32_e32 v152, v152
	v_rcp_f32_e32 v153, v153
	v_lshlrev_b32_e32 v154, 16, v228
	v_and_b32_e32 v155, 0xffff0000, v228
	v_lshlrev_b32_e32 v156, 16, v229
	v_and_b32_e32 v157, 0xffff0000, v229
	v_lshlrev_b32_e32 v158, 16, v230
	v_and_b32_e32 v159, 0xffff0000, v230
	v_lshlrev_b32_e32 v160, 16, v231
	v_and_b32_e32 v161, 0xffff0000, v231
	v_pk_mul_f32 v[146:147], v[146:147], v[154:155]
	v_pk_mul_f32 v[148:149], v[148:149], v[156:157]
	v_pk_mul_f32 v[150:151], v[150:151], v[158:159]
	v_pk_mul_f32 v[152:153], v[152:153], v[160:161]
	v_pk_mul_f32 v[4:5], v[4:5], v[146:147]
	v_pk_mul_f32 v[6:7], v[6:7], v[148:149]
	v_pk_mul_f32 v[0:1], v[0:1], v[150:151]
	v_pk_mul_f32 v[2:3], v[2:3], v[152:153]
	s_branch .Lp3e_done
.Lp3e_half1:
	global_load_dwordx4 v[166:169], v142, s[76:77]
	global_load_dwordx4 v[170:173], v142, s[76:77] offset:256
	v_add_u32_e32 v145, 0xc0000, v142
	global_load_dwordx4 v[174:177], v145, s[76:77]
	global_load_dwordx4 v[178:181], v145, s[76:77] offset:256
	v_add_u32_e32 v144, 0x180000, v142
	global_load_dwordx4 v[184:187], v144, s[76:77]
	global_load_dwordx4 v[188:191], v144, s[76:77] offset:256
	v_add_u32_e32 v145, 0x240000, v142
	global_load_dwordx4 v[192:195], v145, s[76:77]
	global_load_dwordx4 v[196:199], v145, s[76:77] offset:256
	v_add_u32_e32 v144, 0x600000, v142
	global_load_dwordx4 v[200:203], v144, s[76:77]
	global_load_dwordx4 v[204:207], v144, s[76:77] offset:256
	v_add_u32_e32 v145, 0x6c0000, v142
	global_load_dwordx4 v[208:211], v145, s[76:77]
	global_load_dwordx4 v[212:215], v145, s[76:77] offset:256
	v_add_u32_e32 v144, 0x780000, v142
	global_load_dwordx4 v[216:219], v144, s[76:77]
	global_load_dwordx4 v[220:223], v144, s[76:77] offset:256
	v_add_u32_e32 v145, 0x840000, v142
	global_load_dwordx4 v[224:227], v145, s[76:77]
	global_load_dwordx4 v[228:231], v145, s[76:77] offset:256
	s_waitcnt vmcnt(15)
	v_lshlrev_b32_e32 v146, 16, v166
	v_and_b32_e32 v147, 0xffff0000, v166
	v_lshlrev_b32_e32 v148, 16, v167
	v_and_b32_e32 v149, 0xffff0000, v167
	v_lshlrev_b32_e32 v150, 16, v168
	v_and_b32_e32 v151, 0xffff0000, v168
	v_lshlrev_b32_e32 v152, 16, v169
	v_and_b32_e32 v153, 0xffff0000, v169
	v_pk_mul_f32 v[154:155], v[124:125], v[146:147]
	v_pk_mul_f32 v[156:157], v[126:127], v[148:149]
	v_pk_mul_f32 v[158:159], v[120:121], v[150:151]
	v_pk_mul_f32 v[160:161], v[122:123], v[152:153]
	v_cvt_pk_bf16_f32 v166, v154, v155
	v_cvt_pk_bf16_f32 v167, v156, v157
	v_cvt_pk_bf16_f32 v168, v158, v159
	v_cvt_pk_bf16_f32 v169, v160, v161
	global_store_dwordx4 v143, v[166:169], s[72:73]
	s_waitcnt vmcnt(15)
	v_lshlrev_b32_e32 v146, 16, v170
	v_and_b32_e32 v147, 0xffff0000, v170
	v_lshlrev_b32_e32 v148, 16, v171
	v_and_b32_e32 v149, 0xffff0000, v171
	v_lshlrev_b32_e32 v150, 16, v172
	v_and_b32_e32 v151, 0xffff0000, v172
	v_lshlrev_b32_e32 v152, 16, v173
	v_and_b32_e32 v153, 0xffff0000, v173
	v_pk_mul_f32 v[154:155], v[92:93], v[146:147]
	v_pk_mul_f32 v[156:157], v[94:95], v[148:149]
	v_pk_mul_f32 v[158:159], v[88:89], v[150:151]
	v_pk_mul_f32 v[160:161], v[90:91], v[152:153]
	v_cvt_pk_bf16_f32 v170, v154, v155
	v_cvt_pk_bf16_f32 v171, v156, v157
	v_cvt_pk_bf16_f32 v172, v158, v159
	v_cvt_pk_bf16_f32 v173, v160, v161
	global_store_dwordx4 v143, v[170:173], s[72:73] offset:256
	s_waitcnt vmcnt(15)
	v_lshlrev_b32_e32 v146, 16, v174
	v_and_b32_e32 v147, 0xffff0000, v174
	v_lshlrev_b32_e32 v148, 16, v175
	v_and_b32_e32 v149, 0xffff0000, v175
	v_lshlrev_b32_e32 v150, 16, v176
	v_and_b32_e32 v151, 0xffff0000, v176
	v_lshlrev_b32_e32 v152, 16, v177
	v_and_b32_e32 v153, 0xffff0000, v177
	v_pk_mul_f32 v[154:155], v[116:117], v[146:147]
	v_pk_mul_f32 v[156:157], v[118:119], v[148:149]
	v_pk_mul_f32 v[158:159], v[112:113], v[150:151]
	v_pk_mul_f32 v[160:161], v[114:115], v[152:153]
	v_add_u32_e32 v145, 0x20000, v143
	v_cvt_pk_bf16_f32 v174, v154, v155
	v_cvt_pk_bf16_f32 v175, v156, v157
	v_cvt_pk_bf16_f32 v176, v158, v159
	v_cvt_pk_bf16_f32 v177, v160, v161
	global_store_dwordx4 v145, v[174:177], s[72:73]
	s_waitcnt vmcnt(15)
	v_lshlrev_b32_e32 v146, 16, v178
	v_and_b32_e32 v147, 0xffff0000, v178
	v_lshlrev_b32_e32 v148, 16, v179
	v_and_b32_e32 v149, 0xffff0000, v179
	v_lshlrev_b32_e32 v150, 16, v180
	v_and_b32_e32 v151, 0xffff0000, v180
	v_lshlrev_b32_e32 v152, 16, v181
	v_and_b32_e32 v153, 0xffff0000, v181
	v_pk_mul_f32 v[154:155], v[84:85], v[146:147]
	v_pk_mul_f32 v[156:157], v[86:87], v[148:149]
	v_pk_mul_f32 v[158:159], v[80:81], v[150:151]
	v_pk_mul_f32 v[160:161], v[82:83], v[152:153]
	v_cvt_pk_bf16_f32 v178, v154, v155
	v_cvt_pk_bf16_f32 v179, v156, v157
	v_cvt_pk_bf16_f32 v180, v158, v159
	v_cvt_pk_bf16_f32 v181, v160, v161
	global_store_dwordx4 v145, v[178:181], s[72:73] offset:256
	s_waitcnt vmcnt(15)
	v_lshlrev_b32_e32 v146, 16, v184
	v_and_b32_e32 v147, 0xffff0000, v184
	v_lshlrev_b32_e32 v148, 16, v185
	v_and_b32_e32 v149, 0xffff0000, v185
	v_lshlrev_b32_e32 v150, 16, v186
	v_and_b32_e32 v151, 0xffff0000, v186
	v_lshlrev_b32_e32 v152, 16, v187
	v_and_b32_e32 v153, 0xffff0000, v187
	v_pk_mul_f32 v[154:155], v[108:109], v[146:147]
	v_pk_mul_f32 v[156:157], v[110:111], v[148:149]
	v_pk_mul_f32 v[158:159], v[104:105], v[150:151]
	v_pk_mul_f32 v[160:161], v[106:107], v[152:153]
	v_add_u32_e32 v144, 0x40000, v143
	v_cvt_pk_bf16_f32 v184, v154, v155
	v_cvt_pk_bf16_f32 v185, v156, v157
	v_cvt_pk_bf16_f32 v186, v158, v159
	v_cvt_pk_bf16_f32 v187, v160, v161
	global_store_dwordx4 v144, v[184:187], s[72:73]
	s_waitcnt vmcnt(15)
	v_lshlrev_b32_e32 v146, 16, v188
	v_and_b32_e32 v147, 0xffff0000, v188
	v_lshlrev_b32_e32 v148, 16, v189
	v_and_b32_e32 v149, 0xffff0000, v189
	v_lshlrev_b32_e32 v150, 16, v190
	v_and_b32_e32 v151, 0xffff0000, v190
	v_lshlrev_b32_e32 v152, 16, v191
	v_and_b32_e32 v153, 0xffff0000, v191
	v_pk_mul_f32 v[154:155], v[76:77], v[146:147]
	v_pk_mul_f32 v[156:157], v[78:79], v[148:149]
	v_pk_mul_f32 v[158:159], v[72:73], v[150:151]
	v_pk_mul_f32 v[160:161], v[74:75], v[152:153]
	v_cvt_pk_bf16_f32 v188, v154, v155
	v_cvt_pk_bf16_f32 v189, v156, v157
	v_cvt_pk_bf16_f32 v190, v158, v159
	v_cvt_pk_bf16_f32 v191, v160, v161
	global_store_dwordx4 v144, v[188:191], s[72:73] offset:256
	s_waitcnt vmcnt(15)
	v_lshlrev_b32_e32 v146, 16, v192
	v_and_b32_e32 v147, 0xffff0000, v192
	v_lshlrev_b32_e32 v148, 16, v193
	v_and_b32_e32 v149, 0xffff0000, v193
	v_lshlrev_b32_e32 v150, 16, v194
	v_and_b32_e32 v151, 0xffff0000, v194
	v_lshlrev_b32_e32 v152, 16, v195
	v_and_b32_e32 v153, 0xffff0000, v195
	v_pk_mul_f32 v[154:155], v[100:101], v[146:147]
	v_pk_mul_f32 v[156:157], v[102:103], v[148:149]
	v_pk_mul_f32 v[158:159], v[96:97], v[150:151]
	v_pk_mul_f32 v[160:161], v[98:99], v[152:153]
	v_add_u32_e32 v145, 0x60000, v143
	v_cvt_pk_bf16_f32 v192, v154, v155
	v_cvt_pk_bf16_f32 v193, v156, v157
	v_cvt_pk_bf16_f32 v194, v158, v159
	v_cvt_pk_bf16_f32 v195, v160, v161
	global_store_dwordx4 v145, v[192:195], s[72:73]
	s_waitcnt vmcnt(15)
	v_lshlrev_b32_e32 v146, 16, v196
	v_and_b32_e32 v147, 0xffff0000, v196
	v_lshlrev_b32_e32 v148, 16, v197
	v_and_b32_e32 v149, 0xffff0000, v197
	v_lshlrev_b32_e32 v150, 16, v198
	v_and_b32_e32 v151, 0xffff0000, v198
	v_lshlrev_b32_e32 v152, 16, v199
	v_and_b32_e32 v153, 0xffff0000, v199
	v_pk_mul_f32 v[154:155], v[68:69], v[146:147]
	v_pk_mul_f32 v[156:157], v[70:71], v[148:149]
	v_pk_mul_f32 v[158:159], v[64:65], v[150:151]
	v_pk_mul_f32 v[160:161], v[66:67], v[152:153]
	v_cvt_pk_bf16_f32 v196, v154, v155
	v_cvt_pk_bf16_f32 v197, v156, v157
	v_cvt_pk_bf16_f32 v198, v158, v159
	v_cvt_pk_bf16_f32 v199, v160, v161
	global_store_dwordx4 v145, v[196:199], s[72:73] offset:256
	s_waitcnt vmcnt(15)
	v_lshlrev_b32_e32 v146, 16, v200
	v_and_b32_e32 v147, 0xffff0000, v200
	v_lshlrev_b32_e32 v148, 16, v201
	v_and_b32_e32 v149, 0xffff0000, v201
	v_lshlrev_b32_e32 v150, 16, v202
	v_and_b32_e32 v151, 0xffff0000, v202
	v_lshlrev_b32_e32 v152, 16, v203
	v_and_b32_e32 v153, 0xffff0000, v203
	v_pk_mul_f32 v[154:155], v[60:61], v[146:147]
	v_pk_mul_f32 v[156:157], v[62:63], v[148:149]
	v_pk_mul_f32 v[158:159], v[56:57], v[150:151]
	v_pk_mul_f32 v[160:161], v[58:59], v[152:153]
	v_add_u32_e32 v144, 0x100000, v143
	v_cvt_pk_bf16_f32 v200, v154, v155
	v_cvt_pk_bf16_f32 v201, v156, v157
	v_cvt_pk_bf16_f32 v202, v158, v159
	v_cvt_pk_bf16_f32 v203, v160, v161
	global_store_dwordx4 v144, v[200:203], s[72:73]
	s_waitcnt vmcnt(15)
	v_lshlrev_b32_e32 v146, 16, v204
	v_and_b32_e32 v147, 0xffff0000, v204
	v_lshlrev_b32_e32 v148, 16, v205
	v_and_b32_e32 v149, 0xffff0000, v205
	v_lshlrev_b32_e32 v150, 16, v206
	v_and_b32_e32 v151, 0xffff0000, v206
	v_lshlrev_b32_e32 v152, 16, v207
	v_and_b32_e32 v153, 0xffff0000, v207
	v_pk_mul_f32 v[154:155], v[28:29], v[146:147]
	v_pk_mul_f32 v[156:157], v[30:31], v[148:149]
	v_pk_mul_f32 v[158:159], v[24:25], v[150:151]
	v_pk_mul_f32 v[160:161], v[26:27], v[152:153]
	v_cvt_pk_bf16_f32 v204, v154, v155
	v_cvt_pk_bf16_f32 v205, v156, v157
	v_cvt_pk_bf16_f32 v206, v158, v159
	v_cvt_pk_bf16_f32 v207, v160, v161
	global_store_dwordx4 v144, v[204:207], s[72:73] offset:256
	s_waitcnt vmcnt(15)
	v_lshlrev_b32_e32 v146, 16, v208
	v_and_b32_e32 v147, 0xffff0000, v208
	v_lshlrev_b32_e32 v148, 16, v209
	v_and_b32_e32 v149, 0xffff0000, v209
	v_lshlrev_b32_e32 v150, 16, v210
	v_and_b32_e32 v151, 0xffff0000, v210
	v_lshlrev_b32_e32 v152, 16, v211
	v_and_b32_e32 v153, 0xffff0000, v211
	v_pk_mul_f32 v[154:155], v[52:53], v[146:147]
	v_pk_mul_f32 v[156:157], v[54:55], v[148:149]
	v_pk_mul_f32 v[158:159], v[48:49], v[150:151]
	v_pk_mul_f32 v[160:161], v[50:51], v[152:153]
	v_add_u32_e32 v145, 0x120000, v143
	v_cvt_pk_bf16_f32 v208, v154, v155
	v_cvt_pk_bf16_f32 v209, v156, v157
	v_cvt_pk_bf16_f32 v210, v158, v159
	v_cvt_pk_bf16_f32 v211, v160, v161
	global_store_dwordx4 v145, v[208:211], s[72:73]
	s_waitcnt vmcnt(15)
	v_lshlrev_b32_e32 v146, 16, v212
	v_and_b32_e32 v147, 0xffff0000, v212
	v_lshlrev_b32_e32 v148, 16, v213
	v_and_b32_e32 v149, 0xffff0000, v213
	v_lshlrev_b32_e32 v150, 16, v214
	v_and_b32_e32 v151, 0xffff0000, v214
	v_lshlrev_b32_e32 v152, 16, v215
	v_and_b32_e32 v153, 0xffff0000, v215
	v_pk_mul_f32 v[154:155], v[20:21], v[146:147]
	v_pk_mul_f32 v[156:157], v[22:23], v[148:149]
	v_pk_mul_f32 v[158:159], v[16:17], v[150:151]
	v_pk_mul_f32 v[160:161], v[18:19], v[152:153]
	v_cvt_pk_bf16_f32 v212, v154, v155
	v_cvt_pk_bf16_f32 v213, v156, v157
	v_cvt_pk_bf16_f32 v214, v158, v159
	v_cvt_pk_bf16_f32 v215, v160, v161
	global_store_dwordx4 v145, v[212:215], s[72:73] offset:256
	s_waitcnt vmcnt(15)
	v_lshlrev_b32_e32 v146, 16, v216
	v_and_b32_e32 v147, 0xffff0000, v216
	v_lshlrev_b32_e32 v148, 16, v217
	v_and_b32_e32 v149, 0xffff0000, v217
	v_lshlrev_b32_e32 v150, 16, v218
	v_and_b32_e32 v151, 0xffff0000, v218
	v_lshlrev_b32_e32 v152, 16, v219
	v_and_b32_e32 v153, 0xffff0000, v219
	v_pk_mul_f32 v[154:155], v[44:45], v[146:147]
	v_pk_mul_f32 v[156:157], v[46:47], v[148:149]
	v_pk_mul_f32 v[158:159], v[40:41], v[150:151]
	v_pk_mul_f32 v[160:161], v[42:43], v[152:153]
	v_add_u32_e32 v144, 0x140000, v143
	v_cvt_pk_bf16_f32 v216, v154, v155
	v_cvt_pk_bf16_f32 v217, v156, v157
	v_cvt_pk_bf16_f32 v218, v158, v159
	v_cvt_pk_bf16_f32 v219, v160, v161
	global_store_dwordx4 v144, v[216:219], s[72:73]
	s_waitcnt vmcnt(15)
	v_lshlrev_b32_e32 v146, 16, v220
	v_and_b32_e32 v147, 0xffff0000, v220
	v_lshlrev_b32_e32 v148, 16, v221
	v_and_b32_e32 v149, 0xffff0000, v221
	v_lshlrev_b32_e32 v150, 16, v222
	v_and_b32_e32 v151, 0xffff0000, v222
	v_lshlrev_b32_e32 v152, 16, v223
	v_and_b32_e32 v153, 0xffff0000, v223
	v_pk_mul_f32 v[154:155], v[12:13], v[146:147]
	v_pk_mul_f32 v[156:157], v[14:15], v[148:149]
	v_pk_mul_f32 v[158:159], v[8:9], v[150:151]
	v_pk_mul_f32 v[160:161], v[10:11], v[152:153]
	v_cvt_pk_bf16_f32 v220, v154, v155
	v_cvt_pk_bf16_f32 v221, v156, v157
	v_cvt_pk_bf16_f32 v222, v158, v159
	v_cvt_pk_bf16_f32 v223, v160, v161
	global_store_dwordx4 v144, v[220:223], s[72:73] offset:256
	s_waitcnt vmcnt(15)
	v_lshlrev_b32_e32 v146, 16, v224
	v_and_b32_e32 v147, 0xffff0000, v224
	v_lshlrev_b32_e32 v148, 16, v225
	v_and_b32_e32 v149, 0xffff0000, v225
	v_lshlrev_b32_e32 v150, 16, v226
	v_and_b32_e32 v151, 0xffff0000, v226
	v_lshlrev_b32_e32 v152, 16, v227
	v_and_b32_e32 v153, 0xffff0000, v227
	v_pk_mul_f32 v[154:155], v[36:37], v[146:147]
	v_pk_mul_f32 v[156:157], v[38:39], v[148:149]
	v_pk_mul_f32 v[158:159], v[32:33], v[150:151]
	v_pk_mul_f32 v[160:161], v[34:35], v[152:153]
	v_add_u32_e32 v145, 0x160000, v143
	v_cvt_pk_bf16_f32 v224, v154, v155
	v_cvt_pk_bf16_f32 v225, v156, v157
	v_cvt_pk_bf16_f32 v226, v158, v159
	v_cvt_pk_bf16_f32 v227, v160, v161
	global_store_dwordx4 v145, v[224:227], s[72:73]
	s_waitcnt vmcnt(15)
	v_lshlrev_b32_e32 v146, 16, v228
	v_and_b32_e32 v147, 0xffff0000, v228
	v_lshlrev_b32_e32 v148, 16, v229
	v_and_b32_e32 v149, 0xffff0000, v229
	v_lshlrev_b32_e32 v150, 16, v230
	v_and_b32_e32 v151, 0xffff0000, v230
	v_lshlrev_b32_e32 v152, 16, v231
	v_and_b32_e32 v153, 0xffff0000, v231
	v_pk_mul_f32 v[154:155], v[4:5], v[146:147]
	v_pk_mul_f32 v[156:157], v[6:7], v[148:149]
	v_pk_mul_f32 v[158:159], v[0:1], v[150:151]
	v_pk_mul_f32 v[160:161], v[2:3], v[152:153]
	v_cvt_pk_bf16_f32 v228, v154, v155
	v_cvt_pk_bf16_f32 v229, v156, v157
	v_cvt_pk_bf16_f32 v230, v158, v159
	v_cvt_pk_bf16_f32 v231, v160, v161
	global_store_dwordx4 v145, v[228:231], s[72:73] offset:256
.Lp3e_done:
.LBB0_388:
	s_andn2_b64 vcc, exec, s[24:25]
	s_mov_b64 s[24:25], -1
	s_cbranch_vccnz .LBB0_328
	s_and_b64 vcc, exec, s[0:1]
	s_cbranch_vccnz .LBB0_391
	v_mov_b32_e32 v0, 0
	v_mov_b32_e32 v1, v0
	v_mov_b32_e32 v2, v0
	v_mov_b32_e32 v3, v0
	v_mov_b32_e32 v4, v0
	v_mov_b32_e32 v5, v0
	v_mov_b32_e32 v6, v0
	v_mov_b32_e32 v7, v0
	v_mov_b32_e32 v8, v0
	v_mov_b32_e32 v9, v0
	v_mov_b32_e32 v10, v0
	v_mov_b32_e32 v11, v0
	v_mov_b32_e32 v12, v0
	v_mov_b32_e32 v13, v0
	v_mov_b32_e32 v14, v0
	v_mov_b32_e32 v15, v0
	v_mov_b32_e32 v16, v0
	v_mov_b32_e32 v17, v0
	v_mov_b32_e32 v18, v0
	v_mov_b32_e32 v19, v0
	v_mov_b32_e32 v20, v0
	v_mov_b32_e32 v21, v0
	v_mov_b32_e32 v22, v0
	v_mov_b32_e32 v23, v0
	v_mov_b32_e32 v24, v0
	v_mov_b32_e32 v25, v0
	v_mov_b32_e32 v26, v0
	v_mov_b32_e32 v27, v0
	v_mov_b32_e32 v28, v0
	v_mov_b32_e32 v29, v0
	v_mov_b32_e32 v30, v0
	v_mov_b32_e32 v31, v0
	v_mov_b32_e32 v32, v0
	v_mov_b32_e32 v33, v0
	v_mov_b32_e32 v34, v0
	v_mov_b32_e32 v35, v0
	v_mov_b32_e32 v36, v0
	v_mov_b32_e32 v37, v0
	v_mov_b32_e32 v38, v0
	v_mov_b32_e32 v39, v0
	v_mov_b32_e32 v40, v0
	v_mov_b32_e32 v41, v0
	v_mov_b32_e32 v42, v0
	v_mov_b32_e32 v43, v0
	v_mov_b32_e32 v44, v0
	v_mov_b32_e32 v45, v0
	v_mov_b32_e32 v46, v0
	v_mov_b32_e32 v47, v0
	v_mov_b32_e32 v48, v0
	v_mov_b32_e32 v49, v0
	v_mov_b32_e32 v50, v0
	v_mov_b32_e32 v51, v0
	v_mov_b32_e32 v52, v0
	v_mov_b32_e32 v53, v0
	v_mov_b32_e32 v54, v0
	v_mov_b32_e32 v55, v0
	v_mov_b32_e32 v56, v0
	v_mov_b32_e32 v57, v0
	v_mov_b32_e32 v58, v0
	v_mov_b32_e32 v59, v0
	v_mov_b32_e32 v60, v0
	v_mov_b32_e32 v61, v0
	v_mov_b32_e32 v62, v0
	v_mov_b32_e32 v63, v0
	v_mov_b32_e32 v64, v0
	v_mov_b32_e32 v65, v0
	v_mov_b32_e32 v66, v0
	v_mov_b32_e32 v67, v0
	v_mov_b32_e32 v68, v0
	v_mov_b32_e32 v69, v0
	v_mov_b32_e32 v70, v0
	v_mov_b32_e32 v71, v0
	v_mov_b32_e32 v72, v0
	v_mov_b32_e32 v73, v0
	v_mov_b32_e32 v74, v0
	v_mov_b32_e32 v75, v0
	v_mov_b32_e32 v76, v0
	v_mov_b32_e32 v77, v0
	v_mov_b32_e32 v78, v0
	v_mov_b32_e32 v79, v0
	v_mov_b32_e32 v80, v0
	v_mov_b32_e32 v81, v0
	v_mov_b32_e32 v82, v0
	v_mov_b32_e32 v83, v0
	v_mov_b32_e32 v84, v0
	v_mov_b32_e32 v85, v0
	v_mov_b32_e32 v86, v0
	v_mov_b32_e32 v87, v0
	v_mov_b32_e32 v88, v0
	v_mov_b32_e32 v89, v0
	v_mov_b32_e32 v90, v0
	v_mov_b32_e32 v91, v0
	v_mov_b32_e32 v92, v0
	v_mov_b32_e32 v93, v0
	v_mov_b32_e32 v94, v0
	v_mov_b32_e32 v95, v0
	v_mov_b32_e32 v96, v0
	v_mov_b32_e32 v97, v0
	v_mov_b32_e32 v98, v0
	v_mov_b32_e32 v99, v0
	v_mov_b32_e32 v100, v0
	v_mov_b32_e32 v101, v0
	v_mov_b32_e32 v102, v0
	v_mov_b32_e32 v103, v0
	v_mov_b32_e32 v104, v0
	v_mov_b32_e32 v105, v0
	v_mov_b32_e32 v106, v0
	v_mov_b32_e32 v107, v0
	v_mov_b32_e32 v108, v0
	v_mov_b32_e32 v109, v0
	v_mov_b32_e32 v110, v0
	v_mov_b32_e32 v111, v0
	v_mov_b32_e32 v112, v0
	v_mov_b32_e32 v113, v0
	v_mov_b32_e32 v114, v0
	v_mov_b32_e32 v115, v0
	v_mov_b32_e32 v116, v0
	v_mov_b32_e32 v117, v0
	v_mov_b32_e32 v118, v0
	v_mov_b32_e32 v119, v0
	v_mov_b32_e32 v120, v0
	v_mov_b32_e32 v121, v0
	v_mov_b32_e32 v122, v0
	v_mov_b32_e32 v123, v0
	v_mov_b32_e32 v124, v0
	v_mov_b32_e32 v125, v0
	v_mov_b32_e32 v126, v0
	v_mov_b32_e32 v127, v0
.LBB0_391:
	s_andn2_b64 vcc, exec, s[8:9]
	s_cbranch_vccnz .LBB0_327
	s_barrier
	s_branch .LBB0_327
.LBB0_409:
	s_waitcnt vmcnt(0)
	s_barrier

.LBB0_544:
	s_cmp_lt_i32 s80, 6
	s_cselect_b64 s[0:1], -1, 0
	s_and_b64 s[0:1], s[0:1], s[4:5]
	s_andn2_b64 vcc, exec, s[0:1]
	s_cbranch_vccnz .LBB0_548
	s_lshl_b32 s0, s2, 3
	s_add_i32 s0, s97, s0
	s_cmpk_gt_i32 s0, 0x1fff
	s_cbranch_scc1 .LBB0_548
	s_lshl_b32 s2, s82, 3
	v_readlane_b32 s12, v239, 3
	v_readlane_b32 s13, v239, 4
	s_add_u32 s14, s70, 0x10100000
	s_addc_u32 s15, s71, 0
	v_lshlrev_b32_e32 v0, 4, v182
	v_add_u32_e32 v1, 0x1000, v0
	v_add_u32_e32 v2, 0x2000, v0
	v_add_u32_e32 v3, 0x3000, v0
	v_lshlrev_b32_e32 v4, 3, v182
	v_add_u32_e32 v5, 0x1000, v4
	v_xor_b32_e32 v7, 1, v182
	v_lshlrev_b32_e32 v8, 2, v7
	v_xor_b32_e32 v7, 2, v182
	v_lshlrev_b32_e32 v9, 2, v7
	v_xor_b32_e32 v7, 4, v182
	v_lshlrev_b32_e32 v10, 2, v7
	v_xor_b32_e32 v7, 8, v182
	v_lshlrev_b32_e32 v11, 2, v7
	v_xor_b32_e32 v7, 16, v182
	v_lshlrev_b32_e32 v12, 2, v7
	v_xor_b32_e32 v7, 32, v182
	v_lshlrev_b32_e32 v13, 2, v7
	v_mov_b32_e32 v14, 0x358637bd
	global_load_dwordx4 v[16:19], v0, s[66:67] offset:0
	global_load_dwordx4 v[20:23], v0, s[66:67] offset:1024
	global_load_dwordx4 v[24:27], v0, s[66:67] offset:2048
	global_load_dwordx4 v[28:31], v0, s[66:67] offset:3072
	global_load_dwordx4 v[32:35], v1, s[66:67] offset:0
	global_load_dwordx4 v[36:39], v1, s[66:67] offset:1024
	global_load_dwordx4 v[40:43], v1, s[66:67] offset:2048
	global_load_dwordx4 v[44:47], v1, s[66:67] offset:3072
	global_load_dwordx4 v[48:51], v2, s[66:67] offset:0
	global_load_dwordx4 v[52:55], v2, s[66:67] offset:1024
	global_load_dwordx4 v[56:59], v2, s[66:67] offset:2048
	global_load_dwordx4 v[60:63], v2, s[66:67] offset:3072
	global_load_dwordx4 v[64:67], v3, s[66:67] offset:0
	global_load_dwordx4 v[68:71], v3, s[66:67] offset:1024
	global_load_dwordx4 v[72:75], v3, s[66:67] offset:2048
	global_load_dwordx4 v[76:79], v3, s[66:67] offset:3072
.Lp5_row:
	s_lshl_b32 s4, s0, 14
	s_add_u32 s6, s12, s4
	s_addc_u32 s7, s13, 0
	s_add_u32 s8, s68, s4
	s_addc_u32 s9, s69, 0
	s_lshl_b32 s4, s0, 13
	s_add_u32 s10, s14, s4
	s_addc_u32 s11, s15, 0
	global_load_dwordx2 v[144:145], v4, s[10:11] offset:0
	global_load_dwordx4 v[80:83], v0, s[6:7] offset:0
	global_load_dwordx2 v[146:147], v4, s[10:11] offset:512
	global_load_dwordx4 v[84:87], v0, s[6:7] offset:1024
	global_load_dwordx2 v[148:149], v4, s[10:11] offset:1024
	global_load_dwordx4 v[88:91], v0, s[6:7] offset:2048
	global_load_dwordx2 v[150:151], v4, s[10:11] offset:1536
	global_load_dwordx4 v[92:95], v0, s[6:7] offset:3072
	global_load_dwordx2 v[152:153], v4, s[10:11] offset:2048
	global_load_dwordx4 v[96:99], v1, s[6:7] offset:0
	global_load_dwordx2 v[154:155], v4, s[10:11] offset:2560
	global_load_dwordx4 v[100:103], v1, s[6:7] offset:1024
	global_load_dwordx2 v[156:157], v4, s[10:11] offset:3072
	global_load_dwordx4 v[104:107], v1, s[6:7] offset:2048
	global_load_dwordx2 v[158:159], v4, s[10:11] offset:3584
	global_load_dwordx4 v[108:111], v1, s[6:7] offset:3072
	global_load_dwordx2 v[160:161], v5, s[10:11] offset:0
	global_load_dwordx4 v[112:115], v2, s[6:7] offset:0
	global_load_dwordx2 v[162:163], v5, s[10:11] offset:512
	global_load_dwordx4 v[116:119], v2, s[6:7] offset:1024
	global_load_dwordx2 v[164:165], v5, s[10:11] offset:1024
	global_load_dwordx4 v[120:123], v2, s[6:7] offset:2048
	global_load_dwordx2 v[166:167], v5, s[10:11] offset:1536
	global_load_dwordx4 v[124:127], v2, s[6:7] offset:3072
	global_load_dwordx2 v[168:169], v5, s[10:11] offset:2048
	global_load_dwordx4 v[128:131], v3, s[6:7] offset:0
	global_load_dwordx2 v[170:171], v5, s[10:11] offset:2560
	global_load_dwordx4 v[132:135], v3, s[6:7] offset:1024
	global_load_dwordx2 v[172:173], v5, s[10:11] offset:3072
	global_load_dwordx4 v[136:139], v3, s[6:7] offset:2048
	global_load_dwordx2 v[174:175], v5, s[10:11] offset:3584
	global_load_dwordx4 v[140:143], v3, s[6:7] offset:3072
	s_add_i32 s0, s0, s2
	s_waitcnt vmcnt(30)
	v_lshlrev_b32_e32 v176, 16, v144
	v_and_b32_e32 v177, 0xffff0000, v144
	v_lshlrev_b32_e32 v178, 16, v145
	v_and_b32_e32 v179, 0xffff0000, v145
	v_pk_add_f32 v[80:81], v[80:81], v[176:177]
	v_pk_add_f32 v[82:83], v[82:83], v[178:179]
	v_mul_f32_e32 v184, v80, v80
	v_mul_f32_e32 v185, v81, v81
	v_mul_f32_e32 v186, v82, v82
	v_mul_f32_e32 v187, v83, v83
	s_waitcnt vmcnt(28)
	v_lshlrev_b32_e32 v176, 16, v146
	v_and_b32_e32 v177, 0xffff0000, v146
	v_lshlrev_b32_e32 v178, 16, v147
	v_and_b32_e32 v179, 0xffff0000, v147
	v_pk_add_f32 v[84:85], v[84:85], v[176:177]
	v_pk_add_f32 v[86:87], v[86:87], v[178:179]
	v_fmac_f32_e32 v184, v84, v84
	v_fmac_f32_e32 v185, v85, v85
	v_fmac_f32_e32 v186, v86, v86
	v_fmac_f32_e32 v187, v87, v87
	s_waitcnt vmcnt(26)
	v_lshlrev_b32_e32 v176, 16, v148
	v_and_b32_e32 v177, 0xffff0000, v148
	v_lshlrev_b32_e32 v178, 16, v149
	v_and_b32_e32 v179, 0xffff0000, v149
	v_pk_add_f32 v[88:89], v[88:89], v[176:177]
	v_pk_add_f32 v[90:91], v[90:91], v[178:179]
	v_fmac_f32_e32 v184, v88, v88
	v_fmac_f32_e32 v185, v89, v89
	v_fmac_f32_e32 v186, v90, v90
	v_fmac_f32_e32 v187, v91, v91
	s_waitcnt vmcnt(24)
	v_lshlrev_b32_e32 v176, 16, v150
	v_and_b32_e32 v177, 0xffff0000, v150
	v_lshlrev_b32_e32 v178, 16, v151
	v_and_b32_e32 v179, 0xffff0000, v151
	v_pk_add_f32 v[92:93], v[92:93], v[176:177]
	v_pk_add_f32 v[94:95], v[94:95], v[178:179]
	v_fmac_f32_e32 v184, v92, v92
	v_fmac_f32_e32 v185, v93, v93
	v_fmac_f32_e32 v186, v94, v94
	v_fmac_f32_e32 v187, v95, v95
	s_waitcnt vmcnt(22)
	v_lshlrev_b32_e32 v176, 16, v152
	v_and_b32_e32 v177, 0xffff0000, v152
	v_lshlrev_b32_e32 v178, 16, v153
	v_and_b32_e32 v179, 0xffff0000, v153
	v_pk_add_f32 v[96:97], v[96:97], v[176:177]
	v_pk_add_f32 v[98:99], v[98:99], v[178:179]
	v_fmac_f32_e32 v184, v96, v96
	v_fmac_f32_e32 v185, v97, v97
	v_fmac_f32_e32 v186, v98, v98
	v_fmac_f32_e32 v187, v99, v99
	s_waitcnt vmcnt(20)
	v_lshlrev_b32_e32 v176, 16, v154
	v_and_b32_e32 v177, 0xffff0000, v154
	v_lshlrev_b32_e32 v178, 16, v155
	v_and_b32_e32 v179, 0xffff0000, v155
	v_pk_add_f32 v[100:101], v[100:101], v[176:177]
	v_pk_add_f32 v[102:103], v[102:103], v[178:179]
	v_fmac_f32_e32 v184, v100, v100
	v_fmac_f32_e32 v185, v101, v101
	v_fmac_f32_e32 v186, v102, v102
	v_fmac_f32_e32 v187, v103, v103
	s_waitcnt vmcnt(18)
	v_lshlrev_b32_e32 v176, 16, v156
	v_and_b32_e32 v177, 0xffff0000, v156
	v_lshlrev_b32_e32 v178, 16, v157
	v_and_b32_e32 v179, 0xffff0000, v157
	v_pk_add_f32 v[104:105], v[104:105], v[176:177]
	v_pk_add_f32 v[106:107], v[106:107], v[178:179]
	v_fmac_f32_e32 v184, v104, v104
	v_fmac_f32_e32 v185, v105, v105
	v_fmac_f32_e32 v186, v106, v106
	v_fmac_f32_e32 v187, v107, v107
	s_waitcnt vmcnt(16)
	v_lshlrev_b32_e32 v176, 16, v158
	v_and_b32_e32 v177, 0xffff0000, v158
	v_lshlrev_b32_e32 v178, 16, v159
	v_and_b32_e32 v179, 0xffff0000, v159
	v_pk_add_f32 v[108:109], v[108:109], v[176:177]
	v_pk_add_f32 v[110:111], v[110:111], v[178:179]
	v_fmac_f32_e32 v184, v108, v108
	v_fmac_f32_e32 v185, v109, v109
	v_fmac_f32_e32 v186, v110, v110
	v_fmac_f32_e32 v187, v111, v111
	s_waitcnt vmcnt(14)
	v_lshlrev_b32_e32 v176, 16, v160
	v_and_b32_e32 v177, 0xffff0000, v160
	v_lshlrev_b32_e32 v178, 16, v161
	v_and_b32_e32 v179, 0xffff0000, v161
	v_pk_add_f32 v[112:113], v[112:113], v[176:177]
	v_pk_add_f32 v[114:115], v[114:115], v[178:179]
	v_fmac_f32_e32 v184, v112, v112
	v_fmac_f32_e32 v185, v113, v113
	v_fmac_f32_e32 v186, v114, v114
	v_fmac_f32_e32 v187, v115, v115
	s_waitcnt vmcnt(12)
	v_lshlrev_b32_e32 v176, 16, v162
	v_and_b32_e32 v177, 0xffff0000, v162
	v_lshlrev_b32_e32 v178, 16, v163
	v_and_b32_e32 v179, 0xffff0000, v163
	v_pk_add_f32 v[116:117], v[116:117], v[176:177]
	v_pk_add_f32 v[118:119], v[118:119], v[178:179]
	v_fmac_f32_e32 v184, v116, v116
	v_fmac_f32_e32 v185, v117, v117
	v_fmac_f32_e32 v186, v118, v118
	v_fmac_f32_e32 v187, v119, v119
	s_waitcnt vmcnt(10)
	v_lshlrev_b32_e32 v176, 16, v164
	v_and_b32_e32 v177, 0xffff0000, v164
	v_lshlrev_b32_e32 v178, 16, v165
	v_and_b32_e32 v179, 0xffff0000, v165
	v_pk_add_f32 v[120:121], v[120:121], v[176:177]
	v_pk_add_f32 v[122:123], v[122:123], v[178:179]
	v_fmac_f32_e32 v184, v120, v120
	v_fmac_f32_e32 v185, v121, v121
	v_fmac_f32_e32 v186, v122, v122
	v_fmac_f32_e32 v187, v123, v123
	s_waitcnt vmcnt(8)
	v_lshlrev_b32_e32 v176, 16, v166
	v_and_b32_e32 v177, 0xffff0000, v166
	v_lshlrev_b32_e32 v178, 16, v167
	v_and_b32_e32 v179, 0xffff0000, v167
	v_pk_add_f32 v[124:125], v[124:125], v[176:177]
	v_pk_add_f32 v[126:127], v[126:127], v[178:179]
	v_fmac_f32_e32 v184, v124, v124
	v_fmac_f32_e32 v185, v125, v125
	v_fmac_f32_e32 v186, v126, v126
	v_fmac_f32_e32 v187, v127, v127
	s_waitcnt vmcnt(6)
	v_lshlrev_b32_e32 v176, 16, v168
	v_and_b32_e32 v177, 0xffff0000, v168
	v_lshlrev_b32_e32 v178, 16, v169
	v_and_b32_e32 v179, 0xffff0000, v169
	v_pk_add_f32 v[128:129], v[128:129], v[176:177]
	v_pk_add_f32 v[130:131], v[130:131], v[178:179]
	v_fmac_f32_e32 v184, v128, v128
	v_fmac_f32_e32 v185, v129, v129
	v_fmac_f32_e32 v186, v130, v130
	v_fmac_f32_e32 v187, v131, v131
	s_waitcnt vmcnt(4)
	v_lshlrev_b32_e32 v176, 16, v170
	v_and_b32_e32 v177, 0xffff0000, v170
	v_lshlrev_b32_e32 v178, 16, v171
	v_and_b32_e32 v179, 0xffff0000, v171
	v_pk_add_f32 v[132:133], v[132:133], v[176:177]
	v_pk_add_f32 v[134:135], v[134:135], v[178:179]
	v_fmac_f32_e32 v184, v132, v132
	v_fmac_f32_e32 v185, v133, v133
	v_fmac_f32_e32 v186, v134, v134
	v_fmac_f32_e32 v187, v135, v135
	s_waitcnt vmcnt(2)
	v_lshlrev_b32_e32 v176, 16, v172
	v_and_b32_e32 v177, 0xffff0000, v172
	v_lshlrev_b32_e32 v178, 16, v173
	v_and_b32_e32 v179, 0xffff0000, v173
	v_pk_add_f32 v[136:137], v[136:137], v[176:177]
	v_pk_add_f32 v[138:139], v[138:139], v[178:179]
	v_fmac_f32_e32 v184, v136, v136
	v_fmac_f32_e32 v185, v137, v137
	v_fmac_f32_e32 v186, v138, v138
	v_fmac_f32_e32 v187, v139, v139
	s_waitcnt vmcnt(0)
	v_lshlrev_b32_e32 v176, 16, v174
	v_and_b32_e32 v177, 0xffff0000, v174
	v_lshlrev_b32_e32 v178, 16, v175
	v_and_b32_e32 v179, 0xffff0000, v175
	v_pk_add_f32 v[140:141], v[140:141], v[176:177]
	v_pk_add_f32 v[142:143], v[142:143], v[178:179]
	v_fmac_f32_e32 v184, v140, v140
	v_fmac_f32_e32 v185, v141, v141
	v_fmac_f32_e32 v186, v142, v142
	v_fmac_f32_e32 v187, v143, v143
	v_add_f32_e32 v184, v184, v185
	v_add_f32_e32 v186, v186, v187
	v_add_f32_e32 v184, v184, v186
	ds_bpermute_b32 v185, v8, v184
	s_waitcnt lgkmcnt(0)
	v_add_f32_e32 v184, v184, v185
	ds_bpermute_b32 v185, v9, v184
	s_waitcnt lgkmcnt(0)
	v_add_f32_e32 v184, v184, v185
	ds_bpermute_b32 v185, v10, v184
	s_waitcnt lgkmcnt(0)
	v_add_f32_e32 v184, v184, v185
	ds_bpermute_b32 v185, v11, v184
	s_waitcnt lgkmcnt(0)
	v_add_f32_e32 v184, v184, v185
	ds_bpermute_b32 v185, v12, v184
	s_waitcnt lgkmcnt(0)
	v_add_f32_e32 v184, v184, v185
	ds_bpermute_b32 v185, v13, v184
	s_waitcnt lgkmcnt(0)
	v_add_f32_e32 v184, v184, v185
	v_fmamk_f32 v184, v184, 0x39800000, v14
	v_rsq_f32_e32 v184, v184
	s_nop 0
	v_pk_mul_f32 v[80:81], v[80:81], v[184:185] op_sel_hi:[1,0]
	v_pk_mul_f32 v[82:83], v[82:83], v[184:185] op_sel_hi:[1,0]
	v_pk_mul_f32 v[80:81], v[80:81], v[16:17]
	v_pk_mul_f32 v[82:83], v[82:83], v[18:19]
	global_store_dwordx4 v0, v[80:83], s[8:9] offset:0
	v_pk_mul_f32 v[84:85], v[84:85], v[184:185] op_sel_hi:[1,0]
	v_pk_mul_f32 v[86:87], v[86:87], v[184:185] op_sel_hi:[1,0]
	v_pk_mul_f32 v[84:85], v[84:85], v[20:21]
	v_pk_mul_f32 v[86:87], v[86:87], v[22:23]
	global_store_dwordx4 v0, v[84:87], s[8:9] offset:1024
	v_pk_mul_f32 v[88:89], v[88:89], v[184:185] op_sel_hi:[1,0]
	v_pk_mul_f32 v[90:91], v[90:91], v[184:185] op_sel_hi:[1,0]
	v_pk_mul_f32 v[88:89], v[88:89], v[24:25]
	v_pk_mul_f32 v[90:91], v[90:91], v[26:27]
	global_store_dwordx4 v0, v[88:91], s[8:9] offset:2048
	v_pk_mul_f32 v[92:93], v[92:93], v[184:185] op_sel_hi:[1,0]
	v_pk_mul_f32 v[94:95], v[94:95], v[184:185] op_sel_hi:[1,0]
	v_pk_mul_f32 v[92:93], v[92:93], v[28:29]
	v_pk_mul_f32 v[94:95], v[94:95], v[30:31]
	global_store_dwordx4 v0, v[92:95], s[8:9] offset:3072
	v_pk_mul_f32 v[96:97], v[96:97], v[184:185] op_sel_hi:[1,0]
	v_pk_mul_f32 v[98:99], v[98:99], v[184:185] op_sel_hi:[1,0]
	v_pk_mul_f32 v[96:97], v[96:97], v[32:33]
	v_pk_mul_f32 v[98:99], v[98:99], v[34:35]
	global_store_dwordx4 v1, v[96:99], s[8:9] offset:0
	v_pk_mul_f32 v[100:101], v[100:101], v[184:185] op_sel_hi:[1,0]
	v_pk_mul_f32 v[102:103], v[102:103], v[184:185] op_sel_hi:[1,0]
	v_pk_mul_f32 v[100:101], v[100:101], v[36:37]
	v_pk_mul_f32 v[102:103], v[102:103], v[38:39]
	global_store_dwordx4 v1, v[100:103], s[8:9] offset:1024
	v_pk_mul_f32 v[104:105], v[104:105], v[184:185] op_sel_hi:[1,0]
	v_pk_mul_f32 v[106:107], v[106:107], v[184:185] op_sel_hi:[1,0]
	v_pk_mul_f32 v[104:105], v[104:105], v[40:41]
	v_pk_mul_f32 v[106:107], v[106:107], v[42:43]
	global_store_dwordx4 v1, v[104:107], s[8:9] offset:2048
	v_pk_mul_f32 v[108:109], v[108:109], v[184:185] op_sel_hi:[1,0]
	v_pk_mul_f32 v[110:111], v[110:111], v[184:185] op_sel_hi:[1,0]
	v_pk_mul_f32 v[108:109], v[108:109], v[44:45]
	v_pk_mul_f32 v[110:111], v[110:111], v[46:47]
	global_store_dwordx4 v1, v[108:111], s[8:9] offset:3072
	v_pk_mul_f32 v[112:113], v[112:113], v[184:185] op_sel_hi:[1,0]
	v_pk_mul_f32 v[114:115], v[114:115], v[184:185] op_sel_hi:[1,0]
	v_pk_mul_f32 v[112:113], v[112:113], v[48:49]
	v_pk_mul_f32 v[114:115], v[114:115], v[50:51]
	global_store_dwordx4 v2, v[112:115], s[8:9] offset:0
	v_pk_mul_f32 v[116:117], v[116:117], v[184:185] op_sel_hi:[1,0]
	v_pk_mul_f32 v[118:119], v[118:119], v[184:185] op_sel_hi:[1,0]
	v_pk_mul_f32 v[116:117], v[116:117], v[52:53]
	v_pk_mul_f32 v[118:119], v[118:119], v[54:55]
	global_store_dwordx4 v2, v[116:119], s[8:9] offset:1024
	v_pk_mul_f32 v[120:121], v[120:121], v[184:185] op_sel_hi:[1,0]
	v_pk_mul_f32 v[122:123], v[122:123], v[184:185] op_sel_hi:[1,0]
	v_pk_mul_f32 v[120:121], v[120:121], v[56:57]
	v_pk_mul_f32 v[122:123], v[122:123], v[58:59]
	global_store_dwordx4 v2, v[120:123], s[8:9] offset:2048
	v_pk_mul_f32 v[124:125], v[124:125], v[184:185] op_sel_hi:[1,0]
	v_pk_mul_f32 v[126:127], v[126:127], v[184:185] op_sel_hi:[1,0]
	v_pk_mul_f32 v[124:125], v[124:125], v[60:61]
	v_pk_mul_f32 v[126:127], v[126:127], v[62:63]
	global_store_dwordx4 v2, v[124:127], s[8:9] offset:3072
	v_pk_mul_f32 v[128:129], v[128:129], v[184:185] op_sel_hi:[1,0]
	v_pk_mul_f32 v[130:131], v[130:131], v[184:185] op_sel_hi:[1,0]
	v_pk_mul_f32 v[128:129], v[128:129], v[64:65]
	v_pk_mul_f32 v[130:131], v[130:131], v[66:67]
	global_store_dwordx4 v3, v[128:131], s[8:9] offset:0
	v_pk_mul_f32 v[132:133], v[132:133], v[184:185] op_sel_hi:[1,0]
	v_pk_mul_f32 v[134:135], v[134:135], v[184:185] op_sel_hi:[1,0]
	v_pk_mul_f32 v[132:133], v[132:133], v[68:69]
	v_pk_mul_f32 v[134:135], v[134:135], v[70:71]
	global_store_dwordx4 v3, v[132:135], s[8:9] offset:1024
	v_pk_mul_f32 v[136:137], v[136:137], v[184:185] op_sel_hi:[1,0]
	v_pk_mul_f32 v[138:139], v[138:139], v[184:185] op_sel_hi:[1,0]
	v_pk_mul_f32 v[136:137], v[136:137], v[72:73]
	v_pk_mul_f32 v[138:139], v[138:139], v[74:75]
	global_store_dwordx4 v3, v[136:139], s[8:9] offset:2048
	v_pk_mul_f32 v[140:141], v[140:141], v[184:185] op_sel_hi:[1,0]
	v_pk_mul_f32 v[142:143], v[142:143], v[184:185] op_sel_hi:[1,0]
	v_pk_mul_f32 v[140:141], v[140:141], v[76:77]
	v_pk_mul_f32 v[142:143], v[142:143], v[78:79]
	global_store_dwordx4 v3, v[140:143], s[8:9] offset:3072
	s_cmpk_lt_i32 s0, 0x2000
	s_cbranch_scc1 .Lp5_row
